# full-line residual-stream stores in out-proj and down-proj epilogues (adjacent-lane exchange), stat-load hoist in 3 EpiStoreN epilogues
# speedup vs baseline: 1.0111x; 1.0111x over previous
; #define LAS __attribute__((address_space(3)))
; __device__ __forceinline__ ParamsK getpk() { ParamsK q = (ParamsK)__builtin_amdgcn_kernarg_segment_ptr(); asm volatile("" : "+s"(q)); return q; }
; #define WSP asglobal(p->ws)
; __global__ void __launch_bounds__(512, 2) fwd_megakernel(Params p_unused) {
;     extern __shared__ __attribute__((aligned(16))) unsigned char smem[];
;     cg::grid_group grid = cg::this_grid();
;     __shared__ uint4 xb_words;
;     if (threadIdx.x == 0) xb_words = make_uint4(0u, 0u, 0u, 0u);
;     __syncthreads();
;     XcdBarrier xb; { ParamsK p = getpk(); xb = xcd_barrier_post((unsigned*)(WSP + WS_CTL), (volatile LAS unsigned*)&xb_words); }
.amdgcn_target "amdgcn-amd-amdhsa--gfx950"
	.amdhsa_code_object_version 6

; __device__ __forceinline__ unsigned pk2(float lo, float hi) { return pg8::cvt_pk_bf16(lo, hi); }
;     __device__ __forceinline__ void operator()(const f32x4 (&acc)[2][2][4][2], const pg8::Unit& u, int wr, int wc, int fr, int fq) const {
;         const int row0 = u.pm * 256 + wr * 64 + fr, col0 = u.pn * 256 + wc * 32 + 8 * fq;
;         const int Rt = rowbase + u.pm * 256;
;         const float* bp = bias + (size_t)(Rt < TL ? (Rt >> 13) : 8) * FF2 + col0;
;         f32x4 bv[2][2];
; #pragma unroll
;         for (int bj = 0; bj < 2; ++bj) { bv[bj][0] = *(const f32x4*)(bp + bj * 128); bv[bj][1] = *(const f32x4*)(bp + bj * 128 + 4); }
; #pragma unroll
;         for (int ai = 0; ai < 2; ++ai)
; #pragma unroll
;             for (int m = 0; m < 4; ++m) { const int r = row0 + ai * 128 + m * 16, Rg = rowbase + r;
;                 const f32x4 q = *(const f32x4*)(stat + (size_t)Rg * 16 + fq * 4);
;                 float ssq = (q[0] + q[1]) + (q[2] + q[3]); ssq += __shfl_xor(ssq, 16); ssq += __shfl_xor(ssq, 32);
;                 const float rstd = rsqrtf(ssq * (1.f / DM) + 1e-6f);
;                 bf16_t* rowp = O + (size_t)r * ldc + col0;
; #pragma unroll
;                 for (int bj = 0; bj < 2; ++bj) { const f32x4 v0 = acc[ai][bj][m][0] * rstd + bv[bj][0], v1 = acc[ai][bj][m][1] * rstd + bv[bj][1];
;                     u32x4 w; w.x = pk2(v0[0], v0[1]); w.y = pk2(v0[2], v0[3]); w.z = pk2(v1[0], v1[1]); w.w = pk2(v1[2], v1[3]);
;                     *(u32x4*)(rowp + bj * 128) = w; } }
.LBB0_165:
	v_and_b32_e32 v160, 64, v228
	v_xor_b32_e32 v159, 16, v228
	v_add_u32_e32 v160, 64, v160
	s_lshl_b32 s10, s56, 8
	v_cmp_lt_i32_e32 vcc, v159, v160
	s_min_i32 s11, s10, 0x8000
	s_add_i32 s11, s11, 0x8000
	v_cndmask_b32_e32 v159, v228, v159, vcc
	v_lshlrev_b32_e32 v186, 2, v159
	v_xor_b32_e32 v159, 32, v228
	s_ashr_i32 s11, s11, 13
	v_cmp_lt_i32_e32 vcc, v159, v160
	s_mul_i32 s34, s11, 0x1600
	v_add_u32_e32 v158, s10, v182
	v_cndmask_b32_e32 v159, v228, v159, vcc
	s_ashr_i32 s35, s34, 31
	v_lshlrev_b32_e32 v187, 2, v159
	v_ashrrev_i32_e32 v159, 31, v158
	s_lshl_b64 s[34:35], s[34:35], 2
	v_lshlrev_b64 v[160:161], 6, v[158:159]
	v_lshl_or_b32 v176, s55, 8, v184
	s_add_u32 s34, s0, s34
	v_lshl_add_u64 v[178:179], v[152:153], 0, v[160:161]
	s_mov_b32 s10, 0x200000
	s_addc_u32 s35, s51, s35
	v_ashrrev_i32_e32 v177, 31, v176
	v_add_co_u32_e32 v180, vcc, s10, v178
	v_lshl_add_u64 v[94:95], v[176:177], 2, s[34:35]
	s_nop 0
	v_addc_co_u32_e32 v181, vcc, 0, v179, vcc
	global_load_dwordx4 v[98:101], v[94:95], off offset:16
	global_load_dwordx4 v[102:105], v[94:95], off
	global_load_dwordx4 v[90:93], v[94:95], off offset:528
	s_nop 0
	global_load_dwordx4 v[94:97], v[94:95], off offset:512
	v_lshlrev_b64 v[176:177], 1, v[176:177]
	global_load_dwordx4 v[188:191], v[180:181], off
	global_load_dwordx4 v[196:199], v[180:181], off offset:1024
	global_load_dwordx4 v[200:203], v[180:181], off offset:2048
	global_load_dwordx4 v[204:207], v[180:181], off offset:3072
	v_add_co_u32_e32 v194, vcc, 0x2000, v180
	s_nop 1
	v_addc_co_u32_e32 v195, vcc, 0, v181, vcc
	global_load_dwordx4 v[208:211], v[194:195], off
	global_load_dwordx4 v[212:215], v[194:195], off offset:1024
	global_load_dwordx4 v[216:219], v[194:195], off offset:2048
	global_load_dwordx4 v[220:223], v[194:195], off offset:3072
	s_mov_b32 s10, 0x202000
	s_mov_b64 s[44:45], -1
	s_waitcnt vmcnt(0)
	v_mov_b32_e32 v160, v189
	v_mov_b32_e32 v161, v190
	v_mov_b32_e32 v189, v191
	v_pk_add_f32 v[160:161], v[160:161], v[188:189]
	s_nop 0
	v_add_f32_e32 v159, v160, v161
	ds_bpermute_b32 v160, v186, v159
	s_waitcnt lgkmcnt(0)
	v_add_f32_e32 v159, v159, v160
	ds_bpermute_b32 v160, v187, v159
	s_waitcnt lgkmcnt(0)
	v_add_f32_e32 v159, v159, v160
	v_fmamk_f32 v159, v159, 0x3a800000, v162
	v_cmp_gt_f32_e32 vcc, s82, v159
	v_mul_f32_e32 v160, 0x4b800000, v159
	s_nop 0
	v_cndmask_b32_e32 v159, v159, v160, vcc
	v_rsq_f32_e32 v159, v159
	s_nop 0
	v_mul_f32_e32 v160, 0x45800000, v159
	v_cndmask_b32_e32 v188, v159, v160, vcc
	v_mov_b64_e32 v[160:161], s[20:21]
	v_mad_i64_i32 v[190:191], s[34:35], v158, s83, v[160:161]
	v_pk_fma_f32 v[144:145], v[144:145], v[188:189], v[104:105] op_sel_hi:[1,0,1]
	v_pk_fma_f32 v[142:143], v[142:143], v[188:189], v[102:103] op_sel_hi:[1,0,1]
	v_pk_fma_f32 v[192:193], v[140:141], v[188:189], v[100:101] op_sel_hi:[1,0,1]
	v_pk_fma_f32 v[140:141], v[138:139], v[188:189], v[98:99] op_sel_hi:[1,0,1]
	v_lshl_add_u64 v[190:191], v[190:191], 0, v[176:177]
	v_cvt_pk_bf16_f32 v138, v142, v143
	v_cvt_pk_bf16_f32 v139, v144, v145
	v_cvt_pk_bf16_f32 v140, v140, v141
	v_cvt_pk_bf16_f32 v141, v192, v193
	global_store_dwordx4 v[190:191], v[138:141], off
	v_pk_fma_f32 v[136:137], v[136:137], v[188:189], v[96:97] op_sel_hi:[1,0,1]
	v_pk_fma_f32 v[134:135], v[134:135], v[188:189], v[94:95] op_sel_hi:[1,0,1]
	v_pk_fma_f32 v[138:139], v[132:133], v[188:189], v[92:93] op_sel_hi:[1,0,1]
	v_pk_fma_f32 v[132:133], v[130:131], v[188:189], v[90:91] op_sel_hi:[1,0,1]
	v_cvt_pk_bf16_f32 v130, v134, v135
	v_cvt_pk_bf16_f32 v131, v136, v137
	v_cvt_pk_bf16_f32 v132, v132, v133
	v_cvt_pk_bf16_f32 v133, v138, v139
	global_store_dwordx4 v[190:191], v[130:133], off offset:256
	v_or_b32_e32 v136, 16, v158
	s_nop 1
	v_add_f32_e32 v130, v196, v197
	v_add_f32_e32 v131, v198, v199
	v_mad_i64_i32 v[132:133], s[34:35], v136, s83, v[160:161]
	v_add_f32_e32 v130, v130, v131
	ds_bpermute_b32 v131, v186, v130
	v_lshl_add_u64 v[132:133], v[132:133], 0, v[176:177]
	s_waitcnt lgkmcnt(0)
	v_add_f32_e32 v130, v130, v131
	ds_bpermute_b32 v131, v187, v130
	s_waitcnt lgkmcnt(0)
	v_add_f32_e32 v130, v130, v131
	v_fmamk_f32 v130, v130, 0x3a800000, v162
	v_cmp_gt_f32_e32 vcc, s82, v130
	v_mul_f32_e32 v131, 0x4b800000, v130
	s_nop 0
	v_cndmask_b32_e32 v130, v130, v131, vcc
	v_rsq_f32_e32 v130, v130
	s_nop 0
	v_mul_f32_e32 v131, 0x45800000, v130
	v_cndmask_b32_e32 v130, v130, v131, vcc
	v_pk_fma_f32 v[128:129], v[128:129], v[130:131], v[104:105] op_sel_hi:[1,0,1]
	v_pk_fma_f32 v[126:127], v[126:127], v[130:131], v[102:103] op_sel_hi:[1,0,1]
	v_pk_fma_f32 v[134:135], v[124:125], v[130:131], v[100:101] op_sel_hi:[1,0,1]
	v_pk_fma_f32 v[124:125], v[122:123], v[130:131], v[98:99] op_sel_hi:[1,0,1]
	v_cvt_pk_bf16_f32 v122, v126, v127
	v_cvt_pk_bf16_f32 v123, v128, v129
	v_cvt_pk_bf16_f32 v124, v124, v125
	v_cvt_pk_bf16_f32 v125, v134, v135
	global_store_dwordx4 v[132:133], v[122:125], off
	v_pk_fma_f32 v[120:121], v[120:121], v[130:131], v[96:97] op_sel_hi:[1,0,1]
	v_pk_fma_f32 v[118:119], v[118:119], v[130:131], v[94:95] op_sel_hi:[1,0,1]
	v_pk_fma_f32 v[122:123], v[116:117], v[130:131], v[92:93] op_sel_hi:[1,0,1]
	v_pk_fma_f32 v[116:117], v[114:115], v[130:131], v[90:91] op_sel_hi:[1,0,1]
	v_cvt_pk_bf16_f32 v114, v118, v119
	v_cvt_pk_bf16_f32 v115, v120, v121
	v_cvt_pk_bf16_f32 v116, v116, v117
	v_cvt_pk_bf16_f32 v117, v122, v123
	global_store_dwordx4 v[132:133], v[114:117], off offset:256
	v_or_b32_e32 v120, 32, v158
	s_nop 1
	v_add_f32_e32 v114, v200, v201
	v_add_f32_e32 v115, v202, v203
	v_mad_i64_i32 v[116:117], s[34:35], v120, s83, v[160:161]
	v_add_f32_e32 v114, v114, v115
	ds_bpermute_b32 v115, v186, v114
	v_lshl_add_u64 v[116:117], v[116:117], 0, v[176:177]
	s_waitcnt lgkmcnt(0)
; __device__ __forceinline__ unsigned pk2(float lo, float hi) { return pg8::cvt_pk_bf16(lo, hi); }
;     __device__ __forceinline__ void operator()(const f32x4 (&acc)[2][2][4][2], const pg8::Unit& u, int wr, int wc, int fr, int fq) const {
;     ...
;             for (int m = 0; m < 4; ++m) { const int r = row0 + ai * 128 + m * 16, Rg = rowbase + r;
;                 const f32x4 q = *(const f32x4*)(stat + (size_t)Rg * 16 + fq * 4);
;                 float ssq = (q[0] + q[1]) + (q[2] + q[3]); ssq += __shfl_xor(ssq, 16); ssq += __shfl_xor(ssq, 32);
;                 const float rstd = rsqrtf(ssq * (1.f / DM) + 1e-6f);
;                 bf16_t* rowp = O + (size_t)r * ldc + col0;
; #pragma unroll
;                 for (int bj = 0; bj < 2; ++bj) { const f32x4 v0 = acc[ai][bj][m][0] * rstd + bv[bj][0], v1 = acc[ai][bj][m][1] * rstd + bv[bj][1];
;                     u32x4 w; w.x = pk2(v0[0], v0[1]); w.y = pk2(v0[2], v0[3]); w.z = pk2(v1[0], v1[1]); w.w = pk2(v1[2], v1[3]);
;                     *(u32x4*)(rowp + bj * 128) = w; } }
	v_add_f32_e32 v114, v114, v115
	ds_bpermute_b32 v115, v187, v114
	s_waitcnt lgkmcnt(0)
	v_add_f32_e32 v114, v114, v115
	v_fmamk_f32 v114, v114, 0x3a800000, v162
	v_cmp_gt_f32_e32 vcc, s82, v114
	v_mul_f32_e32 v115, 0x4b800000, v114
	s_nop 0
	v_cndmask_b32_e32 v114, v114, v115, vcc
	v_rsq_f32_e32 v114, v114
	s_nop 0
	v_mul_f32_e32 v115, 0x45800000, v114
	v_cndmask_b32_e32 v114, v114, v115, vcc
	v_pk_fma_f32 v[112:113], v[112:113], v[114:115], v[104:105] op_sel_hi:[1,0,1]
	v_pk_fma_f32 v[110:111], v[110:111], v[114:115], v[102:103] op_sel_hi:[1,0,1]
	v_pk_fma_f32 v[118:119], v[108:109], v[114:115], v[100:101] op_sel_hi:[1,0,1]
	v_pk_fma_f32 v[108:109], v[106:107], v[114:115], v[98:99] op_sel_hi:[1,0,1]
	v_cvt_pk_bf16_f32 v106, v110, v111
	v_cvt_pk_bf16_f32 v107, v112, v113
	v_cvt_pk_bf16_f32 v108, v108, v109
	v_cvt_pk_bf16_f32 v109, v118, v119
	global_store_dwordx4 v[116:117], v[106:109], off
	v_pk_fma_f32 v[88:89], v[88:89], v[114:115], v[96:97] op_sel_hi:[1,0,1]
	v_pk_fma_f32 v[86:87], v[86:87], v[114:115], v[94:95] op_sel_hi:[1,0,1]
	v_pk_fma_f32 v[106:107], v[84:85], v[114:115], v[92:93] op_sel_hi:[1,0,1]
	v_pk_fma_f32 v[84:85], v[82:83], v[114:115], v[90:91] op_sel_hi:[1,0,1]
	v_cvt_pk_bf16_f32 v82, v86, v87
	v_cvt_pk_bf16_f32 v83, v88, v89
	v_cvt_pk_bf16_f32 v84, v84, v85
	v_cvt_pk_bf16_f32 v85, v106, v107
	global_store_dwordx4 v[116:117], v[82:85], off offset:256
	v_or_b32_e32 v88, 48, v158
	s_nop 1
	v_add_f32_e32 v82, v204, v205
	v_add_f32_e32 v83, v206, v207
	v_mad_i64_i32 v[84:85], s[34:35], v88, s83, v[160:161]
	v_add_f32_e32 v82, v82, v83
	ds_bpermute_b32 v83, v186, v82
	v_lshl_add_u64 v[84:85], v[84:85], 0, v[176:177]
	s_waitcnt lgkmcnt(0)
	v_add_f32_e32 v82, v82, v83
	ds_bpermute_b32 v83, v187, v82
	s_waitcnt lgkmcnt(0)
	v_add_f32_e32 v82, v82, v83
	v_fmamk_f32 v82, v82, 0x3a800000, v162
	v_cmp_gt_f32_e32 vcc, s82, v82
	v_mul_f32_e32 v83, 0x4b800000, v82
	s_nop 0
	v_cndmask_b32_e32 v82, v82, v83, vcc
	v_rsq_f32_e32 v82, v82
	s_nop 0
	v_mul_f32_e32 v83, 0x45800000, v82
	v_cndmask_b32_e32 v82, v82, v83, vcc
	v_pk_fma_f32 v[80:81], v[80:81], v[82:83], v[104:105] op_sel_hi:[1,0,1]
	v_pk_fma_f32 v[78:79], v[78:79], v[82:83], v[102:103] op_sel_hi:[1,0,1]
	v_pk_fma_f32 v[86:87], v[76:77], v[82:83], v[100:101] op_sel_hi:[1,0,1]
	v_pk_fma_f32 v[76:77], v[74:75], v[82:83], v[98:99] op_sel_hi:[1,0,1]
	v_cvt_pk_bf16_f32 v74, v78, v79
	v_cvt_pk_bf16_f32 v75, v80, v81
	v_cvt_pk_bf16_f32 v76, v76, v77
	v_cvt_pk_bf16_f32 v77, v86, v87
	global_store_dwordx4 v[84:85], v[74:77], off
	v_pk_fma_f32 v[72:73], v[72:73], v[82:83], v[96:97] op_sel_hi:[1,0,1]
	v_pk_fma_f32 v[70:71], v[70:71], v[82:83], v[94:95] op_sel_hi:[1,0,1]
	v_pk_fma_f32 v[74:75], v[68:69], v[82:83], v[92:93] op_sel_hi:[1,0,1]
	v_pk_fma_f32 v[68:69], v[66:67], v[82:83], v[90:91] op_sel_hi:[1,0,1]
	v_cvt_pk_bf16_f32 v66, v70, v71
	v_cvt_pk_bf16_f32 v67, v72, v73
	v_cvt_pk_bf16_f32 v68, v68, v69
	v_cvt_pk_bf16_f32 v69, v74, v75
	global_store_dwordx4 v[84:85], v[66:69], off offset:256
	v_add_u32_e32 v74, 0x80, v158
	s_nop 0
	v_add_co_u32_e32 v66, vcc, s10, v178
	s_nop 1
	v_addc_co_u32_e32 v67, vcc, 0, v179, vcc
	s_nop 1
	v_add_f32_e32 v68, v208, v209
	v_add_f32_e32 v69, v210, v211
	v_mad_i64_i32 v[70:71], s[34:35], v74, s83, v[160:161]
	v_add_f32_e32 v68, v68, v69
	ds_bpermute_b32 v69, v186, v68
	v_lshl_add_u64 v[70:71], v[70:71], 0, v[176:177]
	s_waitcnt lgkmcnt(0)
	v_add_f32_e32 v68, v68, v69
	ds_bpermute_b32 v69, v187, v68
	s_waitcnt lgkmcnt(0)
	v_add_f32_e32 v68, v68, v69
	v_fmamk_f32 v68, v68, 0x3a800000, v162
	v_cmp_gt_f32_e32 vcc, s82, v68
	v_mul_f32_e32 v69, 0x4b800000, v68
	s_nop 0
	v_cndmask_b32_e32 v68, v68, v69, vcc
	v_rsq_f32_e32 v68, v68
	s_nop 0
	v_mul_f32_e32 v69, 0x45800000, v68
	v_cndmask_b32_e32 v68, v68, v69, vcc
	v_pk_fma_f32 v[64:65], v[64:65], v[68:69], v[104:105] op_sel_hi:[1,0,1]
	v_pk_fma_f32 v[62:63], v[62:63], v[68:69], v[102:103] op_sel_hi:[1,0,1]
	v_pk_fma_f32 v[72:73], v[60:61], v[68:69], v[100:101] op_sel_hi:[1,0,1]
	v_pk_fma_f32 v[60:61], v[58:59], v[68:69], v[98:99] op_sel_hi:[1,0,1]
	v_cvt_pk_bf16_f32 v58, v62, v63
	v_cvt_pk_bf16_f32 v59, v64, v65
	v_cvt_pk_bf16_f32 v60, v60, v61
	v_cvt_pk_bf16_f32 v61, v72, v73
	global_store_dwordx4 v[70:71], v[58:61], off
	v_pk_fma_f32 v[56:57], v[56:57], v[68:69], v[96:97] op_sel_hi:[1,0,1]
	v_pk_fma_f32 v[54:55], v[54:55], v[68:69], v[94:95] op_sel_hi:[1,0,1]
	v_pk_fma_f32 v[58:59], v[52:53], v[68:69], v[92:93] op_sel_hi:[1,0,1]
	v_pk_fma_f32 v[52:53], v[50:51], v[68:69], v[90:91] op_sel_hi:[1,0,1]
	v_cvt_pk_bf16_f32 v50, v54, v55
	v_cvt_pk_bf16_f32 v51, v56, v57
	v_cvt_pk_bf16_f32 v52, v52, v53
	v_cvt_pk_bf16_f32 v53, v58, v59
	global_store_dwordx4 v[70:71], v[50:53], off offset:256
	v_add_u32_e32 v56, 0x90, v158
	s_nop 1
	v_add_f32_e32 v50, v212, v213
	v_add_f32_e32 v51, v214, v215
	v_mad_i64_i32 v[52:53], s[34:35], v56, s83, v[160:161]
	v_add_f32_e32 v50, v50, v51
	ds_bpermute_b32 v51, v186, v50
	v_lshl_add_u64 v[52:53], v[52:53], 0, v[176:177]
	s_waitcnt lgkmcnt(0)
; __device__ __forceinline__ unsigned pk2(float lo, float hi) { return pg8::cvt_pk_bf16(lo, hi); }
;     __device__ __forceinline__ void operator()(const f32x4 (&acc)[2][2][4][2], const pg8::Unit& u, int wr, int wc, int fr, int fq) const {
;     ...
;             for (int m = 0; m < 4; ++m) { const int r = row0 + ai * 128 + m * 16, Rg = rowbase + r;
;                 const f32x4 q = *(const f32x4*)(stat + (size_t)Rg * 16 + fq * 4);
;                 float ssq = (q[0] + q[1]) + (q[2] + q[3]); ssq += __shfl_xor(ssq, 16); ssq += __shfl_xor(ssq, 32);
;                 const float rstd = rsqrtf(ssq * (1.f / DM) + 1e-6f);
;                 bf16_t* rowp = O + (size_t)r * ldc + col0;
; #pragma unroll
;                 for (int bj = 0; bj < 2; ++bj) { const f32x4 v0 = acc[ai][bj][m][0] * rstd + bv[bj][0], v1 = acc[ai][bj][m][1] * rstd + bv[bj][1];
;                     u32x4 w; w.x = pk2(v0[0], v0[1]); w.y = pk2(v0[2], v0[3]); w.z = pk2(v1[0], v1[1]); w.w = pk2(v1[2], v1[3]);
;                     *(u32x4*)(rowp + bj * 128) = w; } }
	v_add_f32_e32 v50, v50, v51
	ds_bpermute_b32 v51, v187, v50
	s_waitcnt lgkmcnt(0)
	v_add_f32_e32 v50, v50, v51
	v_fmamk_f32 v50, v50, 0x3a800000, v162
	v_cmp_gt_f32_e32 vcc, s82, v50
	v_mul_f32_e32 v51, 0x4b800000, v50
	s_nop 0
	v_cndmask_b32_e32 v50, v50, v51, vcc
	v_rsq_f32_e32 v50, v50
	s_nop 0
	v_mul_f32_e32 v51, 0x45800000, v50
	v_cndmask_b32_e32 v50, v50, v51, vcc
	v_pk_fma_f32 v[48:49], v[48:49], v[50:51], v[104:105] op_sel_hi:[1,0,1]
	v_pk_fma_f32 v[46:47], v[46:47], v[50:51], v[102:103] op_sel_hi:[1,0,1]
	v_pk_fma_f32 v[54:55], v[44:45], v[50:51], v[100:101] op_sel_hi:[1,0,1]
	v_pk_fma_f32 v[44:45], v[42:43], v[50:51], v[98:99] op_sel_hi:[1,0,1]
	v_cvt_pk_bf16_f32 v42, v46, v47
	v_cvt_pk_bf16_f32 v43, v48, v49
	v_cvt_pk_bf16_f32 v44, v44, v45
	v_cvt_pk_bf16_f32 v45, v54, v55
	global_store_dwordx4 v[52:53], v[42:45], off
	v_pk_fma_f32 v[40:41], v[40:41], v[50:51], v[96:97] op_sel_hi:[1,0,1]
	v_pk_fma_f32 v[38:39], v[38:39], v[50:51], v[94:95] op_sel_hi:[1,0,1]
	v_pk_fma_f32 v[42:43], v[36:37], v[50:51], v[92:93] op_sel_hi:[1,0,1]
	v_pk_fma_f32 v[36:37], v[34:35], v[50:51], v[90:91] op_sel_hi:[1,0,1]
	v_cvt_pk_bf16_f32 v34, v38, v39
	v_cvt_pk_bf16_f32 v35, v40, v41
	v_cvt_pk_bf16_f32 v36, v36, v37
	v_cvt_pk_bf16_f32 v37, v42, v43
	global_store_dwordx4 v[52:53], v[34:37], off offset:256
	v_add_u32_e32 v40, 0xa0, v158
	s_nop 1
	v_add_f32_e32 v34, v216, v217
	v_add_f32_e32 v35, v218, v219
	v_mad_i64_i32 v[36:37], s[34:35], v40, s83, v[160:161]
	v_add_f32_e32 v34, v34, v35
	ds_bpermute_b32 v35, v186, v34
	v_lshl_add_u64 v[36:37], v[36:37], 0, v[176:177]
	s_waitcnt lgkmcnt(0)
	v_add_f32_e32 v34, v34, v35
	ds_bpermute_b32 v35, v187, v34
	s_waitcnt lgkmcnt(0)
	v_add_f32_e32 v34, v34, v35
	v_fmamk_f32 v34, v34, 0x3a800000, v162
	v_cmp_gt_f32_e32 vcc, s82, v34
	v_mul_f32_e32 v35, 0x4b800000, v34
	s_nop 0
	v_cndmask_b32_e32 v34, v34, v35, vcc
	v_rsq_f32_e32 v34, v34
	s_nop 0
	v_mul_f32_e32 v35, 0x45800000, v34
	v_cndmask_b32_e32 v34, v34, v35, vcc
	v_pk_fma_f32 v[32:33], v[32:33], v[34:35], v[104:105] op_sel_hi:[1,0,1]
	v_pk_fma_f32 v[30:31], v[30:31], v[34:35], v[102:103] op_sel_hi:[1,0,1]
	v_pk_fma_f32 v[38:39], v[28:29], v[34:35], v[100:101] op_sel_hi:[1,0,1]
	v_pk_fma_f32 v[28:29], v[26:27], v[34:35], v[98:99] op_sel_hi:[1,0,1]
	v_cvt_pk_bf16_f32 v26, v30, v31
	v_cvt_pk_bf16_f32 v27, v32, v33
	v_cvt_pk_bf16_f32 v28, v28, v29
	v_cvt_pk_bf16_f32 v29, v38, v39
	global_store_dwordx4 v[36:37], v[26:29], off
	v_pk_fma_f32 v[24:25], v[24:25], v[34:35], v[96:97] op_sel_hi:[1,0,1]
	v_pk_fma_f32 v[22:23], v[22:23], v[34:35], v[94:95] op_sel_hi:[1,0,1]
	v_pk_fma_f32 v[26:27], v[20:21], v[34:35], v[92:93] op_sel_hi:[1,0,1]
	v_pk_fma_f32 v[20:21], v[18:19], v[34:35], v[90:91] op_sel_hi:[1,0,1]
	v_cvt_pk_bf16_f32 v18, v22, v23
	v_cvt_pk_bf16_f32 v19, v24, v25
	v_cvt_pk_bf16_f32 v20, v20, v21
	v_cvt_pk_bf16_f32 v21, v26, v27
	global_store_dwordx4 v[36:37], v[18:21], off offset:256
	v_add_u32_e32 v24, 0xb0, v158
	s_nop 1
	v_add_f32_e32 v18, v220, v221
	v_add_f32_e32 v19, v222, v223
	v_mad_i64_i32 v[20:21], s[34:35], v24, s83, v[160:161]
	v_add_f32_e32 v18, v18, v19
	ds_bpermute_b32 v19, v186, v18
	v_lshl_add_u64 v[20:21], v[20:21], 0, v[176:177]
	s_waitcnt lgkmcnt(0)
	v_add_f32_e32 v18, v18, v19
	ds_bpermute_b32 v19, v187, v18
	s_waitcnt lgkmcnt(0)
	v_add_f32_e32 v18, v18, v19
	v_fmamk_f32 v18, v18, 0x3a800000, v162
	v_cmp_gt_f32_e32 vcc, s82, v18
	v_mul_f32_e32 v19, 0x4b800000, v18
	s_nop 0
	v_cndmask_b32_e32 v18, v18, v19, vcc
	v_rsq_f32_e32 v18, v18
	s_nop 0
	v_mul_f32_e32 v19, 0x45800000, v18
	v_cndmask_b32_e32 v18, v18, v19, vcc
	v_pk_fma_f32 v[16:17], v[16:17], v[18:19], v[104:105] op_sel_hi:[1,0,1]
	v_pk_fma_f32 v[14:15], v[14:15], v[18:19], v[102:103] op_sel_hi:[1,0,1]
	v_pk_fma_f32 v[22:23], v[12:13], v[18:19], v[100:101] op_sel_hi:[1,0,1]
	v_pk_fma_f32 v[12:13], v[10:11], v[18:19], v[98:99] op_sel_hi:[1,0,1]
	v_cvt_pk_bf16_f32 v10, v14, v15
	v_cvt_pk_bf16_f32 v11, v16, v17
	v_cvt_pk_bf16_f32 v12, v12, v13
	v_cvt_pk_bf16_f32 v13, v22, v23
	global_store_dwordx4 v[20:21], v[10:13], off
	v_pk_fma_f32 v[8:9], v[8:9], v[18:19], v[96:97] op_sel_hi:[1,0,1]
	v_pk_fma_f32 v[6:7], v[6:7], v[18:19], v[94:95] op_sel_hi:[1,0,1]
	v_pk_fma_f32 v[10:11], v[4:5], v[18:19], v[92:93] op_sel_hi:[1,0,1]
	v_pk_fma_f32 v[4:5], v[2:3], v[18:19], v[90:91] op_sel_hi:[1,0,1]
	v_cvt_pk_bf16_f32 v2, v6, v7
	v_cvt_pk_bf16_f32 v3, v8, v9
	v_cvt_pk_bf16_f32 v4, v4, v5
	v_cvt_pk_bf16_f32 v5, v10, v11
	s_andn2_b64 vcc, exec, s[38:39]
	global_store_dwordx4 v[20:21], v[2:5], off offset:256
	s_cbranch_vccnz .LBB0_158
	s_andn2_b64 vcc, exec, s[18:19]
	s_cbranch_vccnz .LBB0_157
	s_barrier
	s_branch .LBB0_157

; __device__ __forceinline__ unsigned pk2(float lo, float hi) { return pg8::cvt_pk_bf16(lo, hi); }
;     __device__ __forceinline__ void operator()(const f32x4 (&acc)[2][2][4][2], const pg8::Unit& u, int wr, int wc, int fr, int fq) const {
;     ...
;                 const int R = rowbase + u.pm * 256 + ai * 128 + wr * 64 + m * 16 + fr;
;                 const float* src = islat ? rin_l + (size_t)R * DM : rin_c + (size_t)(R - TL) * DM;
;                 float* dst = islat ? rout_l + (size_t)R * DM : rout_c + (size_t)(R - TL) * DM;
;                 float ss = 0.f;
; #pragma unroll
;                 for (int bj = 0; bj < 2; ++bj) { const int c = u.pn * 256 + bj * 128 + wc * 32 + 8 * fq;
;                     const f32x4 xa = *(const f32x4*)(src + c) + gv[bj][0] * acc[ai][bj][m][0];
;                     const f32x4 xb = *(const f32x4*)(src + c + 4) + gv[bj][1] * acc[ai][bj][m][1];
;                     *(f32x4*)(dst + c) = xa; *(f32x4*)(dst + c + 4) = xb;
;                     ss += (xa[0] * xa[0] + xa[1] * xa[1]) + (xa[2] * xa[2] + xa[3] * xa[3]) + (xb[0] * xb[0] + xb[1] * xb[1]) + (xb[2] * xb[2] + xb[3] * xb[3]);
;                     const f32x4 ya = xa * sv[bj][0], yb = xb * sv[bj][1];
;                     u32x4 w; w.x = pk2(ya[0], ya[1]); w.y = pk2(ya[2], ya[3]); w.z = pk2(yb[0], yb[1]); w.w = pk2(yb[2], yb[3]);
;                     *(u32x4*)(Hn + (size_t)R * DM + c) = w; }
;                 ss += __shfl_xor(ss, 16); ss += __shfl_xor(ss, 32);
;                 if (fq == 0) stat[(size_t)R * 16 + u.pn * 4 + wc] = ss;
.LBB0_922:
	s_lshl_b32 s24, s24, 2
	s_ashr_i32 s25, s24, 31
	v_cndmask_b32_e64 v202, v194, v190, s[42:43]
	s_and_b64 s[8:9], s[42:43], exec
	v_ashrrev_i32_e32 v203, 31, v202
	s_cselect_b32 s69, s19, s49
	s_cselect_b32 s68, s18, s48
	v_lshlrev_b64 v[202:203], 12, v[202:203]
	v_lshl_add_u64 v[202:203], s[68:69], 0, v[202:203]
	v_lshl_add_u64 v[212:213], v[202:203], 0, v[188:189]
	s_mov_b32 s100, 0xaaaaaaaa
	s_mov_b32 s101, 0xaaaaaaaa
	v_mov_b32_e32 v222, 0x1000
	v_mov_b32_e32 v223, 16
	v_cndmask_b32_e64 v242, v222, v223, s[100:101]
	v_mov_b32_e32 v243, 0
	global_load_dwordx4 v[202:205], v[212:213], off offset:16
	global_load_dwordx4 v[206:209], v[212:213], off
	v_lshlrev_b64 v[210:211], 11, v[190:191]
	v_and_b32_e32 v200, 64, v228
	v_xor_b32_e32 v195, 16, v228
	v_add_u32_e32 v201, 64, v200
	v_cmp_lt_i32_e32 vcc, v195, v201
	s_waitcnt vmcnt(0)
	v_pk_fma_f32 v[204:205], v[156:157], v[88:89], v[204:205]
	v_pk_fma_f32 v[160:161], v[160:161], v[96:97], v[208:209]
	v_pk_fma_f32 v[158:159], v[158:159], v[94:95], v[206:207]
	v_mul_f32_e32 v157, v161, v161
	v_mul_f32_e32 v156, v159, v159
	v_pk_fma_f32 v[202:203], v[154:155], v[86:87], v[202:203]
	v_fmac_f32_e32 v156, v158, v158
	v_fmac_f32_e32 v157, v160, v160
	v_add_f32_e32 v156, v156, v157
	v_mul_f32_e32 v157, v203, v203
	v_fmac_f32_e32 v157, v202, v202
	v_add_f32_e32 v156, v156, v157
	v_mul_f32_e32 v157, v205, v205
	v_lshl_add_u64 v[154:155], v[192:193], 0, v[188:189]
	v_fmac_f32_e32 v157, v204, v204
	v_cndmask_b32_e64 v222, v202, v158, s[100:101]
	v_cndmask_b32_e64 v223, v203, v159, s[100:101]
	v_cndmask_b32_e64 v224, v204, v160, s[100:101]
	v_cndmask_b32_e64 v225, v205, v161, s[100:101]
	v_mov_b32_dpp v238, v222 quad_perm:[1,0,3,2] row_mask:0xf bank_mask:0xf
	v_mov_b32_dpp v239, v223 quad_perm:[1,0,3,2] row_mask:0xf bank_mask:0xf
	v_mov_b32_dpp v240, v224 quad_perm:[1,0,3,2] row_mask:0xf bank_mask:0xf
	v_mov_b32_dpp v241, v225 quad_perm:[1,0,3,2] row_mask:0xf bank_mask:0xf
	v_cndmask_b32_e64 v214, v158, v238, s[100:101]
	v_cndmask_b32_e64 v218, v238, v202, s[100:101]
	v_cndmask_b32_e64 v215, v159, v239, s[100:101]
	v_cndmask_b32_e64 v219, v239, v203, s[100:101]
	v_cndmask_b32_e64 v216, v160, v240, s[100:101]
	v_cndmask_b32_e64 v220, v240, v204, s[100:101]
	v_cndmask_b32_e64 v217, v161, v241, s[100:101]
	v_cndmask_b32_e64 v221, v241, v205, s[100:101]
	v_lshl_add_u64 v[226:227], v[154:155], 0, v[242:243]
	global_store_dwordx4 v[226:227], v[214:217], off offset:-4096
	global_store_dwordx4 v[226:227], v[218:221], off
	v_add_f32_e32 v194, v157, v156
	v_pk_mul_f32 v[160:161], v[92:93], v[160:161]
	v_pk_mul_f32 v[156:157], v[90:91], v[158:159]
	v_pk_mul_f32 v[192:193], v[84:85], v[204:205]
	v_pk_mul_f32 v[158:159], v[82:83], v[202:203]
	v_cvt_pk_bf16_f32 v156, v156, v157
	v_cvt_pk_bf16_f32 v157, v160, v161
	v_lshl_add_u64 v[160:161], s[60:61], 0, v[210:211]
	v_cvt_pk_bf16_f32 v158, v158, v159
	v_cvt_pk_bf16_f32 v159, v192, v193
	v_lshl_add_u64 v[160:161], v[186:187], 1, v[160:161]
	global_store_dwordx4 v[160:161], v[156:159], off
	global_load_dwordx4 v[156:159], v[212:213], off offset:528
	s_nop 0
	global_load_dwordx4 v[202:205], v[212:213], off offset:512
	v_cndmask_b32_e32 v195, v228, v195, vcc
	v_lshlrev_b32_e32 v200, 2, v195
	v_xor_b32_e32 v195, 32, v228
	v_cmp_lt_i32_e32 vcc, v195, v201
	s_waitcnt vmcnt(1)
	v_pk_fma_f32 v[148:149], v[148:149], v[76:77], v[158:159]
	s_waitcnt vmcnt(0)
	v_pk_fma_f32 v[152:153], v[152:153], v[80:81], v[204:205]
	v_pk_fma_f32 v[150:151], v[150:151], v[78:79], v[202:203]
	v_pk_fma_f32 v[146:147], v[146:147], v[74:75], v[156:157]
	v_cndmask_b32_e64 v222, v146, v150, s[100:101]
	v_cndmask_b32_e64 v223, v147, v151, s[100:101]
	v_cndmask_b32_e64 v224, v148, v152, s[100:101]
	v_cndmask_b32_e64 v225, v149, v153, s[100:101]
	v_mov_b32_dpp v238, v222 quad_perm:[1,0,3,2] row_mask:0xf bank_mask:0xf
	v_mov_b32_dpp v239, v223 quad_perm:[1,0,3,2] row_mask:0xf bank_mask:0xf
	v_mov_b32_dpp v240, v224 quad_perm:[1,0,3,2] row_mask:0xf bank_mask:0xf
	v_mov_b32_dpp v241, v225 quad_perm:[1,0,3,2] row_mask:0xf bank_mask:0xf
	v_cndmask_b32_e64 v214, v150, v238, s[100:101]
	v_cndmask_b32_e64 v218, v238, v146, s[100:101]
	v_cndmask_b32_e64 v215, v151, v239, s[100:101]
	v_cndmask_b32_e64 v219, v239, v147, s[100:101]
	v_cndmask_b32_e64 v216, v152, v240, s[100:101]
	v_cndmask_b32_e64 v220, v240, v148, s[100:101]
	v_cndmask_b32_e64 v217, v153, v241, s[100:101]
	v_cndmask_b32_e64 v221, v241, v149, s[100:101]
	v_lshl_add_u64 v[226:227], v[154:155], 0, v[242:243]
	global_store_dwordx4 v[226:227], v[214:217], off offset:-3584
	global_store_dwordx4 v[226:227], v[218:221], off offset:512
	v_mul_f32_e32 v154, v151, v151
	v_mul_f32_e32 v155, v153, v153
	v_fmac_f32_e32 v154, v150, v150
	v_fmac_f32_e32 v155, v152, v152
	v_add_f32_e32 v154, v154, v155
	v_mul_f32_e32 v155, v147, v147
	v_fmac_f32_e32 v155, v146, v146
	v_add_f32_e32 v154, v154, v155
	v_mul_f32_e32 v155, v149, v149
	v_fmac_f32_e32 v155, v148, v148
	v_add_f32_e32 v154, v155, v154
	v_add_f32_e32 v156, v194, v154
	v_pk_mul_f32 v[152:153], v[64:65], v[152:153]
	v_pk_mul_f32 v[150:151], v[62:63], v[150:151]
	v_pk_mul_f32 v[154:155], v[60:61], v[148:149]
	v_pk_mul_f32 v[148:149], v[58:59], v[146:147]
	v_cvt_pk_bf16_f32 v146, v150, v151
	v_cvt_pk_bf16_f32 v147, v152, v153
	v_cvt_pk_bf16_f32 v148, v148, v149
	v_cvt_pk_bf16_f32 v149, v154, v155
	global_store_dwordx4 v[160:161], v[146:149], off offset:256
	ds_bpermute_b32 v146, v200, v156
	v_cndmask_b32_e32 v195, v228, v195, vcc
	v_lshlrev_b32_e32 v195, 2, v195
	s_waitcnt lgkmcnt(0)
	v_add_f32_e32 v146, v156, v146
	ds_bpermute_b32 v147, v195, v146
	s_and_saveexec_b64 s[34:35], s[38:39]
	s_cbranch_execz .LBB0_924
	v_lshlrev_b64 v[148:149], 6, v[190:191]
	v_lshl_add_u64 v[148:149], s[62:63], 0, v[148:149]
	v_lshl_add_u64 v[148:149], s[24:25], 2, v[148:149]
	s_lshl_b32 s0, s47, 2
	v_lshl_add_u64 v[148:149], v[148:149], 0, s[0:1]
	s_waitcnt lgkmcnt(0)
	v_add_f32_e32 v146, v146, v147
	global_store_dword v[148:149], v146, off

; __device__ __forceinline__ unsigned pk2(float lo, float hi) { return pg8::cvt_pk_bf16(lo, hi); }
;     __device__ __forceinline__ void operator()(const f32x4 (&acc)[2][2][4][2], const pg8::Unit& u, int wr, int wc, int fr, int fq) const {
;     ...
;                 const int R = rowbase + u.pm * 256 + ai * 128 + wr * 64 + m * 16 + fr;
;                 const float* src = islat ? rin_l + (size_t)R * DM : rin_c + (size_t)(R - TL) * DM;
;                 float* dst = islat ? rout_l + (size_t)R * DM : rout_c + (size_t)(R - TL) * DM;
;                 float ss = 0.f;
; #pragma unroll
;                 for (int bj = 0; bj < 2; ++bj) { const int c = u.pn * 256 + bj * 128 + wc * 32 + 8 * fq;
;                     const f32x4 xa = *(const f32x4*)(src + c) + gv[bj][0] * acc[ai][bj][m][0];
;                     const f32x4 xb = *(const f32x4*)(src + c + 4) + gv[bj][1] * acc[ai][bj][m][1];
;                     *(f32x4*)(dst + c) = xa; *(f32x4*)(dst + c + 4) = xb;
;                     ss += (xa[0] * xa[0] + xa[1] * xa[1]) + (xa[2] * xa[2] + xa[3] * xa[3]) + (xb[0] * xb[0] + xb[1] * xb[1]) + (xb[2] * xb[2] + xb[3] * xb[3]);
;                     const f32x4 ya = xa * sv[bj][0], yb = xb * sv[bj][1];
;                     u32x4 w; w.x = pk2(ya[0], ya[1]); w.y = pk2(ya[2], ya[3]); w.z = pk2(yb[0], yb[1]); w.w = pk2(yb[2], yb[3]);
;                     *(u32x4*)(Hn + (size_t)R * DM + c) = w; }
;                 ss += __shfl_xor(ss, 16); ss += __shfl_xor(ss, 32);
;                 if (fq == 0) stat[(size_t)R * 16 + u.pn * 4 + wc] = ss;
.LBB0_928:
	v_cndmask_b32_e64 v150, v150, v146, s[42:43]
	v_ashrrev_i32_e32 v151, 31, v150
	v_lshlrev_b64 v[150:151], 12, v[150:151]
	v_lshl_add_u64 v[150:151], s[68:69], 0, v[150:151]
	v_lshl_add_u64 v[158:159], v[150:151], 0, v[188:189]
	global_load_dwordx4 v[150:153], v[158:159], off
	global_load_dwordx4 v[154:157], v[158:159], off offset:16
	v_lshlrev_b64 v[160:161], 11, v[146:147]
	v_lshl_add_u64 v[192:193], v[148:149], 0, v[188:189]
	v_lshl_add_u64 v[148:149], s[60:61], 0, v[160:161]
	v_lshl_add_u64 v[160:161], v[186:187], 1, v[148:149]
	s_waitcnt vmcnt(1)
	v_pk_fma_f32 v[144:145], v[144:145], v[96:97], v[152:153]
	v_pk_fma_f32 v[142:143], v[142:143], v[94:95], v[150:151]
	s_waitcnt vmcnt(0)
	v_pk_fma_f32 v[140:141], v[140:141], v[88:89], v[156:157]
	v_pk_fma_f32 v[138:139], v[138:139], v[86:87], v[154:155]
	v_pk_mul_f32 v[150:151], v[92:93], v[144:145]
	v_pk_mul_f32 v[148:149], v[90:91], v[142:143]
	v_pk_mul_f32 v[152:153], v[84:85], v[140:141]
	v_pk_mul_f32 v[154:155], v[82:83], v[138:139]
	v_cvt_pk_bf16_f32 v148, v148, v149
	v_cvt_pk_bf16_f32 v149, v150, v151
	v_cvt_pk_bf16_f32 v150, v154, v155
	v_cvt_pk_bf16_f32 v151, v152, v153
	v_cndmask_b32_e64 v222, v138, v142, s[100:101]
	v_cndmask_b32_e64 v223, v139, v143, s[100:101]
	v_cndmask_b32_e64 v224, v140, v144, s[100:101]
	v_cndmask_b32_e64 v225, v141, v145, s[100:101]
	v_mov_b32_dpp v238, v222 quad_perm:[1,0,3,2] row_mask:0xf bank_mask:0xf
	v_mov_b32_dpp v239, v223 quad_perm:[1,0,3,2] row_mask:0xf bank_mask:0xf
	v_mov_b32_dpp v240, v224 quad_perm:[1,0,3,2] row_mask:0xf bank_mask:0xf
	v_mov_b32_dpp v241, v225 quad_perm:[1,0,3,2] row_mask:0xf bank_mask:0xf
	v_cndmask_b32_e64 v214, v142, v238, s[100:101]
	v_cndmask_b32_e64 v218, v238, v138, s[100:101]
	v_cndmask_b32_e64 v215, v143, v239, s[100:101]
	v_cndmask_b32_e64 v219, v239, v139, s[100:101]
	v_cndmask_b32_e64 v216, v144, v240, s[100:101]
	v_cndmask_b32_e64 v220, v240, v140, s[100:101]
	v_cndmask_b32_e64 v217, v145, v241, s[100:101]
	v_cndmask_b32_e64 v221, v241, v141, s[100:101]
	v_lshl_add_u64 v[226:227], v[192:193], 0, v[242:243]
	global_store_dwordx4 v[226:227], v[214:217], off offset:-4096
	global_store_dwordx4 v[226:227], v[218:221], off
	global_store_dwordx4 v[160:161], v[148:151], off
	global_load_dwordx4 v[148:151], v[158:159], off offset:512
	s_nop 0
	global_load_dwordx4 v[152:155], v[158:159], off offset:528
	v_mul_f32_e32 v143, v143, v143
	v_mul_f32_e32 v145, v145, v145
	v_mul_f32_e32 v139, v139, v139
	v_fmac_f32_e32 v143, v142, v142
	v_fmac_f32_e32 v145, v144, v144
	v_mul_f32_e32 v141, v141, v141
	v_fmac_f32_e32 v139, v138, v138
	v_add_f32_e32 v138, v143, v145
	v_fmac_f32_e32 v141, v140, v140
	v_add_f32_e32 v138, v138, v139
	v_add_f32_e32 v138, v141, v138
	s_waitcnt vmcnt(1)
	v_pk_fma_f32 v[136:137], v[136:137], v[80:81], v[150:151]
	v_pk_fma_f32 v[134:135], v[134:135], v[78:79], v[148:149]
	s_waitcnt vmcnt(0)
	v_pk_fma_f32 v[130:131], v[130:131], v[74:75], v[152:153]
	v_mul_f32_e32 v139, v135, v135
	v_mul_f32_e32 v140, v137, v137
	v_pk_fma_f32 v[132:133], v[132:133], v[76:77], v[154:155]
	v_mul_f32_e32 v141, v131, v131
	v_fmac_f32_e32 v139, v134, v134
	v_fmac_f32_e32 v140, v136, v136
	v_mul_f32_e32 v142, v133, v133
	v_fmac_f32_e32 v141, v130, v130
	v_add_f32_e32 v139, v139, v140
	v_fmac_f32_e32 v142, v132, v132
	v_add_f32_e32 v139, v139, v141
	v_add_f32_e32 v139, v142, v139
	v_add_f32_e32 v142, v138, v139
	ds_bpermute_b32 v143, v200, v142
	v_cndmask_b32_e64 v222, v130, v134, s[100:101]
	v_cndmask_b32_e64 v223, v131, v135, s[100:101]
	v_cndmask_b32_e64 v224, v132, v136, s[100:101]
	v_cndmask_b32_e64 v225, v133, v137, s[100:101]
	v_mov_b32_dpp v238, v222 quad_perm:[1,0,3,2] row_mask:0xf bank_mask:0xf
	v_mov_b32_dpp v239, v223 quad_perm:[1,0,3,2] row_mask:0xf bank_mask:0xf
	v_mov_b32_dpp v240, v224 quad_perm:[1,0,3,2] row_mask:0xf bank_mask:0xf
	v_mov_b32_dpp v241, v225 quad_perm:[1,0,3,2] row_mask:0xf bank_mask:0xf
	v_cndmask_b32_e64 v214, v134, v238, s[100:101]
	v_cndmask_b32_e64 v218, v238, v130, s[100:101]
	v_cndmask_b32_e64 v215, v135, v239, s[100:101]
	v_cndmask_b32_e64 v219, v239, v131, s[100:101]
	v_cndmask_b32_e64 v216, v136, v240, s[100:101]
	v_cndmask_b32_e64 v220, v240, v132, s[100:101]
	v_cndmask_b32_e64 v217, v137, v241, s[100:101]
	v_cndmask_b32_e64 v221, v241, v133, s[100:101]
	v_lshl_add_u64 v[226:227], v[192:193], 0, v[242:243]
	global_store_dwordx4 v[226:227], v[214:217], off offset:-3584
	global_store_dwordx4 v[226:227], v[218:221], off offset:512
	v_pk_mul_f32 v[140:141], v[58:59], v[130:131]
	v_pk_mul_f32 v[136:137], v[64:65], v[136:137]
	v_pk_mul_f32 v[134:135], v[62:63], v[134:135]
	s_waitcnt lgkmcnt(0)
	v_add_f32_e32 v130, v142, v143
	ds_bpermute_b32 v131, v195, v130
	v_pk_mul_f32 v[138:139], v[60:61], v[132:133]
	v_cvt_pk_bf16_f32 v132, v134, v135
	v_cvt_pk_bf16_f32 v133, v136, v137
	v_cvt_pk_bf16_f32 v134, v140, v141
	v_cvt_pk_bf16_f32 v135, v138, v139
	global_store_dwordx4 v[160:161], v[132:135], off offset:256
	s_and_saveexec_b64 s[34:35], s[38:39]
	s_cbranch_execz .LBB0_930
	v_lshlrev_b64 v[132:133], 6, v[146:147]
	v_lshl_add_u64 v[132:133], s[62:63], 0, v[132:133]
	v_lshl_add_u64 v[132:133], s[24:25], 2, v[132:133]
	s_lshl_b32 s0, s47, 2
	v_lshl_add_u64 v[132:133], v[132:133], 0, s[0:1]
	s_waitcnt lgkmcnt(0)
	v_add_f32_e32 v130, v130, v131
	global_store_dword v[132:133], v130, off

; __device__ __forceinline__ unsigned pk2(float lo, float hi) { return pg8::cvt_pk_bf16(lo, hi); }
;     __device__ __forceinline__ void operator()(const f32x4 (&acc)[2][2][4][2], const pg8::Unit& u, int wr, int wc, int fr, int fq) const {
;     ...
;                 const int R = rowbase + u.pm * 256 + ai * 128 + wr * 64 + m * 16 + fr;
;                 const float* src = islat ? rin_l + (size_t)R * DM : rin_c + (size_t)(R - TL) * DM;
;                 float* dst = islat ? rout_l + (size_t)R * DM : rout_c + (size_t)(R - TL) * DM;
;                 float ss = 0.f;
; #pragma unroll
;                 for (int bj = 0; bj < 2; ++bj) { const int c = u.pn * 256 + bj * 128 + wc * 32 + 8 * fq;
;                     const f32x4 xa = *(const f32x4*)(src + c) + gv[bj][0] * acc[ai][bj][m][0];
;                     const f32x4 xb = *(const f32x4*)(src + c + 4) + gv[bj][1] * acc[ai][bj][m][1];
;                     *(f32x4*)(dst + c) = xa; *(f32x4*)(dst + c + 4) = xb;
;                     ss += (xa[0] * xa[0] + xa[1] * xa[1]) + (xa[2] * xa[2] + xa[3] * xa[3]) + (xb[0] * xb[0] + xb[1] * xb[1]) + (xb[2] * xb[2] + xb[3] * xb[3]);
;                     const f32x4 ya = xa * sv[bj][0], yb = xb * sv[bj][1];
;                     u32x4 w; w.x = pk2(ya[0], ya[1]); w.y = pk2(ya[2], ya[3]); w.z = pk2(yb[0], yb[1]); w.w = pk2(yb[2], yb[3]);
;                     *(u32x4*)(Hn + (size_t)R * DM + c) = w; }
;                 ss += __shfl_xor(ss, 16); ss += __shfl_xor(ss, 32);
;                 if (fq == 0) stat[(size_t)R * 16 + u.pn * 4 + wc] = ss;
.LBB0_934:
	v_cndmask_b32_e64 v134, v134, v130, s[42:43]
	v_ashrrev_i32_e32 v135, 31, v134
	v_lshlrev_b64 v[134:135], 12, v[134:135]
	v_lshl_add_u64 v[134:135], s[68:69], 0, v[134:135]
	v_lshl_add_u64 v[142:143], v[134:135], 0, v[188:189]
	global_load_dwordx4 v[134:137], v[142:143], off
	global_load_dwordx4 v[138:141], v[142:143], off offset:16
	v_lshlrev_b64 v[144:145], 11, v[130:131]
	v_lshl_add_u64 v[146:147], v[132:133], 0, v[188:189]
	v_lshl_add_u64 v[132:133], s[60:61], 0, v[144:145]
	v_lshl_add_u64 v[144:145], v[186:187], 1, v[132:133]
	s_waitcnt vmcnt(1)
	v_pk_fma_f32 v[128:129], v[128:129], v[96:97], v[136:137]
	v_pk_fma_f32 v[126:127], v[126:127], v[94:95], v[134:135]
	s_waitcnt vmcnt(0)
	v_pk_fma_f32 v[124:125], v[124:125], v[88:89], v[140:141]
	v_pk_fma_f32 v[122:123], v[122:123], v[86:87], v[138:139]
	v_pk_mul_f32 v[134:135], v[92:93], v[128:129]
	v_pk_mul_f32 v[132:133], v[90:91], v[126:127]
	v_pk_mul_f32 v[136:137], v[84:85], v[124:125]
	v_pk_mul_f32 v[138:139], v[82:83], v[122:123]
	v_cvt_pk_bf16_f32 v132, v132, v133
	v_cvt_pk_bf16_f32 v133, v134, v135
	v_cvt_pk_bf16_f32 v134, v138, v139
	v_cvt_pk_bf16_f32 v135, v136, v137
	v_cndmask_b32_e64 v222, v122, v126, s[100:101]
	v_cndmask_b32_e64 v223, v123, v127, s[100:101]
	v_cndmask_b32_e64 v224, v124, v128, s[100:101]
	v_cndmask_b32_e64 v225, v125, v129, s[100:101]
	v_mov_b32_dpp v238, v222 quad_perm:[1,0,3,2] row_mask:0xf bank_mask:0xf
	v_mov_b32_dpp v239, v223 quad_perm:[1,0,3,2] row_mask:0xf bank_mask:0xf
	v_mov_b32_dpp v240, v224 quad_perm:[1,0,3,2] row_mask:0xf bank_mask:0xf
	v_mov_b32_dpp v241, v225 quad_perm:[1,0,3,2] row_mask:0xf bank_mask:0xf
	v_cndmask_b32_e64 v214, v126, v238, s[100:101]
	v_cndmask_b32_e64 v218, v238, v122, s[100:101]
	v_cndmask_b32_e64 v215, v127, v239, s[100:101]
	v_cndmask_b32_e64 v219, v239, v123, s[100:101]
	v_cndmask_b32_e64 v216, v128, v240, s[100:101]
	v_cndmask_b32_e64 v220, v240, v124, s[100:101]
	v_cndmask_b32_e64 v217, v129, v241, s[100:101]
	v_cndmask_b32_e64 v221, v241, v125, s[100:101]
	v_lshl_add_u64 v[226:227], v[146:147], 0, v[242:243]
	global_store_dwordx4 v[226:227], v[214:217], off offset:-4096
	global_store_dwordx4 v[226:227], v[218:221], off
	global_store_dwordx4 v[144:145], v[132:135], off
	global_load_dwordx4 v[132:135], v[142:143], off offset:512
	s_nop 0
	global_load_dwordx4 v[136:139], v[142:143], off offset:528
	v_mul_f32_e32 v127, v127, v127
	v_mul_f32_e32 v129, v129, v129
	v_mul_f32_e32 v123, v123, v123
	v_fmac_f32_e32 v127, v126, v126
	v_fmac_f32_e32 v129, v128, v128
	v_mul_f32_e32 v125, v125, v125
	v_fmac_f32_e32 v123, v122, v122
	v_add_f32_e32 v122, v127, v129
	v_fmac_f32_e32 v125, v124, v124
	v_add_f32_e32 v122, v122, v123
	v_add_f32_e32 v122, v125, v122
	s_waitcnt vmcnt(1)
	v_pk_fma_f32 v[120:121], v[120:121], v[80:81], v[134:135]
	v_pk_fma_f32 v[118:119], v[118:119], v[78:79], v[132:133]
	s_waitcnt vmcnt(0)
	v_pk_fma_f32 v[114:115], v[114:115], v[74:75], v[136:137]
	v_mul_f32_e32 v123, v119, v119
	v_mul_f32_e32 v124, v121, v121
	v_pk_fma_f32 v[116:117], v[116:117], v[76:77], v[138:139]
	v_mul_f32_e32 v125, v115, v115
	v_fmac_f32_e32 v123, v118, v118
	v_fmac_f32_e32 v124, v120, v120
	v_mul_f32_e32 v126, v117, v117
	v_fmac_f32_e32 v125, v114, v114
	v_add_f32_e32 v123, v123, v124
	v_fmac_f32_e32 v126, v116, v116
	v_add_f32_e32 v123, v123, v125
	v_add_f32_e32 v123, v126, v123
	v_add_f32_e32 v126, v122, v123
	ds_bpermute_b32 v127, v200, v126
	v_cndmask_b32_e64 v222, v114, v118, s[100:101]
	v_cndmask_b32_e64 v223, v115, v119, s[100:101]
	v_cndmask_b32_e64 v224, v116, v120, s[100:101]
	v_cndmask_b32_e64 v225, v117, v121, s[100:101]
	v_mov_b32_dpp v238, v222 quad_perm:[1,0,3,2] row_mask:0xf bank_mask:0xf
	v_mov_b32_dpp v239, v223 quad_perm:[1,0,3,2] row_mask:0xf bank_mask:0xf
	v_mov_b32_dpp v240, v224 quad_perm:[1,0,3,2] row_mask:0xf bank_mask:0xf
	v_mov_b32_dpp v241, v225 quad_perm:[1,0,3,2] row_mask:0xf bank_mask:0xf
	v_cndmask_b32_e64 v214, v118, v238, s[100:101]
	v_cndmask_b32_e64 v218, v238, v114, s[100:101]
	v_cndmask_b32_e64 v215, v119, v239, s[100:101]
	v_cndmask_b32_e64 v219, v239, v115, s[100:101]
	v_cndmask_b32_e64 v216, v120, v240, s[100:101]
	v_cndmask_b32_e64 v220, v240, v116, s[100:101]
	v_cndmask_b32_e64 v217, v121, v241, s[100:101]
	v_cndmask_b32_e64 v221, v241, v117, s[100:101]
	v_lshl_add_u64 v[226:227], v[146:147], 0, v[242:243]
	global_store_dwordx4 v[226:227], v[214:217], off offset:-3584
	global_store_dwordx4 v[226:227], v[218:221], off offset:512
	v_pk_mul_f32 v[124:125], v[58:59], v[114:115]
	v_pk_mul_f32 v[120:121], v[64:65], v[120:121]
	v_pk_mul_f32 v[118:119], v[62:63], v[118:119]
	s_waitcnt lgkmcnt(0)
	v_add_f32_e32 v114, v126, v127
	ds_bpermute_b32 v115, v195, v114
	v_pk_mul_f32 v[122:123], v[60:61], v[116:117]
	v_cvt_pk_bf16_f32 v116, v118, v119
	v_cvt_pk_bf16_f32 v117, v120, v121
	v_cvt_pk_bf16_f32 v118, v124, v125
	v_cvt_pk_bf16_f32 v119, v122, v123
	global_store_dwordx4 v[144:145], v[116:119], off offset:256
	s_and_saveexec_b64 s[34:35], s[38:39]
	s_cbranch_execz .LBB0_936
	v_lshlrev_b64 v[116:117], 6, v[130:131]
	v_lshl_add_u64 v[116:117], s[62:63], 0, v[116:117]
	v_lshl_add_u64 v[116:117], s[24:25], 2, v[116:117]
	s_lshl_b32 s0, s47, 2
	v_lshl_add_u64 v[116:117], v[116:117], 0, s[0:1]
	s_waitcnt lgkmcnt(0)
	v_add_f32_e32 v114, v114, v115
	global_store_dword v[116:117], v114, off

; __device__ __forceinline__ unsigned pk2(float lo, float hi) { return pg8::cvt_pk_bf16(lo, hi); }
;     __device__ __forceinline__ void operator()(const f32x4 (&acc)[2][2][4][2], const pg8::Unit& u, int wr, int wc, int fr, int fq) const {
;     ...
;                 const int R = rowbase + u.pm * 256 + ai * 128 + wr * 64 + m * 16 + fr;
;                 const float* src = islat ? rin_l + (size_t)R * DM : rin_c + (size_t)(R - TL) * DM;
;                 float* dst = islat ? rout_l + (size_t)R * DM : rout_c + (size_t)(R - TL) * DM;
;                 float ss = 0.f;
; #pragma unroll
;                 for (int bj = 0; bj < 2; ++bj) { const int c = u.pn * 256 + bj * 128 + wc * 32 + 8 * fq;
;                     const f32x4 xa = *(const f32x4*)(src + c) + gv[bj][0] * acc[ai][bj][m][0];
;                     const f32x4 xb = *(const f32x4*)(src + c + 4) + gv[bj][1] * acc[ai][bj][m][1];
;                     *(f32x4*)(dst + c) = xa; *(f32x4*)(dst + c + 4) = xb;
;                     ss += (xa[0] * xa[0] + xa[1] * xa[1]) + (xa[2] * xa[2] + xa[3] * xa[3]) + (xb[0] * xb[0] + xb[1] * xb[1]) + (xb[2] * xb[2] + xb[3] * xb[3]);
;                     const f32x4 ya = xa * sv[bj][0], yb = xb * sv[bj][1];
;                     u32x4 w; w.x = pk2(ya[0], ya[1]); w.y = pk2(ya[2], ya[3]); w.z = pk2(yb[0], yb[1]); w.w = pk2(yb[2], yb[3]);
;                     *(u32x4*)(Hn + (size_t)R * DM + c) = w; }
;                 ss += __shfl_xor(ss, 16); ss += __shfl_xor(ss, 32);
;                 if (fq == 0) stat[(size_t)R * 16 + u.pn * 4 + wc] = ss;
.LBB0_940:
	v_cndmask_b32_e64 v118, v118, v114, s[42:43]
	v_ashrrev_i32_e32 v119, 31, v118
	v_lshlrev_b64 v[118:119], 12, v[118:119]
	v_lshl_add_u64 v[118:119], s[68:69], 0, v[118:119]
	v_lshl_add_u64 v[126:127], v[118:119], 0, v[188:189]
	global_load_dwordx4 v[118:121], v[126:127], off
	global_load_dwordx4 v[122:125], v[126:127], off offset:16
	v_lshlrev_b64 v[128:129], 11, v[114:115]
	v_lshl_add_u64 v[130:131], v[116:117], 0, v[188:189]
	v_lshl_add_u64 v[116:117], s[60:61], 0, v[128:129]
	v_lshl_add_u64 v[128:129], v[186:187], 1, v[116:117]
	s_waitcnt vmcnt(1)
	v_pk_fma_f32 v[112:113], v[112:113], v[96:97], v[120:121]
	v_pk_fma_f32 v[110:111], v[110:111], v[94:95], v[118:119]
	s_waitcnt vmcnt(0)
	v_pk_fma_f32 v[108:109], v[108:109], v[88:89], v[124:125]
	v_pk_fma_f32 v[106:107], v[106:107], v[86:87], v[122:123]
	v_pk_mul_f32 v[118:119], v[92:93], v[112:113]
	v_pk_mul_f32 v[116:117], v[90:91], v[110:111]
	v_pk_mul_f32 v[120:121], v[84:85], v[108:109]
	v_pk_mul_f32 v[122:123], v[82:83], v[106:107]
	v_cvt_pk_bf16_f32 v116, v116, v117
	v_cvt_pk_bf16_f32 v117, v118, v119
	v_cvt_pk_bf16_f32 v118, v122, v123
	v_cvt_pk_bf16_f32 v119, v120, v121
	v_cndmask_b32_e64 v222, v106, v110, s[100:101]
	v_cndmask_b32_e64 v223, v107, v111, s[100:101]
	v_cndmask_b32_e64 v224, v108, v112, s[100:101]
	v_cndmask_b32_e64 v225, v109, v113, s[100:101]
	v_mov_b32_dpp v238, v222 quad_perm:[1,0,3,2] row_mask:0xf bank_mask:0xf
	v_mov_b32_dpp v239, v223 quad_perm:[1,0,3,2] row_mask:0xf bank_mask:0xf
	v_mov_b32_dpp v240, v224 quad_perm:[1,0,3,2] row_mask:0xf bank_mask:0xf
	v_mov_b32_dpp v241, v225 quad_perm:[1,0,3,2] row_mask:0xf bank_mask:0xf
	v_cndmask_b32_e64 v214, v110, v238, s[100:101]
	v_cndmask_b32_e64 v218, v238, v106, s[100:101]
	v_cndmask_b32_e64 v215, v111, v239, s[100:101]
	v_cndmask_b32_e64 v219, v239, v107, s[100:101]
	v_cndmask_b32_e64 v216, v112, v240, s[100:101]
	v_cndmask_b32_e64 v220, v240, v108, s[100:101]
	v_cndmask_b32_e64 v217, v113, v241, s[100:101]
	v_cndmask_b32_e64 v221, v241, v109, s[100:101]
	v_lshl_add_u64 v[226:227], v[130:131], 0, v[242:243]
	global_store_dwordx4 v[226:227], v[214:217], off offset:-4096
	global_store_dwordx4 v[226:227], v[218:221], off
	global_store_dwordx4 v[128:129], v[116:119], off
	global_load_dwordx4 v[116:119], v[126:127], off offset:512
	s_nop 0
	global_load_dwordx4 v[120:123], v[126:127], off offset:528
	v_mul_f32_e32 v111, v111, v111
	v_mul_f32_e32 v113, v113, v113
	v_mul_f32_e32 v107, v107, v107
	v_fmac_f32_e32 v111, v110, v110
	v_fmac_f32_e32 v113, v112, v112
	v_mul_f32_e32 v109, v109, v109
	v_fmac_f32_e32 v107, v106, v106
	v_add_f32_e32 v106, v111, v113
	v_fmac_f32_e32 v109, v108, v108
	v_add_f32_e32 v106, v106, v107
	v_add_f32_e32 v106, v109, v106
	s_waitcnt vmcnt(1)
	v_pk_fma_f32 v[104:105], v[104:105], v[80:81], v[118:119]
	v_pk_fma_f32 v[102:103], v[102:103], v[78:79], v[116:117]
	s_waitcnt vmcnt(0)
	v_pk_fma_f32 v[98:99], v[98:99], v[74:75], v[120:121]
	v_mul_f32_e32 v107, v103, v103
	v_mul_f32_e32 v108, v105, v105
	v_pk_fma_f32 v[100:101], v[100:101], v[76:77], v[122:123]
	v_mul_f32_e32 v109, v99, v99
	v_fmac_f32_e32 v107, v102, v102
	v_fmac_f32_e32 v108, v104, v104
	v_mul_f32_e32 v110, v101, v101
	v_fmac_f32_e32 v109, v98, v98
	v_add_f32_e32 v107, v107, v108
	v_fmac_f32_e32 v110, v100, v100
	v_add_f32_e32 v107, v107, v109
	v_add_f32_e32 v107, v110, v107
	v_add_f32_e32 v110, v106, v107
	ds_bpermute_b32 v111, v200, v110
	v_cndmask_b32_e64 v222, v98, v102, s[100:101]
	v_cndmask_b32_e64 v223, v99, v103, s[100:101]
	v_cndmask_b32_e64 v224, v100, v104, s[100:101]
	v_cndmask_b32_e64 v225, v101, v105, s[100:101]
	v_mov_b32_dpp v238, v222 quad_perm:[1,0,3,2] row_mask:0xf bank_mask:0xf
	v_mov_b32_dpp v239, v223 quad_perm:[1,0,3,2] row_mask:0xf bank_mask:0xf
	v_mov_b32_dpp v240, v224 quad_perm:[1,0,3,2] row_mask:0xf bank_mask:0xf
	v_mov_b32_dpp v241, v225 quad_perm:[1,0,3,2] row_mask:0xf bank_mask:0xf
	v_cndmask_b32_e64 v214, v102, v238, s[100:101]
	v_cndmask_b32_e64 v218, v238, v98, s[100:101]
	v_cndmask_b32_e64 v215, v103, v239, s[100:101]
	v_cndmask_b32_e64 v219, v239, v99, s[100:101]
	v_cndmask_b32_e64 v216, v104, v240, s[100:101]
	v_cndmask_b32_e64 v220, v240, v100, s[100:101]
	v_cndmask_b32_e64 v217, v105, v241, s[100:101]
	v_cndmask_b32_e64 v221, v241, v101, s[100:101]
	v_lshl_add_u64 v[226:227], v[130:131], 0, v[242:243]
	global_store_dwordx4 v[226:227], v[214:217], off offset:-3584
	global_store_dwordx4 v[226:227], v[218:221], off offset:512
	v_pk_mul_f32 v[108:109], v[58:59], v[98:99]
	v_pk_mul_f32 v[104:105], v[64:65], v[104:105]
	v_pk_mul_f32 v[102:103], v[62:63], v[102:103]
	s_waitcnt lgkmcnt(0)
	v_add_f32_e32 v98, v110, v111
	ds_bpermute_b32 v99, v195, v98
	v_pk_mul_f32 v[106:107], v[60:61], v[100:101]
	v_cvt_pk_bf16_f32 v100, v102, v103
	v_cvt_pk_bf16_f32 v101, v104, v105
	v_cvt_pk_bf16_f32 v102, v108, v109
	v_cvt_pk_bf16_f32 v103, v106, v107
	global_store_dwordx4 v[128:129], v[100:103], off offset:256
	s_and_saveexec_b64 s[34:35], s[38:39]
	s_cbranch_execz .LBB0_942
	v_lshlrev_b64 v[100:101], 6, v[114:115]
	v_lshl_add_u64 v[100:101], s[62:63], 0, v[100:101]
	v_lshl_add_u64 v[100:101], s[24:25], 2, v[100:101]
	s_lshl_b32 s0, s47, 2
	v_lshl_add_u64 v[100:101], v[100:101], 0, s[0:1]
	s_waitcnt lgkmcnt(0)
	v_add_f32_e32 v98, v98, v99
	global_store_dword v[100:101], v98, off

; __device__ __forceinline__ unsigned pk2(float lo, float hi) { return pg8::cvt_pk_bf16(lo, hi); }
;     __device__ __forceinline__ void operator()(const f32x4 (&acc)[2][2][4][2], const pg8::Unit& u, int wr, int wc, int fr, int fq) const {
;     ...
;                 const int R = rowbase + u.pm * 256 + ai * 128 + wr * 64 + m * 16 + fr;
;                 const float* src = islat ? rin_l + (size_t)R * DM : rin_c + (size_t)(R - TL) * DM;
;                 float* dst = islat ? rout_l + (size_t)R * DM : rout_c + (size_t)(R - TL) * DM;
;                 float ss = 0.f;
; #pragma unroll
;                 for (int bj = 0; bj < 2; ++bj) { const int c = u.pn * 256 + bj * 128 + wc * 32 + 8 * fq;
;                     const f32x4 xa = *(const f32x4*)(src + c) + gv[bj][0] * acc[ai][bj][m][0];
;                     const f32x4 xb = *(const f32x4*)(src + c + 4) + gv[bj][1] * acc[ai][bj][m][1];
;                     *(f32x4*)(dst + c) = xa; *(f32x4*)(dst + c + 4) = xb;
;                     ss += (xa[0] * xa[0] + xa[1] * xa[1]) + (xa[2] * xa[2] + xa[3] * xa[3]) + (xb[0] * xb[0] + xb[1] * xb[1]) + (xb[2] * xb[2] + xb[3] * xb[3]);
;                     const f32x4 ya = xa * sv[bj][0], yb = xb * sv[bj][1];
;                     u32x4 w; w.x = pk2(ya[0], ya[1]); w.y = pk2(ya[2], ya[3]); w.z = pk2(yb[0], yb[1]); w.w = pk2(yb[2], yb[3]);
;                     *(u32x4*)(Hn + (size_t)R * DM + c) = w; }
;                 ss += __shfl_xor(ss, 16); ss += __shfl_xor(ss, 32);
;                 if (fq == 0) stat[(size_t)R * 16 + u.pn * 4 + wc] = ss;
.LBB0_946:
	v_cndmask_b32_e64 v102, v102, v98, s[42:43]
	v_ashrrev_i32_e32 v103, 31, v102
	v_lshlrev_b64 v[102:103], 12, v[102:103]
	v_lshl_add_u64 v[102:103], s[68:69], 0, v[102:103]
	v_lshl_add_u64 v[110:111], v[102:103], 0, v[188:189]
	global_load_dwordx4 v[102:105], v[110:111], off
	global_load_dwordx4 v[106:109], v[110:111], off offset:16
	v_lshlrev_b64 v[112:113], 11, v[98:99]
	v_lshl_add_u64 v[114:115], v[100:101], 0, v[188:189]
	v_lshl_add_u64 v[100:101], s[60:61], 0, v[112:113]
	v_lshl_add_u64 v[112:113], v[186:187], 1, v[100:101]
	s_waitcnt vmcnt(1)
	v_pk_fma_f32 v[72:73], v[72:73], v[96:97], v[104:105]
	v_pk_fma_f32 v[70:71], v[70:71], v[94:95], v[102:103]
	s_waitcnt vmcnt(0)
	v_pk_fma_f32 v[68:69], v[68:69], v[88:89], v[108:109]
	v_pk_fma_f32 v[66:67], v[66:67], v[86:87], v[106:107]
	v_pk_mul_f32 v[102:103], v[92:93], v[72:73]
	v_pk_mul_f32 v[100:101], v[90:91], v[70:71]
	v_pk_mul_f32 v[104:105], v[84:85], v[68:69]
	v_pk_mul_f32 v[106:107], v[82:83], v[66:67]
	v_cvt_pk_bf16_f32 v100, v100, v101
	v_cvt_pk_bf16_f32 v101, v102, v103
	v_cvt_pk_bf16_f32 v102, v106, v107
	v_cvt_pk_bf16_f32 v103, v104, v105
	v_cndmask_b32_e64 v222, v66, v70, s[100:101]
	v_cndmask_b32_e64 v223, v67, v71, s[100:101]
	v_cndmask_b32_e64 v224, v68, v72, s[100:101]
	v_cndmask_b32_e64 v225, v69, v73, s[100:101]
	v_mov_b32_dpp v238, v222 quad_perm:[1,0,3,2] row_mask:0xf bank_mask:0xf
	v_mov_b32_dpp v239, v223 quad_perm:[1,0,3,2] row_mask:0xf bank_mask:0xf
	v_mov_b32_dpp v240, v224 quad_perm:[1,0,3,2] row_mask:0xf bank_mask:0xf
	v_mov_b32_dpp v241, v225 quad_perm:[1,0,3,2] row_mask:0xf bank_mask:0xf
	v_cndmask_b32_e64 v214, v70, v238, s[100:101]
	v_cndmask_b32_e64 v218, v238, v66, s[100:101]
	v_cndmask_b32_e64 v215, v71, v239, s[100:101]
	v_cndmask_b32_e64 v219, v239, v67, s[100:101]
	v_cndmask_b32_e64 v216, v72, v240, s[100:101]
	v_cndmask_b32_e64 v220, v240, v68, s[100:101]
	v_cndmask_b32_e64 v217, v73, v241, s[100:101]
	v_cndmask_b32_e64 v221, v241, v69, s[100:101]
	v_lshl_add_u64 v[226:227], v[114:115], 0, v[242:243]
	global_store_dwordx4 v[226:227], v[214:217], off offset:-4096
	global_store_dwordx4 v[226:227], v[218:221], off
	global_store_dwordx4 v[112:113], v[100:103], off
	global_load_dwordx4 v[100:103], v[110:111], off offset:512
	s_nop 0
	global_load_dwordx4 v[104:107], v[110:111], off offset:528
	v_mul_f32_e32 v71, v71, v71
	v_mul_f32_e32 v73, v73, v73
	v_mul_f32_e32 v67, v67, v67
	v_fmac_f32_e32 v71, v70, v70
	v_fmac_f32_e32 v73, v72, v72
	v_mul_f32_e32 v69, v69, v69
	v_fmac_f32_e32 v67, v66, v66
	v_add_f32_e32 v66, v71, v73
	v_fmac_f32_e32 v69, v68, v68
	v_add_f32_e32 v66, v66, v67
	v_add_f32_e32 v66, v69, v66
	s_waitcnt vmcnt(1)
	v_pk_fma_f32 v[56:57], v[56:57], v[80:81], v[102:103]
	v_pk_fma_f32 v[54:55], v[54:55], v[78:79], v[100:101]
	s_waitcnt vmcnt(0)
	v_pk_fma_f32 v[50:51], v[50:51], v[74:75], v[104:105]
	v_mul_f32_e32 v67, v55, v55
	v_mul_f32_e32 v68, v57, v57
	v_pk_fma_f32 v[52:53], v[52:53], v[76:77], v[106:107]
	v_mul_f32_e32 v69, v51, v51
	v_fmac_f32_e32 v67, v54, v54
	v_fmac_f32_e32 v68, v56, v56
	v_mul_f32_e32 v70, v53, v53
	v_fmac_f32_e32 v69, v50, v50
	v_add_f32_e32 v67, v67, v68
	v_fmac_f32_e32 v70, v52, v52
	v_add_f32_e32 v67, v67, v69
	v_add_f32_e32 v67, v70, v67
	v_add_f32_e32 v70, v66, v67
	ds_bpermute_b32 v71, v200, v70
	v_cndmask_b32_e64 v222, v50, v54, s[100:101]
	v_cndmask_b32_e64 v223, v51, v55, s[100:101]
	v_cndmask_b32_e64 v224, v52, v56, s[100:101]
	v_cndmask_b32_e64 v225, v53, v57, s[100:101]
	v_mov_b32_dpp v238, v222 quad_perm:[1,0,3,2] row_mask:0xf bank_mask:0xf
	v_mov_b32_dpp v239, v223 quad_perm:[1,0,3,2] row_mask:0xf bank_mask:0xf
	v_mov_b32_dpp v240, v224 quad_perm:[1,0,3,2] row_mask:0xf bank_mask:0xf
	v_mov_b32_dpp v241, v225 quad_perm:[1,0,3,2] row_mask:0xf bank_mask:0xf
	v_cndmask_b32_e64 v214, v54, v238, s[100:101]
	v_cndmask_b32_e64 v218, v238, v50, s[100:101]
	v_cndmask_b32_e64 v215, v55, v239, s[100:101]
	v_cndmask_b32_e64 v219, v239, v51, s[100:101]
	v_cndmask_b32_e64 v216, v56, v240, s[100:101]
	v_cndmask_b32_e64 v220, v240, v52, s[100:101]
	v_cndmask_b32_e64 v217, v57, v241, s[100:101]
	v_cndmask_b32_e64 v221, v241, v53, s[100:101]
	v_lshl_add_u64 v[226:227], v[114:115], 0, v[242:243]
	global_store_dwordx4 v[226:227], v[214:217], off offset:-3584
	global_store_dwordx4 v[226:227], v[218:221], off offset:512
	v_pk_mul_f32 v[68:69], v[58:59], v[50:51]
	v_pk_mul_f32 v[56:57], v[64:65], v[56:57]
	v_pk_mul_f32 v[54:55], v[62:63], v[54:55]
	s_waitcnt lgkmcnt(0)
	v_add_f32_e32 v50, v70, v71
	ds_bpermute_b32 v51, v195, v50
	v_pk_mul_f32 v[66:67], v[60:61], v[52:53]
	v_cvt_pk_bf16_f32 v52, v54, v55
	v_cvt_pk_bf16_f32 v53, v56, v57
	v_cvt_pk_bf16_f32 v54, v68, v69
	v_cvt_pk_bf16_f32 v55, v66, v67
	global_store_dwordx4 v[112:113], v[52:55], off offset:256
	s_and_saveexec_b64 s[34:35], s[38:39]
	s_cbranch_execz .LBB0_948
	v_lshlrev_b64 v[52:53], 6, v[98:99]
	v_lshl_add_u64 v[52:53], s[62:63], 0, v[52:53]
	v_lshl_add_u64 v[52:53], s[24:25], 2, v[52:53]
	s_lshl_b32 s0, s47, 2
	v_lshl_add_u64 v[52:53], v[52:53], 0, s[0:1]
	s_waitcnt lgkmcnt(0)
	v_add_f32_e32 v50, v50, v51
	global_store_dword v[52:53], v50, off

; __device__ __forceinline__ unsigned pk2(float lo, float hi) { return pg8::cvt_pk_bf16(lo, hi); }
;     __device__ __forceinline__ void operator()(const f32x4 (&acc)[2][2][4][2], const pg8::Unit& u, int wr, int wc, int fr, int fq) const {
;     ...
;                 const int R = rowbase + u.pm * 256 + ai * 128 + wr * 64 + m * 16 + fr;
;                 const float* src = islat ? rin_l + (size_t)R * DM : rin_c + (size_t)(R - TL) * DM;
;                 float* dst = islat ? rout_l + (size_t)R * DM : rout_c + (size_t)(R - TL) * DM;
;                 float ss = 0.f;
; #pragma unroll
;                 for (int bj = 0; bj < 2; ++bj) { const int c = u.pn * 256 + bj * 128 + wc * 32 + 8 * fq;
;                     const f32x4 xa = *(const f32x4*)(src + c) + gv[bj][0] * acc[ai][bj][m][0];
;                     const f32x4 xb = *(const f32x4*)(src + c + 4) + gv[bj][1] * acc[ai][bj][m][1];
;                     *(f32x4*)(dst + c) = xa; *(f32x4*)(dst + c + 4) = xb;
;                     ss += (xa[0] * xa[0] + xa[1] * xa[1]) + (xa[2] * xa[2] + xa[3] * xa[3]) + (xb[0] * xb[0] + xb[1] * xb[1]) + (xb[2] * xb[2] + xb[3] * xb[3]);
;                     const f32x4 ya = xa * sv[bj][0], yb = xb * sv[bj][1];
;                     u32x4 w; w.x = pk2(ya[0], ya[1]); w.y = pk2(ya[2], ya[3]); w.z = pk2(yb[0], yb[1]); w.w = pk2(yb[2], yb[3]);
;                     *(u32x4*)(Hn + (size_t)R * DM + c) = w; }
;                 ss += __shfl_xor(ss, 16); ss += __shfl_xor(ss, 32);
;                 if (fq == 0) stat[(size_t)R * 16 + u.pn * 4 + wc] = ss;
.LBB0_952:
	v_cndmask_b32_e64 v54, v54, v50, s[42:43]
	v_ashrrev_i32_e32 v55, 31, v54
	v_lshlrev_b64 v[54:55], 12, v[54:55]
	v_lshl_add_u64 v[54:55], s[68:69], 0, v[54:55]
	v_lshl_add_u64 v[70:71], v[54:55], 0, v[188:189]
	global_load_dwordx4 v[54:57], v[70:71], off
	global_load_dwordx4 v[66:69], v[70:71], off offset:16
	v_lshlrev_b64 v[72:73], 11, v[50:51]
	v_lshl_add_u64 v[98:99], v[52:53], 0, v[188:189]
	v_lshl_add_u64 v[52:53], s[60:61], 0, v[72:73]
	v_lshl_add_u64 v[72:73], v[186:187], 1, v[52:53]
	s_waitcnt vmcnt(1)
	v_pk_fma_f32 v[48:49], v[48:49], v[96:97], v[56:57]
	v_pk_fma_f32 v[46:47], v[46:47], v[94:95], v[54:55]
	s_waitcnt vmcnt(0)
	v_pk_fma_f32 v[44:45], v[44:45], v[88:89], v[68:69]
	v_pk_fma_f32 v[42:43], v[42:43], v[86:87], v[66:67]
	v_pk_mul_f32 v[54:55], v[92:93], v[48:49]
	v_pk_mul_f32 v[52:53], v[90:91], v[46:47]
	v_pk_mul_f32 v[56:57], v[84:85], v[44:45]
	v_pk_mul_f32 v[66:67], v[82:83], v[42:43]
	v_cvt_pk_bf16_f32 v52, v52, v53
	v_cvt_pk_bf16_f32 v53, v54, v55
	v_cvt_pk_bf16_f32 v54, v66, v67
	v_cvt_pk_bf16_f32 v55, v56, v57
	v_cndmask_b32_e64 v222, v42, v46, s[100:101]
	v_cndmask_b32_e64 v223, v43, v47, s[100:101]
	v_cndmask_b32_e64 v224, v44, v48, s[100:101]
	v_cndmask_b32_e64 v225, v45, v49, s[100:101]
	v_mov_b32_dpp v238, v222 quad_perm:[1,0,3,2] row_mask:0xf bank_mask:0xf
	v_mov_b32_dpp v239, v223 quad_perm:[1,0,3,2] row_mask:0xf bank_mask:0xf
	v_mov_b32_dpp v240, v224 quad_perm:[1,0,3,2] row_mask:0xf bank_mask:0xf
	v_mov_b32_dpp v241, v225 quad_perm:[1,0,3,2] row_mask:0xf bank_mask:0xf
	v_cndmask_b32_e64 v214, v46, v238, s[100:101]
	v_cndmask_b32_e64 v218, v238, v42, s[100:101]
	v_cndmask_b32_e64 v215, v47, v239, s[100:101]
	v_cndmask_b32_e64 v219, v239, v43, s[100:101]
	v_cndmask_b32_e64 v216, v48, v240, s[100:101]
	v_cndmask_b32_e64 v220, v240, v44, s[100:101]
	v_cndmask_b32_e64 v217, v49, v241, s[100:101]
	v_cndmask_b32_e64 v221, v241, v45, s[100:101]
	v_lshl_add_u64 v[226:227], v[98:99], 0, v[242:243]
	global_store_dwordx4 v[226:227], v[214:217], off offset:-4096
	global_store_dwordx4 v[226:227], v[218:221], off
	global_store_dwordx4 v[72:73], v[52:55], off
	global_load_dwordx4 v[52:55], v[70:71], off offset:512
	s_nop 0
	global_load_dwordx4 v[66:69], v[70:71], off offset:528
	v_mul_f32_e32 v47, v47, v47
	v_mul_f32_e32 v49, v49, v49
	v_mul_f32_e32 v43, v43, v43
	v_fmac_f32_e32 v47, v46, v46
	v_fmac_f32_e32 v49, v48, v48
	v_mul_f32_e32 v45, v45, v45
	v_fmac_f32_e32 v43, v42, v42
	v_add_f32_e32 v42, v47, v49
	v_fmac_f32_e32 v45, v44, v44
	v_add_f32_e32 v42, v42, v43
	v_add_f32_e32 v42, v45, v42
	s_waitcnt vmcnt(1)
	v_pk_fma_f32 v[40:41], v[40:41], v[80:81], v[54:55]
	v_pk_fma_f32 v[38:39], v[38:39], v[78:79], v[52:53]
	s_waitcnt vmcnt(0)
	v_pk_fma_f32 v[34:35], v[34:35], v[74:75], v[66:67]
	v_mul_f32_e32 v43, v39, v39
	v_mul_f32_e32 v44, v41, v41
	v_pk_fma_f32 v[36:37], v[36:37], v[76:77], v[68:69]
	v_mul_f32_e32 v45, v35, v35
	v_fmac_f32_e32 v43, v38, v38
	v_fmac_f32_e32 v44, v40, v40
	v_mul_f32_e32 v46, v37, v37
	v_fmac_f32_e32 v45, v34, v34
	v_add_f32_e32 v43, v43, v44
	v_fmac_f32_e32 v46, v36, v36
	v_add_f32_e32 v43, v43, v45
	v_add_f32_e32 v43, v46, v43
	v_add_f32_e32 v46, v42, v43
	ds_bpermute_b32 v47, v200, v46
	v_cndmask_b32_e64 v222, v34, v38, s[100:101]
	v_cndmask_b32_e64 v223, v35, v39, s[100:101]
	v_cndmask_b32_e64 v224, v36, v40, s[100:101]
	v_cndmask_b32_e64 v225, v37, v41, s[100:101]
	v_mov_b32_dpp v238, v222 quad_perm:[1,0,3,2] row_mask:0xf bank_mask:0xf
	v_mov_b32_dpp v239, v223 quad_perm:[1,0,3,2] row_mask:0xf bank_mask:0xf
	v_mov_b32_dpp v240, v224 quad_perm:[1,0,3,2] row_mask:0xf bank_mask:0xf
	v_mov_b32_dpp v241, v225 quad_perm:[1,0,3,2] row_mask:0xf bank_mask:0xf
	v_cndmask_b32_e64 v214, v38, v238, s[100:101]
	v_cndmask_b32_e64 v218, v238, v34, s[100:101]
	v_cndmask_b32_e64 v215, v39, v239, s[100:101]
	v_cndmask_b32_e64 v219, v239, v35, s[100:101]
	v_cndmask_b32_e64 v216, v40, v240, s[100:101]
	v_cndmask_b32_e64 v220, v240, v36, s[100:101]
	v_cndmask_b32_e64 v217, v41, v241, s[100:101]
	v_cndmask_b32_e64 v221, v241, v37, s[100:101]
	v_lshl_add_u64 v[226:227], v[98:99], 0, v[242:243]
	global_store_dwordx4 v[226:227], v[214:217], off offset:-3584
	global_store_dwordx4 v[226:227], v[218:221], off offset:512
	v_pk_mul_f32 v[44:45], v[58:59], v[34:35]
	v_pk_mul_f32 v[40:41], v[64:65], v[40:41]
	v_pk_mul_f32 v[38:39], v[62:63], v[38:39]
	s_waitcnt lgkmcnt(0)
	v_add_f32_e32 v34, v46, v47
	ds_bpermute_b32 v35, v195, v34
	v_pk_mul_f32 v[42:43], v[60:61], v[36:37]
	v_cvt_pk_bf16_f32 v36, v38, v39
	v_cvt_pk_bf16_f32 v37, v40, v41
	v_cvt_pk_bf16_f32 v38, v44, v45
	v_cvt_pk_bf16_f32 v39, v42, v43
	global_store_dwordx4 v[72:73], v[36:39], off offset:256
	s_and_saveexec_b64 s[34:35], s[38:39]
	s_cbranch_execz .LBB0_954
	v_lshlrev_b64 v[36:37], 6, v[50:51]
	v_lshl_add_u64 v[36:37], s[62:63], 0, v[36:37]
	v_lshl_add_u64 v[36:37], s[24:25], 2, v[36:37]
	s_lshl_b32 s0, s47, 2
	v_lshl_add_u64 v[36:37], v[36:37], 0, s[0:1]
	s_waitcnt lgkmcnt(0)
	v_add_f32_e32 v34, v34, v35
	global_store_dword v[36:37], v34, off

; __device__ __forceinline__ unsigned pk2(float lo, float hi) { return pg8::cvt_pk_bf16(lo, hi); }
;     __device__ __forceinline__ void operator()(const f32x4 (&acc)[2][2][4][2], const pg8::Unit& u, int wr, int wc, int fr, int fq) const {
;     ...
;                 const int R = rowbase + u.pm * 256 + ai * 128 + wr * 64 + m * 16 + fr;
;                 const float* src = islat ? rin_l + (size_t)R * DM : rin_c + (size_t)(R - TL) * DM;
;                 float* dst = islat ? rout_l + (size_t)R * DM : rout_c + (size_t)(R - TL) * DM;
;                 float ss = 0.f;
; #pragma unroll
;                 for (int bj = 0; bj < 2; ++bj) { const int c = u.pn * 256 + bj * 128 + wc * 32 + 8 * fq;
;                     const f32x4 xa = *(const f32x4*)(src + c) + gv[bj][0] * acc[ai][bj][m][0];
;                     const f32x4 xb = *(const f32x4*)(src + c + 4) + gv[bj][1] * acc[ai][bj][m][1];
;                     *(f32x4*)(dst + c) = xa; *(f32x4*)(dst + c + 4) = xb;
;                     ss += (xa[0] * xa[0] + xa[1] * xa[1]) + (xa[2] * xa[2] + xa[3] * xa[3]) + (xb[0] * xb[0] + xb[1] * xb[1]) + (xb[2] * xb[2] + xb[3] * xb[3]);
;                     const f32x4 ya = xa * sv[bj][0], yb = xb * sv[bj][1];
;                     u32x4 w; w.x = pk2(ya[0], ya[1]); w.y = pk2(ya[2], ya[3]); w.z = pk2(yb[0], yb[1]); w.w = pk2(yb[2], yb[3]);
;                     *(u32x4*)(Hn + (size_t)R * DM + c) = w; }
;                 ss += __shfl_xor(ss, 16); ss += __shfl_xor(ss, 32);
;                 if (fq == 0) stat[(size_t)R * 16 + u.pn * 4 + wc] = ss;
.LBB0_958:
	v_cndmask_b32_e64 v38, v38, v34, s[42:43]
	v_ashrrev_i32_e32 v39, 31, v38
	v_lshlrev_b64 v[38:39], 12, v[38:39]
	v_lshl_add_u64 v[38:39], s[68:69], 0, v[38:39]
	v_lshl_add_u64 v[46:47], v[38:39], 0, v[188:189]
	global_load_dwordx4 v[38:41], v[46:47], off
	global_load_dwordx4 v[42:45], v[46:47], off offset:16
	v_lshlrev_b64 v[48:49], 11, v[34:35]
	v_lshl_add_u64 v[50:51], v[36:37], 0, v[188:189]
	v_lshl_add_u64 v[36:37], s[60:61], 0, v[48:49]
	v_lshl_add_u64 v[48:49], v[186:187], 1, v[36:37]
	s_waitcnt vmcnt(1)
	v_pk_fma_f32 v[32:33], v[32:33], v[96:97], v[40:41]
	v_pk_fma_f32 v[30:31], v[30:31], v[94:95], v[38:39]
	s_waitcnt vmcnt(0)
	v_pk_fma_f32 v[28:29], v[28:29], v[88:89], v[44:45]
	v_pk_fma_f32 v[26:27], v[26:27], v[86:87], v[42:43]
	v_pk_mul_f32 v[38:39], v[92:93], v[32:33]
	v_pk_mul_f32 v[36:37], v[90:91], v[30:31]
	v_pk_mul_f32 v[40:41], v[84:85], v[28:29]
	v_pk_mul_f32 v[42:43], v[82:83], v[26:27]
	v_cvt_pk_bf16_f32 v36, v36, v37
	v_cvt_pk_bf16_f32 v37, v38, v39
	v_cvt_pk_bf16_f32 v38, v42, v43
	v_cvt_pk_bf16_f32 v39, v40, v41
	v_cndmask_b32_e64 v222, v26, v30, s[100:101]
	v_cndmask_b32_e64 v223, v27, v31, s[100:101]
	v_cndmask_b32_e64 v224, v28, v32, s[100:101]
	v_cndmask_b32_e64 v225, v29, v33, s[100:101]
	v_mov_b32_dpp v238, v222 quad_perm:[1,0,3,2] row_mask:0xf bank_mask:0xf
	v_mov_b32_dpp v239, v223 quad_perm:[1,0,3,2] row_mask:0xf bank_mask:0xf
	v_mov_b32_dpp v240, v224 quad_perm:[1,0,3,2] row_mask:0xf bank_mask:0xf
	v_mov_b32_dpp v241, v225 quad_perm:[1,0,3,2] row_mask:0xf bank_mask:0xf
	v_cndmask_b32_e64 v214, v30, v238, s[100:101]
	v_cndmask_b32_e64 v218, v238, v26, s[100:101]
	v_cndmask_b32_e64 v215, v31, v239, s[100:101]
	v_cndmask_b32_e64 v219, v239, v27, s[100:101]
	v_cndmask_b32_e64 v216, v32, v240, s[100:101]
	v_cndmask_b32_e64 v220, v240, v28, s[100:101]
	v_cndmask_b32_e64 v217, v33, v241, s[100:101]
	v_cndmask_b32_e64 v221, v241, v29, s[100:101]
	v_lshl_add_u64 v[226:227], v[50:51], 0, v[242:243]
	global_store_dwordx4 v[226:227], v[214:217], off offset:-4096
	global_store_dwordx4 v[226:227], v[218:221], off
	global_store_dwordx4 v[48:49], v[36:39], off
	global_load_dwordx4 v[36:39], v[46:47], off offset:512
	s_nop 0
	global_load_dwordx4 v[40:43], v[46:47], off offset:528
	v_mul_f32_e32 v31, v31, v31
	v_mul_f32_e32 v33, v33, v33
	v_mul_f32_e32 v27, v27, v27
	v_fmac_f32_e32 v31, v30, v30
	v_fmac_f32_e32 v33, v32, v32
	v_mul_f32_e32 v29, v29, v29
	v_fmac_f32_e32 v27, v26, v26
	v_add_f32_e32 v26, v31, v33
	v_fmac_f32_e32 v29, v28, v28
	v_add_f32_e32 v26, v26, v27
	v_add_f32_e32 v26, v29, v26
	s_waitcnt vmcnt(1)
	v_pk_fma_f32 v[24:25], v[24:25], v[80:81], v[38:39]
	v_pk_fma_f32 v[22:23], v[22:23], v[78:79], v[36:37]
	s_waitcnt vmcnt(0)
	v_pk_fma_f32 v[18:19], v[18:19], v[74:75], v[40:41]
	v_mul_f32_e32 v27, v23, v23
	v_mul_f32_e32 v28, v25, v25
	v_pk_fma_f32 v[20:21], v[20:21], v[76:77], v[42:43]
	v_mul_f32_e32 v29, v19, v19
	v_fmac_f32_e32 v27, v22, v22
	v_fmac_f32_e32 v28, v24, v24
	v_mul_f32_e32 v30, v21, v21
	v_fmac_f32_e32 v29, v18, v18
	v_add_f32_e32 v27, v27, v28
	v_fmac_f32_e32 v30, v20, v20
	v_add_f32_e32 v27, v27, v29
	v_add_f32_e32 v27, v30, v27
	v_add_f32_e32 v30, v26, v27
	ds_bpermute_b32 v31, v200, v30
	v_cndmask_b32_e64 v222, v18, v22, s[100:101]
	v_cndmask_b32_e64 v223, v19, v23, s[100:101]
	v_cndmask_b32_e64 v224, v20, v24, s[100:101]
	v_cndmask_b32_e64 v225, v21, v25, s[100:101]
	v_mov_b32_dpp v238, v222 quad_perm:[1,0,3,2] row_mask:0xf bank_mask:0xf
	v_mov_b32_dpp v239, v223 quad_perm:[1,0,3,2] row_mask:0xf bank_mask:0xf
	v_mov_b32_dpp v240, v224 quad_perm:[1,0,3,2] row_mask:0xf bank_mask:0xf
	v_mov_b32_dpp v241, v225 quad_perm:[1,0,3,2] row_mask:0xf bank_mask:0xf
	v_cndmask_b32_e64 v214, v22, v238, s[100:101]
	v_cndmask_b32_e64 v218, v238, v18, s[100:101]
	v_cndmask_b32_e64 v215, v23, v239, s[100:101]
	v_cndmask_b32_e64 v219, v239, v19, s[100:101]
	v_cndmask_b32_e64 v216, v24, v240, s[100:101]
	v_cndmask_b32_e64 v220, v240, v20, s[100:101]
	v_cndmask_b32_e64 v217, v25, v241, s[100:101]
	v_cndmask_b32_e64 v221, v241, v21, s[100:101]
	v_lshl_add_u64 v[226:227], v[50:51], 0, v[242:243]
	global_store_dwordx4 v[226:227], v[214:217], off offset:-3584
	global_store_dwordx4 v[226:227], v[218:221], off offset:512
	v_pk_mul_f32 v[28:29], v[58:59], v[18:19]
	v_pk_mul_f32 v[24:25], v[64:65], v[24:25]
	v_pk_mul_f32 v[22:23], v[62:63], v[22:23]
	s_waitcnt lgkmcnt(0)
	v_add_f32_e32 v18, v30, v31
	ds_bpermute_b32 v19, v195, v18
	v_pk_mul_f32 v[26:27], v[60:61], v[20:21]
	v_cvt_pk_bf16_f32 v20, v22, v23
	v_cvt_pk_bf16_f32 v21, v24, v25
	v_cvt_pk_bf16_f32 v22, v28, v29
	v_cvt_pk_bf16_f32 v23, v26, v27
	global_store_dwordx4 v[48:49], v[20:23], off offset:256
	s_and_saveexec_b64 s[34:35], s[38:39]
	s_cbranch_execz .LBB0_960
	v_lshlrev_b64 v[20:21], 6, v[34:35]
	v_lshl_add_u64 v[20:21], s[62:63], 0, v[20:21]
	v_lshl_add_u64 v[20:21], s[24:25], 2, v[20:21]
	s_lshl_b32 s0, s47, 2
	v_lshl_add_u64 v[20:21], v[20:21], 0, s[0:1]
	s_waitcnt lgkmcnt(0)
	v_add_f32_e32 v18, v18, v19
	global_store_dword v[20:21], v18, off

; __device__ __forceinline__ unsigned pk2(float lo, float hi) { return pg8::cvt_pk_bf16(lo, hi); }
;     __device__ __forceinline__ void operator()(const f32x4 (&acc)[2][2][4][2], const pg8::Unit& u, int wr, int wc, int fr, int fq) const {
;     ...
;                 const int R = rowbase + u.pm * 256 + ai * 128 + wr * 64 + m * 16 + fr;
;                 const float* src = islat ? rin_l + (size_t)R * DM : rin_c + (size_t)(R - TL) * DM;
;                 float* dst = islat ? rout_l + (size_t)R * DM : rout_c + (size_t)(R - TL) * DM;
;                 float ss = 0.f;
; #pragma unroll
;                 for (int bj = 0; bj < 2; ++bj) { const int c = u.pn * 256 + bj * 128 + wc * 32 + 8 * fq;
;                     const f32x4 xa = *(const f32x4*)(src + c) + gv[bj][0] * acc[ai][bj][m][0];
;                     const f32x4 xb = *(const f32x4*)(src + c + 4) + gv[bj][1] * acc[ai][bj][m][1];
;                     *(f32x4*)(dst + c) = xa; *(f32x4*)(dst + c + 4) = xb;
;                     ss += (xa[0] * xa[0] + xa[1] * xa[1]) + (xa[2] * xa[2] + xa[3] * xa[3]) + (xb[0] * xb[0] + xb[1] * xb[1]) + (xb[2] * xb[2] + xb[3] * xb[3]);
;                     const f32x4 ya = xa * sv[bj][0], yb = xb * sv[bj][1];
;                     u32x4 w; w.x = pk2(ya[0], ya[1]); w.y = pk2(ya[2], ya[3]); w.z = pk2(yb[0], yb[1]); w.w = pk2(yb[2], yb[3]);
;                     *(u32x4*)(Hn + (size_t)R * DM + c) = w; }
;                 ss += __shfl_xor(ss, 16); ss += __shfl_xor(ss, 32);
;                 if (fq == 0) stat[(size_t)R * 16 + u.pn * 4 + wc] = ss;
.LBB0_964:
	v_cndmask_b32_e64 v22, v22, v18, s[42:43]
	v_ashrrev_i32_e32 v23, 31, v22
	v_lshlrev_b64 v[22:23], 12, v[22:23]
	v_lshl_add_u64 v[22:23], s[68:69], 0, v[22:23]
	v_lshl_add_u64 v[30:31], v[22:23], 0, v[188:189]
	global_load_dwordx4 v[22:25], v[30:31], off
	global_load_dwordx4 v[26:29], v[30:31], off offset:16
	v_lshlrev_b64 v[32:33], 11, v[18:19]
	v_lshl_add_u64 v[34:35], v[20:21], 0, v[188:189]
	v_lshl_add_u64 v[20:21], s[60:61], 0, v[32:33]
	v_lshl_add_u64 v[32:33], v[186:187], 1, v[20:21]
	s_waitcnt vmcnt(1)
	v_pk_fma_f32 v[16:17], v[16:17], v[96:97], v[24:25]
	v_pk_fma_f32 v[14:15], v[14:15], v[94:95], v[22:23]
	s_waitcnt vmcnt(0)
	v_pk_fma_f32 v[12:13], v[12:13], v[88:89], v[28:29]
	v_pk_fma_f32 v[10:11], v[10:11], v[86:87], v[26:27]
	v_pk_mul_f32 v[22:23], v[92:93], v[16:17]
	v_pk_mul_f32 v[20:21], v[90:91], v[14:15]
	v_pk_mul_f32 v[24:25], v[84:85], v[12:13]
	v_pk_mul_f32 v[26:27], v[82:83], v[10:11]
	v_cvt_pk_bf16_f32 v20, v20, v21
	v_cvt_pk_bf16_f32 v21, v22, v23
	v_cvt_pk_bf16_f32 v22, v26, v27
	v_cvt_pk_bf16_f32 v23, v24, v25
	v_cndmask_b32_e64 v222, v10, v14, s[100:101]
	v_cndmask_b32_e64 v223, v11, v15, s[100:101]
	v_cndmask_b32_e64 v224, v12, v16, s[100:101]
	v_cndmask_b32_e64 v225, v13, v17, s[100:101]
	v_mov_b32_dpp v238, v222 quad_perm:[1,0,3,2] row_mask:0xf bank_mask:0xf
	v_mov_b32_dpp v239, v223 quad_perm:[1,0,3,2] row_mask:0xf bank_mask:0xf
	v_mov_b32_dpp v240, v224 quad_perm:[1,0,3,2] row_mask:0xf bank_mask:0xf
	v_mov_b32_dpp v241, v225 quad_perm:[1,0,3,2] row_mask:0xf bank_mask:0xf
	v_cndmask_b32_e64 v214, v14, v238, s[100:101]
	v_cndmask_b32_e64 v218, v238, v10, s[100:101]
	v_cndmask_b32_e64 v215, v15, v239, s[100:101]
	v_cndmask_b32_e64 v219, v239, v11, s[100:101]
	v_cndmask_b32_e64 v216, v16, v240, s[100:101]
	v_cndmask_b32_e64 v220, v240, v12, s[100:101]
	v_cndmask_b32_e64 v217, v17, v241, s[100:101]
	v_cndmask_b32_e64 v221, v241, v13, s[100:101]
	v_lshl_add_u64 v[226:227], v[34:35], 0, v[242:243]
	global_store_dwordx4 v[226:227], v[214:217], off offset:-4096
	global_store_dwordx4 v[226:227], v[218:221], off
	global_store_dwordx4 v[32:33], v[20:23], off
	global_load_dwordx4 v[20:23], v[30:31], off offset:512
	s_nop 0
	global_load_dwordx4 v[24:27], v[30:31], off offset:528
	v_mul_f32_e32 v15, v15, v15
	v_mul_f32_e32 v17, v17, v17
	v_mul_f32_e32 v11, v11, v11
	v_fmac_f32_e32 v15, v14, v14
	v_fmac_f32_e32 v17, v16, v16
	v_mul_f32_e32 v13, v13, v13
	v_fmac_f32_e32 v11, v10, v10
	v_add_f32_e32 v10, v15, v17
	v_fmac_f32_e32 v13, v12, v12
	v_add_f32_e32 v10, v10, v11
	v_add_f32_e32 v10, v13, v10
	s_waitcnt vmcnt(1)
	v_pk_fma_f32 v[8:9], v[8:9], v[80:81], v[22:23]
	v_pk_fma_f32 v[6:7], v[6:7], v[78:79], v[20:21]
	s_waitcnt vmcnt(0)
	v_pk_fma_f32 v[2:3], v[2:3], v[74:75], v[24:25]
	v_mul_f32_e32 v11, v7, v7
	v_mul_f32_e32 v12, v9, v9
	v_pk_fma_f32 v[4:5], v[4:5], v[76:77], v[26:27]
	v_mul_f32_e32 v13, v3, v3
	v_fmac_f32_e32 v11, v6, v6
	v_fmac_f32_e32 v12, v8, v8
	v_mul_f32_e32 v14, v5, v5
	v_fmac_f32_e32 v13, v2, v2
	v_add_f32_e32 v11, v11, v12
	v_fmac_f32_e32 v14, v4, v4
	v_add_f32_e32 v11, v11, v13
	v_add_f32_e32 v11, v14, v11
	v_add_f32_e32 v14, v10, v11
	ds_bpermute_b32 v15, v200, v14
	v_cndmask_b32_e64 v222, v2, v6, s[100:101]
	v_cndmask_b32_e64 v223, v3, v7, s[100:101]
	v_cndmask_b32_e64 v224, v4, v8, s[100:101]
	v_cndmask_b32_e64 v225, v5, v9, s[100:101]
	v_mov_b32_dpp v238, v222 quad_perm:[1,0,3,2] row_mask:0xf bank_mask:0xf
	v_mov_b32_dpp v239, v223 quad_perm:[1,0,3,2] row_mask:0xf bank_mask:0xf
	v_mov_b32_dpp v240, v224 quad_perm:[1,0,3,2] row_mask:0xf bank_mask:0xf
	v_mov_b32_dpp v241, v225 quad_perm:[1,0,3,2] row_mask:0xf bank_mask:0xf
	v_cndmask_b32_e64 v214, v6, v238, s[100:101]
	v_cndmask_b32_e64 v218, v238, v2, s[100:101]
	v_cndmask_b32_e64 v215, v7, v239, s[100:101]
	v_cndmask_b32_e64 v219, v239, v3, s[100:101]
	v_cndmask_b32_e64 v216, v8, v240, s[100:101]
	v_cndmask_b32_e64 v220, v240, v4, s[100:101]
	v_cndmask_b32_e64 v217, v9, v241, s[100:101]
	v_cndmask_b32_e64 v221, v241, v5, s[100:101]
	v_lshl_add_u64 v[226:227], v[34:35], 0, v[242:243]
	global_store_dwordx4 v[226:227], v[214:217], off offset:-3584
	global_store_dwordx4 v[226:227], v[218:221], off offset:512
	v_pk_mul_f32 v[12:13], v[58:59], v[2:3]
	v_pk_mul_f32 v[8:9], v[64:65], v[8:9]
	v_pk_mul_f32 v[6:7], v[62:63], v[6:7]
	s_waitcnt lgkmcnt(0)
	v_add_f32_e32 v2, v14, v15
	ds_bpermute_b32 v3, v195, v2
	v_pk_mul_f32 v[10:11], v[60:61], v[4:5]
	v_cvt_pk_bf16_f32 v4, v6, v7
	v_cvt_pk_bf16_f32 v5, v8, v9
	v_cvt_pk_bf16_f32 v6, v12, v13
	v_cvt_pk_bf16_f32 v7, v10, v11
	global_store_dwordx4 v[32:33], v[4:7], off offset:256
	s_and_saveexec_b64 s[34:35], s[38:39]
	s_cbranch_execz .LBB0_966
	v_lshlrev_b64 v[4:5], 6, v[18:19]
	v_lshl_add_u64 v[4:5], s[62:63], 0, v[4:5]
	v_lshl_add_u64 v[4:5], s[24:25], 2, v[4:5]
	s_lshl_b32 s0, s47, 2
	v_lshl_add_u64 v[4:5], v[4:5], 0, s[0:1]
	s_waitcnt lgkmcnt(0)
	v_add_f32_e32 v2, v2, v3
	global_store_dword v[4:5], v2, off

; __device__ __forceinline__ unsigned pk2(float lo, float hi) { return pg8::cvt_pk_bf16(lo, hi); }
;     __device__ __forceinline__ void operator()(const f32x4 (&acc)[2][2][4][2], const pg8::Unit& u, int wr, int wc, int fr, int fq) const {
;         const int row0 = u.pm * 256 + wr * 64 + fr, col0 = u.pn * 256 + wc * 32 + 8 * fq;
;         const int Rt = rowbase + u.pm * 256;
;         const float* bp = bias + (size_t)(Rt < TL ? (Rt >> 13) : 8) * FF2 + col0;
;         f32x4 bv[2][2];
; #pragma unroll
;         for (int bj = 0; bj < 2; ++bj) { bv[bj][0] = *(const f32x4*)(bp + bj * 128); bv[bj][1] = *(const f32x4*)(bp + bj * 128 + 4); }
; #pragma unroll
;         for (int ai = 0; ai < 2; ++ai)
; #pragma unroll
;             for (int m = 0; m < 4; ++m) { const int r = row0 + ai * 128 + m * 16, Rg = rowbase + r;
;                 const f32x4 q = *(const f32x4*)(stat + (size_t)Rg * 16 + fq * 4);
;                 float ssq = (q[0] + q[1]) + (q[2] + q[3]); ssq += __shfl_xor(ssq, 16); ssq += __shfl_xor(ssq, 32);
;                 const float rstd = rsqrtf(ssq * (1.f / DM) + 1e-6f);
;                 bf16_t* rowp = O + (size_t)r * ldc + col0;
; #pragma unroll
;                 for (int bj = 0; bj < 2; ++bj) { const f32x4 v0 = acc[ai][bj][m][0] * rstd + bv[bj][0], v1 = acc[ai][bj][m][1] * rstd + bv[bj][1];
;                     u32x4 w; w.x = pk2(v0[0], v0[1]); w.y = pk2(v0[2], v0[3]); w.z = pk2(v1[0], v1[1]); w.w = pk2(v1[2], v1[3]);
;                     *(u32x4*)(rowp + bj * 128) = w; } }
.LBB0_1036:
	s_lshl_b32 s10, s40, 8
	v_add_u32_e32 v180, s10, v176
	v_add_u32_e32 v130, s52, v180
	v_ashrrev_i32_e32 v131, 31, v130
	v_lshlrev_b64 v[130:131], 6, v[130:131]
	v_lshl_add_u64 v[130:131], v[152:153], 0, v[130:131]
	global_load_dwordx4 v[182:185], v[130:131], off
	global_load_dwordx4 v[196:199], v[130:131], off offset:1024
	global_load_dwordx4 v[200:203], v[130:131], off offset:2048
	global_load_dwordx4 v[204:207], v[130:131], off offset:3072
	v_add_co_u32_e32 v194, vcc, 0x2000, v130
	s_nop 1
	v_addc_co_u32_e32 v195, vcc, 0, v131, vcc
	global_load_dwordx4 v[208:211], v[194:195], off
	global_load_dwordx4 v[212:215], v[194:195], off offset:1024
	global_load_dwordx4 v[216:219], v[194:195], off offset:2048
	global_load_dwordx4 v[220:223], v[194:195], off offset:3072
	s_add_i32 s10, s10, s52
	s_min_i32 s10, s10, 0x10000
	s_ashr_i32 s10, s10, 13
	s_mulk_i32 s10, 0x1600
	s_ashr_i32 s11, s10, 31
	s_lshl_b64 s[10:11], s[10:11], 2
	v_lshl_or_b32 v160, s41, 8, v178
	s_add_u32 s10, s57, s10
	v_ashrrev_i32_e32 v161, 31, v160
	s_addc_u32 s11, s62, s11
	v_lshl_add_u64 v[130:131], v[160:161], 2, s[10:11]
	global_load_dwordx4 v[142:145], v[130:131], off
	global_load_dwordx4 v[138:141], v[130:131], off offset:16
	global_load_dwordx4 v[134:137], v[130:131], off offset:512
	s_nop 0
	global_load_dwordx4 v[130:133], v[130:131], off offset:528
	v_and_b32_e32 v186, 64, v228
	v_xor_b32_e32 v181, 16, v228
	v_add_u32_e32 v189, 64, v186
	v_cmp_lt_i32_e32 vcc, v181, v189
	v_xor_b32_e32 v188, 32, v228
	v_or_b32_e32 v192, 16, v180
	v_cndmask_b32_e32 v181, v228, v181, vcc
	v_lshlrev_b32_e32 v181, 2, v181
	v_cmp_lt_i32_e32 vcc, v188, v189
	v_mov_b64_e32 v[158:159], s[22:23]
	v_lshlrev_b64 v[160:161], 1, v[160:161]
	s_mov_b64 s[34:35], -1
	s_waitcnt vmcnt(0)
	v_mov_b32_e32 v186, v183
	v_mov_b32_e32 v187, v184
	v_mov_b32_e32 v183, v185
	v_pk_add_f32 v[182:183], v[186:187], v[182:183]
	v_mad_i64_i32 v[184:185], s[10:11], v180, s92, v[158:159]
	v_add_f32_e32 v183, v182, v183
	ds_bpermute_b32 v186, v181, v183
	v_cndmask_b32_e32 v182, v228, v188, vcc
	v_lshlrev_b32_e32 v182, 2, v182
	v_lshl_add_u64 v[184:185], v[184:185], 0, v[160:161]
	s_waitcnt lgkmcnt(0)
	v_add_f32_e32 v183, v183, v186
	ds_bpermute_b32 v187, v182, v183
	v_add_u32_e32 v186, s52, v192
	s_waitcnt lgkmcnt(0)
	v_add_f32_e32 v183, v183, v187
	v_fmamk_f32 v183, v183, 0x3a800000, v162
	v_mul_f32_e32 v187, 0x4b800000, v183
	v_cmp_gt_f32_e32 vcc, s82, v183
	s_nop 1
	v_cndmask_b32_e32 v183, v183, v187, vcc
	v_rsq_f32_e32 v183, v183
	v_ashrrev_i32_e32 v187, 31, v186
	v_lshlrev_b64 v[186:187], 6, v[186:187]
	v_lshl_add_u64 v[186:187], v[152:153], 0, v[186:187]
	v_mul_f32_e32 v188, 0x45800000, v183
	v_cndmask_b32_e32 v188, v183, v188, vcc
	v_pk_fma_f32 v[128:129], v[128:129], v[188:189], v[144:145] op_sel_hi:[1,0,1]
	v_pk_fma_f32 v[126:127], v[126:127], v[188:189], v[142:143] op_sel_hi:[1,0,1]
	v_pk_fma_f32 v[124:125], v[124:125], v[188:189], v[140:141] op_sel_hi:[1,0,1]
	v_pk_fma_f32 v[122:123], v[122:123], v[188:189], v[138:139] op_sel_hi:[1,0,1]
	v_pk_fma_f32 v[120:121], v[120:121], v[188:189], v[136:137] op_sel_hi:[1,0,1]
	v_pk_fma_f32 v[118:119], v[118:119], v[188:189], v[134:135] op_sel_hi:[1,0,1]
	v_pk_fma_f32 v[190:191], v[116:117], v[188:189], v[132:133] op_sel_hi:[1,0,1]
	v_pk_fma_f32 v[188:189], v[114:115], v[188:189], v[130:131] op_sel_hi:[1,0,1]
	v_cvt_pk_bf16_f32 v114, v126, v127
	v_cvt_pk_bf16_f32 v115, v128, v129
	v_cvt_pk_bf16_f32 v116, v122, v123
	v_cvt_pk_bf16_f32 v117, v124, v125
	v_cvt_pk_bf16_f32 v118, v118, v119
	v_cvt_pk_bf16_f32 v119, v120, v121
	v_cvt_pk_bf16_f32 v120, v188, v189
	v_cvt_pk_bf16_f32 v121, v190, v191
	global_store_dwordx4 v[184:185], v[114:117], off
	global_store_dwordx4 v[184:185], v[118:121], off offset:256
	v_or_b32_e32 v122, 32, v180
	s_nop 1
	v_add_f32_e32 v114, v196, v197
	v_add_f32_e32 v115, v198, v199
	v_add_u32_e32 v116, s52, v122
	v_add_f32_e32 v114, v114, v115
	ds_bpermute_b32 v115, v181, v114
	s_waitcnt lgkmcnt(0)
	v_add_f32_e32 v117, v114, v115
	ds_bpermute_b32 v118, v182, v117
	v_mad_i64_i32 v[114:115], s[10:11], v192, s92, v[158:159]
	v_lshl_add_u64 v[114:115], v[114:115], 0, v[160:161]
	s_waitcnt lgkmcnt(0)
	v_add_f32_e32 v117, v117, v118
	v_fmamk_f32 v117, v117, 0x3a800000, v162
	v_mul_f32_e32 v118, 0x4b800000, v117
	v_cmp_gt_f32_e32 vcc, s82, v117
	s_nop 1
	v_cndmask_b32_e32 v117, v117, v118, vcc
	v_rsq_f32_e32 v118, v117
	v_ashrrev_i32_e32 v117, 31, v116
	v_lshlrev_b64 v[116:117], 6, v[116:117]
	v_lshl_add_u64 v[116:117], v[152:153], 0, v[116:117]
	v_mul_f32_e32 v119, 0x45800000, v118
	v_cndmask_b32_e32 v118, v118, v119, vcc
	v_pk_fma_f32 v[112:113], v[112:113], v[118:119], v[144:145] op_sel_hi:[1,0,1]
	v_pk_fma_f32 v[110:111], v[110:111], v[118:119], v[142:143] op_sel_hi:[1,0,1]
	v_pk_fma_f32 v[108:109], v[108:109], v[118:119], v[140:141] op_sel_hi:[1,0,1]
	v_pk_fma_f32 v[106:107], v[106:107], v[118:119], v[138:139] op_sel_hi:[1,0,1]
	v_pk_fma_f32 v[104:105], v[104:105], v[118:119], v[136:137] op_sel_hi:[1,0,1]
	v_pk_fma_f32 v[102:103], v[102:103], v[118:119], v[134:135] op_sel_hi:[1,0,1]
	v_pk_fma_f32 v[120:121], v[100:101], v[118:119], v[132:133] op_sel_hi:[1,0,1]
	v_pk_fma_f32 v[118:119], v[98:99], v[118:119], v[130:131] op_sel_hi:[1,0,1]
	v_cvt_pk_bf16_f32 v98, v110, v111
	v_cvt_pk_bf16_f32 v99, v112, v113
	v_cvt_pk_bf16_f32 v100, v106, v107
	v_cvt_pk_bf16_f32 v101, v108, v109
	v_cvt_pk_bf16_f32 v102, v102, v103
	v_cvt_pk_bf16_f32 v103, v104, v105
	v_cvt_pk_bf16_f32 v104, v118, v119
	v_cvt_pk_bf16_f32 v105, v120, v121
	global_store_dwordx4 v[114:115], v[98:101], off
	global_store_dwordx4 v[114:115], v[102:105], off offset:256
	v_or_b32_e32 v106, 48, v180
	s_nop 1
	v_add_f32_e32 v98, v200, v201
	v_add_f32_e32 v99, v202, v203
	v_add_u32_e32 v100, s52, v106
	v_add_f32_e32 v98, v98, v99
	ds_bpermute_b32 v99, v181, v98
	s_waitcnt lgkmcnt(0)
; __device__ __forceinline__ unsigned pk2(float lo, float hi) { return pg8::cvt_pk_bf16(lo, hi); }
;     __device__ __forceinline__ void operator()(const f32x4 (&acc)[2][2][4][2], const pg8::Unit& u, int wr, int wc, int fr, int fq) const {
;     ...
;             for (int m = 0; m < 4; ++m) { const int r = row0 + ai * 128 + m * 16, Rg = rowbase + r;
;                 const f32x4 q = *(const f32x4*)(stat + (size_t)Rg * 16 + fq * 4);
;                 float ssq = (q[0] + q[1]) + (q[2] + q[3]); ssq += __shfl_xor(ssq, 16); ssq += __shfl_xor(ssq, 32);
;                 const float rstd = rsqrtf(ssq * (1.f / DM) + 1e-6f);
;                 bf16_t* rowp = O + (size_t)r * ldc + col0;
; #pragma unroll
;                 for (int bj = 0; bj < 2; ++bj) { const f32x4 v0 = acc[ai][bj][m][0] * rstd + bv[bj][0], v1 = acc[ai][bj][m][1] * rstd + bv[bj][1];
;                     u32x4 w; w.x = pk2(v0[0], v0[1]); w.y = pk2(v0[2], v0[3]); w.z = pk2(v1[0], v1[1]); w.w = pk2(v1[2], v1[3]);
;                     *(u32x4*)(rowp + bj * 128) = w; } }
	v_add_f32_e32 v101, v98, v99
	ds_bpermute_b32 v102, v182, v101
	v_mad_i64_i32 v[98:99], s[10:11], v122, s92, v[158:159]
	v_lshl_add_u64 v[98:99], v[98:99], 0, v[160:161]
	s_waitcnt lgkmcnt(0)
	v_add_f32_e32 v101, v101, v102
	v_fmamk_f32 v101, v101, 0x3a800000, v162
	v_mul_f32_e32 v102, 0x4b800000, v101
	v_cmp_gt_f32_e32 vcc, s82, v101
	s_nop 1
	v_cndmask_b32_e32 v101, v101, v102, vcc
	v_rsq_f32_e32 v102, v101
	v_ashrrev_i32_e32 v101, 31, v100
	v_lshlrev_b64 v[100:101], 6, v[100:101]
	v_lshl_add_u64 v[100:101], v[152:153], 0, v[100:101]
	v_mul_f32_e32 v103, 0x45800000, v102
	v_cndmask_b32_e32 v102, v102, v103, vcc
	v_pk_fma_f32 v[96:97], v[96:97], v[102:103], v[144:145] op_sel_hi:[1,0,1]
	v_pk_fma_f32 v[94:95], v[94:95], v[102:103], v[142:143] op_sel_hi:[1,0,1]
	v_pk_fma_f32 v[92:93], v[92:93], v[102:103], v[140:141] op_sel_hi:[1,0,1]
	v_pk_fma_f32 v[90:91], v[90:91], v[102:103], v[138:139] op_sel_hi:[1,0,1]
	v_pk_fma_f32 v[88:89], v[88:89], v[102:103], v[136:137] op_sel_hi:[1,0,1]
	v_pk_fma_f32 v[86:87], v[86:87], v[102:103], v[134:135] op_sel_hi:[1,0,1]
	v_pk_fma_f32 v[104:105], v[84:85], v[102:103], v[132:133] op_sel_hi:[1,0,1]
	v_pk_fma_f32 v[102:103], v[82:83], v[102:103], v[130:131] op_sel_hi:[1,0,1]
	v_cvt_pk_bf16_f32 v82, v94, v95
	v_cvt_pk_bf16_f32 v83, v96, v97
	v_cvt_pk_bf16_f32 v84, v90, v91
	v_cvt_pk_bf16_f32 v85, v92, v93
	v_cvt_pk_bf16_f32 v86, v86, v87
	v_cvt_pk_bf16_f32 v87, v88, v89
	v_cvt_pk_bf16_f32 v88, v102, v103
	v_cvt_pk_bf16_f32 v89, v104, v105
	global_store_dwordx4 v[98:99], v[82:85], off
	global_store_dwordx4 v[98:99], v[86:89], off offset:256
	v_add_u32_e32 v90, 0x80, v180
	s_nop 1
	v_add_f32_e32 v82, v204, v205
	v_add_f32_e32 v83, v206, v207
	v_add_u32_e32 v84, s52, v90
	v_add_f32_e32 v82, v82, v83
	ds_bpermute_b32 v83, v181, v82
	s_waitcnt lgkmcnt(0)
	v_add_f32_e32 v85, v82, v83
	ds_bpermute_b32 v86, v182, v85
	v_mad_i64_i32 v[82:83], s[10:11], v106, s92, v[158:159]
	v_lshl_add_u64 v[82:83], v[82:83], 0, v[160:161]
	s_waitcnt lgkmcnt(0)
	v_add_f32_e32 v85, v85, v86
	v_fmamk_f32 v85, v85, 0x3a800000, v162
	v_mul_f32_e32 v86, 0x4b800000, v85
	v_cmp_gt_f32_e32 vcc, s82, v85
	s_nop 1
	v_cndmask_b32_e32 v85, v85, v86, vcc
	v_rsq_f32_e32 v86, v85
	v_ashrrev_i32_e32 v85, 31, v84
	v_lshlrev_b64 v[84:85], 6, v[84:85]
	v_lshl_add_u64 v[84:85], v[152:153], 0, v[84:85]
	v_mul_f32_e32 v87, 0x45800000, v86
	v_cndmask_b32_e32 v86, v86, v87, vcc
	v_pk_fma_f32 v[80:81], v[80:81], v[86:87], v[144:145] op_sel_hi:[1,0,1]
	v_pk_fma_f32 v[78:79], v[78:79], v[86:87], v[142:143] op_sel_hi:[1,0,1]
	v_pk_fma_f32 v[76:77], v[76:77], v[86:87], v[140:141] op_sel_hi:[1,0,1]
	v_pk_fma_f32 v[74:75], v[74:75], v[86:87], v[138:139] op_sel_hi:[1,0,1]
	v_pk_fma_f32 v[72:73], v[72:73], v[86:87], v[136:137] op_sel_hi:[1,0,1]
	v_pk_fma_f32 v[70:71], v[70:71], v[86:87], v[134:135] op_sel_hi:[1,0,1]
	v_pk_fma_f32 v[88:89], v[68:69], v[86:87], v[132:133] op_sel_hi:[1,0,1]
	v_pk_fma_f32 v[86:87], v[66:67], v[86:87], v[130:131] op_sel_hi:[1,0,1]
	v_cvt_pk_bf16_f32 v66, v78, v79
	v_cvt_pk_bf16_f32 v67, v80, v81
	v_cvt_pk_bf16_f32 v68, v74, v75
	v_cvt_pk_bf16_f32 v69, v76, v77
	v_cvt_pk_bf16_f32 v70, v70, v71
	v_cvt_pk_bf16_f32 v71, v72, v73
	v_cvt_pk_bf16_f32 v72, v86, v87
	v_cvt_pk_bf16_f32 v73, v88, v89
	global_store_dwordx4 v[82:83], v[66:69], off
	global_store_dwordx4 v[82:83], v[70:73], off offset:256
	v_add_u32_e32 v74, 0x90, v180
	s_nop 1
	v_add_f32_e32 v66, v208, v209
	v_add_f32_e32 v67, v210, v211
	v_add_u32_e32 v68, s52, v74
	v_add_f32_e32 v66, v66, v67
	ds_bpermute_b32 v67, v181, v66
	s_waitcnt lgkmcnt(0)
	v_add_f32_e32 v69, v66, v67
	ds_bpermute_b32 v70, v182, v69
	v_mad_i64_i32 v[66:67], s[10:11], v90, s92, v[158:159]
	v_lshl_add_u64 v[66:67], v[66:67], 0, v[160:161]
	s_waitcnt lgkmcnt(0)
	v_add_f32_e32 v69, v69, v70
	v_fmamk_f32 v69, v69, 0x3a800000, v162
	v_mul_f32_e32 v70, 0x4b800000, v69
	v_cmp_gt_f32_e32 vcc, s82, v69
	s_nop 1
	v_cndmask_b32_e32 v69, v69, v70, vcc
	v_rsq_f32_e32 v70, v69
	v_ashrrev_i32_e32 v69, 31, v68
	v_lshlrev_b64 v[68:69], 6, v[68:69]
	v_lshl_add_u64 v[68:69], v[152:153], 0, v[68:69]
	v_mul_f32_e32 v71, 0x45800000, v70
	v_cndmask_b32_e32 v70, v70, v71, vcc
	v_pk_fma_f32 v[64:65], v[64:65], v[70:71], v[144:145] op_sel_hi:[1,0,1]
	v_pk_fma_f32 v[62:63], v[62:63], v[70:71], v[142:143] op_sel_hi:[1,0,1]
	v_pk_fma_f32 v[60:61], v[60:61], v[70:71], v[140:141] op_sel_hi:[1,0,1]
	v_pk_fma_f32 v[58:59], v[58:59], v[70:71], v[138:139] op_sel_hi:[1,0,1]
	v_pk_fma_f32 v[56:57], v[56:57], v[70:71], v[136:137] op_sel_hi:[1,0,1]
	v_pk_fma_f32 v[54:55], v[54:55], v[70:71], v[134:135] op_sel_hi:[1,0,1]
	v_pk_fma_f32 v[72:73], v[52:53], v[70:71], v[132:133] op_sel_hi:[1,0,1]
	v_pk_fma_f32 v[70:71], v[50:51], v[70:71], v[130:131] op_sel_hi:[1,0,1]
	v_cvt_pk_bf16_f32 v50, v62, v63
	v_cvt_pk_bf16_f32 v51, v64, v65
	v_cvt_pk_bf16_f32 v52, v58, v59
	v_cvt_pk_bf16_f32 v53, v60, v61
	v_cvt_pk_bf16_f32 v54, v54, v55
	v_cvt_pk_bf16_f32 v55, v56, v57
	v_cvt_pk_bf16_f32 v56, v70, v71
	v_cvt_pk_bf16_f32 v57, v72, v73
	global_store_dwordx4 v[66:67], v[50:53], off
	global_store_dwordx4 v[66:67], v[54:57], off offset:256
	v_add_u32_e32 v58, 0xa0, v180
	s_nop 1
	v_add_f32_e32 v50, v212, v213
	v_add_f32_e32 v51, v214, v215
	v_add_u32_e32 v52, s52, v58
	v_add_f32_e32 v50, v50, v51
	ds_bpermute_b32 v51, v181, v50
	s_waitcnt lgkmcnt(0)
; __device__ __forceinline__ unsigned pk2(float lo, float hi) { return pg8::cvt_pk_bf16(lo, hi); }
;     __device__ __forceinline__ void operator()(const f32x4 (&acc)[2][2][4][2], const pg8::Unit& u, int wr, int wc, int fr, int fq) const {
;     ...
;             for (int m = 0; m < 4; ++m) { const int r = row0 + ai * 128 + m * 16, Rg = rowbase + r;
;                 const f32x4 q = *(const f32x4*)(stat + (size_t)Rg * 16 + fq * 4);
;                 float ssq = (q[0] + q[1]) + (q[2] + q[3]); ssq += __shfl_xor(ssq, 16); ssq += __shfl_xor(ssq, 32);
;                 const float rstd = rsqrtf(ssq * (1.f / DM) + 1e-6f);
;                 bf16_t* rowp = O + (size_t)r * ldc + col0;
; #pragma unroll
;                 for (int bj = 0; bj < 2; ++bj) { const f32x4 v0 = acc[ai][bj][m][0] * rstd + bv[bj][0], v1 = acc[ai][bj][m][1] * rstd + bv[bj][1];
;                     u32x4 w; w.x = pk2(v0[0], v0[1]); w.y = pk2(v0[2], v0[3]); w.z = pk2(v1[0], v1[1]); w.w = pk2(v1[2], v1[3]);
;                     *(u32x4*)(rowp + bj * 128) = w; } }
	v_add_f32_e32 v53, v50, v51
	ds_bpermute_b32 v54, v182, v53
	v_mad_i64_i32 v[50:51], s[10:11], v74, s92, v[158:159]
	v_lshl_add_u64 v[50:51], v[50:51], 0, v[160:161]
	s_waitcnt lgkmcnt(0)
	v_add_f32_e32 v53, v53, v54
	v_fmamk_f32 v53, v53, 0x3a800000, v162
	v_mul_f32_e32 v54, 0x4b800000, v53
	v_cmp_gt_f32_e32 vcc, s82, v53
	s_nop 1
	v_cndmask_b32_e32 v53, v53, v54, vcc
	v_rsq_f32_e32 v54, v53
	v_ashrrev_i32_e32 v53, 31, v52
	v_lshlrev_b64 v[52:53], 6, v[52:53]
	v_lshl_add_u64 v[52:53], v[152:153], 0, v[52:53]
	v_mul_f32_e32 v55, 0x45800000, v54
	v_cndmask_b32_e32 v54, v54, v55, vcc
	v_pk_fma_f32 v[48:49], v[48:49], v[54:55], v[144:145] op_sel_hi:[1,0,1]
	v_pk_fma_f32 v[46:47], v[46:47], v[54:55], v[142:143] op_sel_hi:[1,0,1]
	v_pk_fma_f32 v[44:45], v[44:45], v[54:55], v[140:141] op_sel_hi:[1,0,1]
	v_pk_fma_f32 v[42:43], v[42:43], v[54:55], v[138:139] op_sel_hi:[1,0,1]
	v_pk_fma_f32 v[40:41], v[40:41], v[54:55], v[136:137] op_sel_hi:[1,0,1]
	v_pk_fma_f32 v[38:39], v[38:39], v[54:55], v[134:135] op_sel_hi:[1,0,1]
	v_pk_fma_f32 v[56:57], v[36:37], v[54:55], v[132:133] op_sel_hi:[1,0,1]
	v_pk_fma_f32 v[54:55], v[34:35], v[54:55], v[130:131] op_sel_hi:[1,0,1]
	v_cvt_pk_bf16_f32 v34, v46, v47
	v_cvt_pk_bf16_f32 v35, v48, v49
	v_cvt_pk_bf16_f32 v36, v42, v43
	v_cvt_pk_bf16_f32 v37, v44, v45
	v_cvt_pk_bf16_f32 v38, v38, v39
	v_cvt_pk_bf16_f32 v39, v40, v41
	v_cvt_pk_bf16_f32 v40, v54, v55
	v_cvt_pk_bf16_f32 v41, v56, v57
	global_store_dwordx4 v[50:51], v[34:37], off
	global_store_dwordx4 v[50:51], v[38:41], off offset:256
	v_add_u32_e32 v42, 0xb0, v180
	s_nop 1
	v_add_f32_e32 v34, v216, v217
	v_add_f32_e32 v35, v218, v219
	v_add_u32_e32 v36, s52, v42
	v_add_f32_e32 v34, v34, v35
	ds_bpermute_b32 v35, v181, v34
	s_waitcnt lgkmcnt(0)
	v_add_f32_e32 v37, v34, v35
	ds_bpermute_b32 v38, v182, v37
	v_mad_i64_i32 v[34:35], s[10:11], v58, s92, v[158:159]
	v_lshl_add_u64 v[34:35], v[34:35], 0, v[160:161]
	s_waitcnt lgkmcnt(0)
	v_add_f32_e32 v37, v37, v38
	v_fmamk_f32 v37, v37, 0x3a800000, v162
	v_mul_f32_e32 v38, 0x4b800000, v37
	v_cmp_gt_f32_e32 vcc, s82, v37
	s_nop 1
	v_cndmask_b32_e32 v37, v37, v38, vcc
	v_rsq_f32_e32 v38, v37
	v_ashrrev_i32_e32 v37, 31, v36
	v_lshlrev_b64 v[36:37], 6, v[36:37]
	v_lshl_add_u64 v[36:37], v[152:153], 0, v[36:37]
	v_mul_f32_e32 v39, 0x45800000, v38
	v_cndmask_b32_e32 v38, v38, v39, vcc
	v_pk_fma_f32 v[32:33], v[32:33], v[38:39], v[144:145] op_sel_hi:[1,0,1]
	v_pk_fma_f32 v[30:31], v[30:31], v[38:39], v[142:143] op_sel_hi:[1,0,1]
	v_pk_fma_f32 v[28:29], v[28:29], v[38:39], v[140:141] op_sel_hi:[1,0,1]
	v_pk_fma_f32 v[26:27], v[26:27], v[38:39], v[138:139] op_sel_hi:[1,0,1]
	v_pk_fma_f32 v[24:25], v[24:25], v[38:39], v[136:137] op_sel_hi:[1,0,1]
	v_pk_fma_f32 v[22:23], v[22:23], v[38:39], v[134:135] op_sel_hi:[1,0,1]
	v_pk_fma_f32 v[40:41], v[20:21], v[38:39], v[132:133] op_sel_hi:[1,0,1]
	v_pk_fma_f32 v[38:39], v[18:19], v[38:39], v[130:131] op_sel_hi:[1,0,1]
	v_cvt_pk_bf16_f32 v18, v30, v31
	v_cvt_pk_bf16_f32 v19, v32, v33
	v_cvt_pk_bf16_f32 v20, v26, v27
	v_cvt_pk_bf16_f32 v21, v28, v29
	v_cvt_pk_bf16_f32 v22, v22, v23
	v_cvt_pk_bf16_f32 v23, v24, v25
	v_cvt_pk_bf16_f32 v24, v38, v39
	v_cvt_pk_bf16_f32 v25, v40, v41
	global_store_dwordx4 v[34:35], v[18:21], off
	global_store_dwordx4 v[34:35], v[22:25], off offset:256
	s_andn2_b64 vcc, exec, s[38:39]
	s_nop 1
	v_add_f32_e32 v18, v220, v221
	v_add_f32_e32 v19, v222, v223
	s_nop 0
	v_add_f32_e32 v18, v18, v19
	ds_bpermute_b32 v19, v181, v18
	s_waitcnt lgkmcnt(0)
	v_add_f32_e32 v18, v18, v19
	ds_bpermute_b32 v19, v182, v18
	s_waitcnt lgkmcnt(0)
	v_add_f32_e32 v18, v18, v19
	v_fmamk_f32 v18, v18, 0x3a800000, v162
	v_mul_f32_e32 v19, 0x4b800000, v18
	v_cmp_gt_f32_e64 s[40:41], s82, v18
	s_nop 1
	v_cndmask_b32_e64 v18, v18, v19, s[40:41]
	v_rsq_f32_e32 v20, v18
	v_mad_i64_i32 v[18:19], s[10:11], v42, s92, v[158:159]
	v_lshl_add_u64 v[18:19], v[18:19], 0, v[160:161]
	v_mul_f32_e32 v21, 0x45800000, v20
	v_cndmask_b32_e64 v20, v20, v21, s[40:41]
	v_pk_fma_f32 v[16:17], v[16:17], v[20:21], v[144:145] op_sel_hi:[1,0,1]
	v_pk_fma_f32 v[14:15], v[14:15], v[20:21], v[142:143] op_sel_hi:[1,0,1]
	v_pk_fma_f32 v[12:13], v[12:13], v[20:21], v[140:141] op_sel_hi:[1,0,1]
	v_pk_fma_f32 v[10:11], v[10:11], v[20:21], v[138:139] op_sel_hi:[1,0,1]
	v_pk_fma_f32 v[8:9], v[8:9], v[20:21], v[136:137] op_sel_hi:[1,0,1]
	v_pk_fma_f32 v[6:7], v[6:7], v[20:21], v[134:135] op_sel_hi:[1,0,1]
	v_pk_fma_f32 v[22:23], v[4:5], v[20:21], v[132:133] op_sel_hi:[1,0,1]
	v_pk_fma_f32 v[20:21], v[2:3], v[20:21], v[130:131] op_sel_hi:[1,0,1]
	v_cvt_pk_bf16_f32 v2, v14, v15
	v_cvt_pk_bf16_f32 v3, v16, v17
	v_cvt_pk_bf16_f32 v4, v10, v11
	v_cvt_pk_bf16_f32 v5, v12, v13
	v_cvt_pk_bf16_f32 v6, v6, v7
	v_cvt_pk_bf16_f32 v7, v8, v9
	v_cvt_pk_bf16_f32 v8, v20, v21
	v_cvt_pk_bf16_f32 v9, v22, v23
	global_store_dwordx4 v[18:19], v[2:5], off
	global_store_dwordx4 v[18:19], v[6:9], off offset:256
	s_cbranch_vccnz .LBB0_1029
	s_andn2_b64 vcc, exec, s[20:21]
	s_cbranch_vccnz .LBB0_1028
	s_barrier
	s_branch .LBB0_1028

; __device__ __forceinline__ unsigned pk2(float lo, float hi) { return pg8::cvt_pk_bf16(lo, hi); }
;     __device__ __forceinline__ void operator()(const f32x4 (&acc)[2][2][4][2], const pg8::Unit& u, int wr, int wc, int fr, int fq) const {
;     ...
;                 const int R = rowbase + u.pm * 256 + ai * 128 + wr * 64 + m * 16 + fr;
;                 const float* src = islat ? rin_l + (size_t)R * DM : rin_c + (size_t)(R - TL) * DM;
;                 float* dst = islat ? rout_l + (size_t)R * DM : rout_c + (size_t)(R - TL) * DM;
;                 float ss = 0.f;
; #pragma unroll
;                 for (int bj = 0; bj < 2; ++bj) { const int c = u.pn * 256 + bj * 128 + wc * 32 + 8 * fq;
;                     const f32x4 xa = *(const f32x4*)(src + c) + gv[bj][0] * acc[ai][bj][m][0];
;                     const f32x4 xb = *(const f32x4*)(src + c + 4) + gv[bj][1] * acc[ai][bj][m][1];
;                     *(f32x4*)(dst + c) = xa; *(f32x4*)(dst + c + 4) = xb;
;                     ss += (xa[0] * xa[0] + xa[1] * xa[1]) + (xa[2] * xa[2] + xa[3] * xa[3]) + (xb[0] * xb[0] + xb[1] * xb[1]) + (xb[2] * xb[2] + xb[3] * xb[3]);
;                     const f32x4 ya = xa * sv[bj][0], yb = xb * sv[bj][1];
;                     u32x4 w; w.x = pk2(ya[0], ya[1]); w.y = pk2(ya[2], ya[3]); w.z = pk2(yb[0], yb[1]); w.w = pk2(yb[2], yb[3]);
;                     *(u32x4*)(Hn + (size_t)R * DM + c) = w; }
;                 ss += __shfl_xor(ss, 16); ss += __shfl_xor(ss, 32);
;                 if (fq == 0) stat[(size_t)R * 16 + u.pn * 4 + wc] = ss;
.LBB0_1215:
	v_and_b32_e32 v200, 64, v228
	v_xor_b32_e32 v195, 16, v228
	v_add_u32_e32 v202, 64, v200
	v_cmp_lt_i32_e32 vcc, v195, v202
	s_lshl_b32 s24, s0, 2
	s_ashr_i32 s25, s24, 31
	v_cndmask_b32_e32 v195, v228, v195, vcc
	v_lshlrev_b32_e32 v200, 2, v195
	v_xor_b32_e32 v195, 32, v228
	v_cmp_lt_i32_e32 vcc, v195, v202
	v_cndmask_b32_e64 v202, v194, v190, s[42:43]
	s_and_b64 s[10:11], s[42:43], exec
	v_ashrrev_i32_e32 v203, 31, v202
	s_cselect_b32 s69, s49, s67
	s_cselect_b32 s68, s48, s66
	v_lshlrev_b64 v[202:203], 12, v[202:203]
	v_lshl_add_u64 v[202:203], s[68:69], 0, v[202:203]
	v_lshl_add_u64 v[212:213], v[202:203], 0, v[188:189]
	s_mov_b32 s100, 0xaaaaaaaa
	s_mov_b32 s101, 0xaaaaaaaa
	v_mov_b32_e32 v222, 0x1000
	v_mov_b32_e32 v223, 16
	v_cndmask_b32_e64 v242, v222, v223, s[100:101]
	v_mov_b32_e32 v243, 0
	global_load_dwordx4 v[202:205], v[212:213], off offset:16
	global_load_dwordx4 v[206:209], v[212:213], off
	v_lshlrev_b64 v[210:211], 11, v[190:191]
	v_cndmask_b32_e32 v195, v228, v195, vcc
	v_lshlrev_b32_e32 v195, 2, v195
	s_waitcnt vmcnt(0)
	v_pk_fma_f32 v[204:205], v[156:157], v[88:89], v[204:205]
	v_pk_fma_f32 v[160:161], v[160:161], v[96:97], v[208:209]
	v_pk_fma_f32 v[158:159], v[158:159], v[94:95], v[206:207]
	v_mul_f32_e32 v157, v161, v161
	v_mul_f32_e32 v156, v159, v159
	v_pk_fma_f32 v[202:203], v[154:155], v[86:87], v[202:203]
	v_fmac_f32_e32 v156, v158, v158
	v_fmac_f32_e32 v157, v160, v160
	v_add_f32_e32 v156, v156, v157
	v_mul_f32_e32 v157, v203, v203
	v_fmac_f32_e32 v157, v202, v202
	v_add_f32_e32 v156, v156, v157
	v_mul_f32_e32 v157, v205, v205
	v_lshl_add_u64 v[154:155], v[192:193], 0, v[188:189]
	v_fmac_f32_e32 v157, v204, v204
	v_cndmask_b32_e64 v222, v202, v158, s[100:101]
	v_cndmask_b32_e64 v223, v203, v159, s[100:101]
	v_cndmask_b32_e64 v224, v204, v160, s[100:101]
	v_cndmask_b32_e64 v225, v205, v161, s[100:101]
	v_mov_b32_dpp v238, v222 quad_perm:[1,0,3,2] row_mask:0xf bank_mask:0xf
	v_mov_b32_dpp v239, v223 quad_perm:[1,0,3,2] row_mask:0xf bank_mask:0xf
	v_mov_b32_dpp v240, v224 quad_perm:[1,0,3,2] row_mask:0xf bank_mask:0xf
	v_mov_b32_dpp v241, v225 quad_perm:[1,0,3,2] row_mask:0xf bank_mask:0xf
	v_cndmask_b32_e64 v214, v158, v238, s[100:101]
	v_cndmask_b32_e64 v218, v238, v202, s[100:101]
	v_cndmask_b32_e64 v215, v159, v239, s[100:101]
	v_cndmask_b32_e64 v219, v239, v203, s[100:101]
	v_cndmask_b32_e64 v216, v160, v240, s[100:101]
	v_cndmask_b32_e64 v220, v240, v204, s[100:101]
	v_cndmask_b32_e64 v217, v161, v241, s[100:101]
	v_cndmask_b32_e64 v221, v241, v205, s[100:101]
	v_lshl_add_u64 v[226:227], v[154:155], 0, v[242:243]
	global_store_dwordx4 v[226:227], v[214:217], off offset:-4096
	global_store_dwordx4 v[226:227], v[218:221], off
	v_add_f32_e32 v194, v157, v156
	v_pk_mul_f32 v[160:161], v[92:93], v[160:161]
	v_pk_mul_f32 v[156:157], v[90:91], v[158:159]
	v_pk_mul_f32 v[192:193], v[84:85], v[204:205]
	v_pk_mul_f32 v[158:159], v[82:83], v[202:203]
	v_cvt_pk_bf16_f32 v156, v156, v157
	v_cvt_pk_bf16_f32 v157, v160, v161
	v_lshl_add_u64 v[160:161], s[60:61], 0, v[210:211]
	v_cvt_pk_bf16_f32 v158, v158, v159
	v_cvt_pk_bf16_f32 v159, v192, v193
	v_lshl_add_u64 v[160:161], v[186:187], 1, v[160:161]
	global_store_dwordx4 v[160:161], v[156:159], off
	global_load_dwordx4 v[156:159], v[212:213], off offset:528
	s_nop 0
	global_load_dwordx4 v[202:205], v[212:213], off offset:512
	s_waitcnt vmcnt(1)
	v_pk_fma_f32 v[148:149], v[148:149], v[76:77], v[158:159]
	s_waitcnt vmcnt(0)
	v_pk_fma_f32 v[152:153], v[152:153], v[80:81], v[204:205]
	v_pk_fma_f32 v[150:151], v[150:151], v[78:79], v[202:203]
	v_pk_fma_f32 v[146:147], v[146:147], v[74:75], v[156:157]
	v_cndmask_b32_e64 v222, v146, v150, s[100:101]
	v_cndmask_b32_e64 v223, v147, v151, s[100:101]
	v_cndmask_b32_e64 v224, v148, v152, s[100:101]
	v_cndmask_b32_e64 v225, v149, v153, s[100:101]
	v_mov_b32_dpp v238, v222 quad_perm:[1,0,3,2] row_mask:0xf bank_mask:0xf
	v_mov_b32_dpp v239, v223 quad_perm:[1,0,3,2] row_mask:0xf bank_mask:0xf
	v_mov_b32_dpp v240, v224 quad_perm:[1,0,3,2] row_mask:0xf bank_mask:0xf
	v_mov_b32_dpp v241, v225 quad_perm:[1,0,3,2] row_mask:0xf bank_mask:0xf
	v_cndmask_b32_e64 v214, v150, v238, s[100:101]
	v_cndmask_b32_e64 v218, v238, v146, s[100:101]
	v_cndmask_b32_e64 v215, v151, v239, s[100:101]
	v_cndmask_b32_e64 v219, v239, v147, s[100:101]
	v_cndmask_b32_e64 v216, v152, v240, s[100:101]
	v_cndmask_b32_e64 v220, v240, v148, s[100:101]
	v_cndmask_b32_e64 v217, v153, v241, s[100:101]
	v_cndmask_b32_e64 v221, v241, v149, s[100:101]
	v_lshl_add_u64 v[226:227], v[154:155], 0, v[242:243]
	global_store_dwordx4 v[226:227], v[214:217], off offset:-3584
	global_store_dwordx4 v[226:227], v[218:221], off offset:512
	v_mul_f32_e32 v154, v151, v151
	v_mul_f32_e32 v155, v153, v153
	v_fmac_f32_e32 v154, v150, v150
	v_fmac_f32_e32 v155, v152, v152
	v_add_f32_e32 v154, v154, v155
	v_mul_f32_e32 v155, v147, v147
	v_fmac_f32_e32 v155, v146, v146
	v_add_f32_e32 v154, v154, v155
	v_mul_f32_e32 v155, v149, v149
	v_fmac_f32_e32 v155, v148, v148
	v_add_f32_e32 v154, v155, v154
	v_add_f32_e32 v156, v194, v154
	v_pk_mul_f32 v[152:153], v[64:65], v[152:153]
	v_pk_mul_f32 v[150:151], v[62:63], v[150:151]
	v_pk_mul_f32 v[154:155], v[60:61], v[148:149]
	v_pk_mul_f32 v[148:149], v[58:59], v[146:147]
	v_cvt_pk_bf16_f32 v146, v150, v151
	v_cvt_pk_bf16_f32 v147, v152, v153
	v_cvt_pk_bf16_f32 v148, v148, v149
	v_cvt_pk_bf16_f32 v149, v154, v155
	global_store_dwordx4 v[160:161], v[146:149], off offset:256
	ds_bpermute_b32 v146, v200, v156
	s_waitcnt lgkmcnt(0)
	v_add_f32_e32 v146, v156, v146
	ds_bpermute_b32 v147, v195, v146
	s_and_saveexec_b64 s[34:35], s[38:39]
	s_cbranch_execz .LBB0_1217
	v_lshlrev_b64 v[148:149], 6, v[190:191]
	v_lshl_add_u64 v[148:149], s[62:63], 0, v[148:149]
	v_lshl_add_u64 v[148:149], s[24:25], 2, v[148:149]
	s_lshl_b32 s0, s56, 2
	v_lshl_add_u64 v[148:149], v[148:149], 0, s[0:1]
	s_waitcnt lgkmcnt(0)
	v_add_f32_e32 v146, v146, v147
	global_store_dword v[148:149], v146, off

; __device__ __forceinline__ unsigned pk2(float lo, float hi) { return pg8::cvt_pk_bf16(lo, hi); }
;     __device__ __forceinline__ void operator()(const f32x4 (&acc)[2][2][4][2], const pg8::Unit& u, int wr, int wc, int fr, int fq) const {
;     ...
;                 const int R = rowbase + u.pm * 256 + ai * 128 + wr * 64 + m * 16 + fr;
;                 const float* src = islat ? rin_l + (size_t)R * DM : rin_c + (size_t)(R - TL) * DM;
;                 float* dst = islat ? rout_l + (size_t)R * DM : rout_c + (size_t)(R - TL) * DM;
;                 float ss = 0.f;
; #pragma unroll
;                 for (int bj = 0; bj < 2; ++bj) { const int c = u.pn * 256 + bj * 128 + wc * 32 + 8 * fq;
;                     const f32x4 xa = *(const f32x4*)(src + c) + gv[bj][0] * acc[ai][bj][m][0];
;                     const f32x4 xb = *(const f32x4*)(src + c + 4) + gv[bj][1] * acc[ai][bj][m][1];
;                     *(f32x4*)(dst + c) = xa; *(f32x4*)(dst + c + 4) = xb;
;                     ss += (xa[0] * xa[0] + xa[1] * xa[1]) + (xa[2] * xa[2] + xa[3] * xa[3]) + (xb[0] * xb[0] + xb[1] * xb[1]) + (xb[2] * xb[2] + xb[3] * xb[3]);
;                     const f32x4 ya = xa * sv[bj][0], yb = xb * sv[bj][1];
;                     u32x4 w; w.x = pk2(ya[0], ya[1]); w.y = pk2(ya[2], ya[3]); w.z = pk2(yb[0], yb[1]); w.w = pk2(yb[2], yb[3]);
;                     *(u32x4*)(Hn + (size_t)R * DM + c) = w; }
;                 ss += __shfl_xor(ss, 16); ss += __shfl_xor(ss, 32);
;                 if (fq == 0) stat[(size_t)R * 16 + u.pn * 4 + wc] = ss;
.LBB0_1221:
	v_cndmask_b32_e64 v150, v150, v146, s[42:43]
	v_ashrrev_i32_e32 v151, 31, v150
	v_lshlrev_b64 v[150:151], 12, v[150:151]
	v_lshl_add_u64 v[150:151], s[68:69], 0, v[150:151]
	v_lshl_add_u64 v[158:159], v[150:151], 0, v[188:189]
	global_load_dwordx4 v[150:153], v[158:159], off
	global_load_dwordx4 v[154:157], v[158:159], off offset:16
	v_lshlrev_b64 v[160:161], 11, v[146:147]
	v_lshl_add_u64 v[192:193], v[148:149], 0, v[188:189]
	v_lshl_add_u64 v[148:149], s[60:61], 0, v[160:161]
	v_lshl_add_u64 v[160:161], v[186:187], 1, v[148:149]
	s_waitcnt vmcnt(1)
	v_pk_fma_f32 v[144:145], v[144:145], v[96:97], v[152:153]
	v_pk_fma_f32 v[142:143], v[142:143], v[94:95], v[150:151]
	s_waitcnt vmcnt(0)
	v_pk_fma_f32 v[140:141], v[140:141], v[88:89], v[156:157]
	v_pk_fma_f32 v[138:139], v[138:139], v[86:87], v[154:155]
	v_pk_mul_f32 v[150:151], v[92:93], v[144:145]
	v_pk_mul_f32 v[148:149], v[90:91], v[142:143]
	v_pk_mul_f32 v[152:153], v[84:85], v[140:141]
	v_pk_mul_f32 v[154:155], v[82:83], v[138:139]
	v_cvt_pk_bf16_f32 v148, v148, v149
	v_cvt_pk_bf16_f32 v149, v150, v151
	v_cvt_pk_bf16_f32 v150, v154, v155
	v_cvt_pk_bf16_f32 v151, v152, v153
	v_cndmask_b32_e64 v222, v138, v142, s[100:101]
	v_cndmask_b32_e64 v223, v139, v143, s[100:101]
	v_cndmask_b32_e64 v224, v140, v144, s[100:101]
	v_cndmask_b32_e64 v225, v141, v145, s[100:101]
	v_mov_b32_dpp v238, v222 quad_perm:[1,0,3,2] row_mask:0xf bank_mask:0xf
	v_mov_b32_dpp v239, v223 quad_perm:[1,0,3,2] row_mask:0xf bank_mask:0xf
	v_mov_b32_dpp v240, v224 quad_perm:[1,0,3,2] row_mask:0xf bank_mask:0xf
	v_mov_b32_dpp v241, v225 quad_perm:[1,0,3,2] row_mask:0xf bank_mask:0xf
	v_cndmask_b32_e64 v214, v142, v238, s[100:101]
	v_cndmask_b32_e64 v218, v238, v138, s[100:101]
	v_cndmask_b32_e64 v215, v143, v239, s[100:101]
	v_cndmask_b32_e64 v219, v239, v139, s[100:101]
	v_cndmask_b32_e64 v216, v144, v240, s[100:101]
	v_cndmask_b32_e64 v220, v240, v140, s[100:101]
	v_cndmask_b32_e64 v217, v145, v241, s[100:101]
	v_cndmask_b32_e64 v221, v241, v141, s[100:101]
	v_lshl_add_u64 v[226:227], v[192:193], 0, v[242:243]
	global_store_dwordx4 v[226:227], v[214:217], off offset:-4096
	global_store_dwordx4 v[226:227], v[218:221], off
	global_store_dwordx4 v[160:161], v[148:151], off
	global_load_dwordx4 v[148:151], v[158:159], off offset:512
	s_nop 0
	global_load_dwordx4 v[152:155], v[158:159], off offset:528
	v_mul_f32_e32 v143, v143, v143
	v_mul_f32_e32 v145, v145, v145
	v_mul_f32_e32 v139, v139, v139
	v_fmac_f32_e32 v143, v142, v142
	v_fmac_f32_e32 v145, v144, v144
	v_mul_f32_e32 v141, v141, v141
	v_fmac_f32_e32 v139, v138, v138
	v_add_f32_e32 v138, v143, v145
	v_fmac_f32_e32 v141, v140, v140
	v_add_f32_e32 v138, v138, v139
	v_add_f32_e32 v138, v141, v138
	s_waitcnt vmcnt(1)
	v_pk_fma_f32 v[136:137], v[136:137], v[80:81], v[150:151]
	v_pk_fma_f32 v[134:135], v[134:135], v[78:79], v[148:149]
	s_waitcnt vmcnt(0)
	v_pk_fma_f32 v[130:131], v[130:131], v[74:75], v[152:153]
	v_mul_f32_e32 v139, v135, v135
	v_mul_f32_e32 v140, v137, v137
	v_pk_fma_f32 v[132:133], v[132:133], v[76:77], v[154:155]
	v_mul_f32_e32 v141, v131, v131
	v_fmac_f32_e32 v139, v134, v134
	v_fmac_f32_e32 v140, v136, v136
	v_mul_f32_e32 v142, v133, v133
	v_fmac_f32_e32 v141, v130, v130
	v_add_f32_e32 v139, v139, v140
	v_fmac_f32_e32 v142, v132, v132
	v_add_f32_e32 v139, v139, v141
	v_add_f32_e32 v139, v142, v139
	v_add_f32_e32 v142, v138, v139
	ds_bpermute_b32 v143, v200, v142
	v_cndmask_b32_e64 v222, v130, v134, s[100:101]
	v_cndmask_b32_e64 v223, v131, v135, s[100:101]
	v_cndmask_b32_e64 v224, v132, v136, s[100:101]
	v_cndmask_b32_e64 v225, v133, v137, s[100:101]
	v_mov_b32_dpp v238, v222 quad_perm:[1,0,3,2] row_mask:0xf bank_mask:0xf
	v_mov_b32_dpp v239, v223 quad_perm:[1,0,3,2] row_mask:0xf bank_mask:0xf
	v_mov_b32_dpp v240, v224 quad_perm:[1,0,3,2] row_mask:0xf bank_mask:0xf
	v_mov_b32_dpp v241, v225 quad_perm:[1,0,3,2] row_mask:0xf bank_mask:0xf
	v_cndmask_b32_e64 v214, v134, v238, s[100:101]
	v_cndmask_b32_e64 v218, v238, v130, s[100:101]
	v_cndmask_b32_e64 v215, v135, v239, s[100:101]
	v_cndmask_b32_e64 v219, v239, v131, s[100:101]
	v_cndmask_b32_e64 v216, v136, v240, s[100:101]
	v_cndmask_b32_e64 v220, v240, v132, s[100:101]
	v_cndmask_b32_e64 v217, v137, v241, s[100:101]
	v_cndmask_b32_e64 v221, v241, v133, s[100:101]
	v_lshl_add_u64 v[226:227], v[192:193], 0, v[242:243]
	global_store_dwordx4 v[226:227], v[214:217], off offset:-3584
	global_store_dwordx4 v[226:227], v[218:221], off offset:512
	v_pk_mul_f32 v[140:141], v[58:59], v[130:131]
	v_pk_mul_f32 v[136:137], v[64:65], v[136:137]
	v_pk_mul_f32 v[134:135], v[62:63], v[134:135]
	s_waitcnt lgkmcnt(0)
	v_add_f32_e32 v130, v142, v143
	ds_bpermute_b32 v131, v195, v130
	v_pk_mul_f32 v[138:139], v[60:61], v[132:133]
	v_cvt_pk_bf16_f32 v132, v134, v135
	v_cvt_pk_bf16_f32 v133, v136, v137
	v_cvt_pk_bf16_f32 v134, v140, v141
	v_cvt_pk_bf16_f32 v135, v138, v139
	global_store_dwordx4 v[160:161], v[132:135], off offset:256
	s_and_saveexec_b64 s[34:35], s[38:39]
	s_cbranch_execz .LBB0_1223
	v_lshlrev_b64 v[132:133], 6, v[146:147]
	v_lshl_add_u64 v[132:133], s[62:63], 0, v[132:133]
	v_lshl_add_u64 v[132:133], s[24:25], 2, v[132:133]
	s_lshl_b32 s0, s56, 2
	v_lshl_add_u64 v[132:133], v[132:133], 0, s[0:1]
	s_waitcnt lgkmcnt(0)
	v_add_f32_e32 v130, v130, v131
	global_store_dword v[132:133], v130, off

; __device__ __forceinline__ unsigned pk2(float lo, float hi) { return pg8::cvt_pk_bf16(lo, hi); }
;     __device__ __forceinline__ void operator()(const f32x4 (&acc)[2][2][4][2], const pg8::Unit& u, int wr, int wc, int fr, int fq) const {
;     ...
;                 const int R = rowbase + u.pm * 256 + ai * 128 + wr * 64 + m * 16 + fr;
;                 const float* src = islat ? rin_l + (size_t)R * DM : rin_c + (size_t)(R - TL) * DM;
;                 float* dst = islat ? rout_l + (size_t)R * DM : rout_c + (size_t)(R - TL) * DM;
;                 float ss = 0.f;
; #pragma unroll
;                 for (int bj = 0; bj < 2; ++bj) { const int c = u.pn * 256 + bj * 128 + wc * 32 + 8 * fq;
;                     const f32x4 xa = *(const f32x4*)(src + c) + gv[bj][0] * acc[ai][bj][m][0];
;                     const f32x4 xb = *(const f32x4*)(src + c + 4) + gv[bj][1] * acc[ai][bj][m][1];
;                     *(f32x4*)(dst + c) = xa; *(f32x4*)(dst + c + 4) = xb;
;                     ss += (xa[0] * xa[0] + xa[1] * xa[1]) + (xa[2] * xa[2] + xa[3] * xa[3]) + (xb[0] * xb[0] + xb[1] * xb[1]) + (xb[2] * xb[2] + xb[3] * xb[3]);
;                     const f32x4 ya = xa * sv[bj][0], yb = xb * sv[bj][1];
;                     u32x4 w; w.x = pk2(ya[0], ya[1]); w.y = pk2(ya[2], ya[3]); w.z = pk2(yb[0], yb[1]); w.w = pk2(yb[2], yb[3]);
;                     *(u32x4*)(Hn + (size_t)R * DM + c) = w; }
;                 ss += __shfl_xor(ss, 16); ss += __shfl_xor(ss, 32);
;                 if (fq == 0) stat[(size_t)R * 16 + u.pn * 4 + wc] = ss;
.LBB0_1227:
	v_cndmask_b32_e64 v134, v134, v130, s[42:43]
	v_ashrrev_i32_e32 v135, 31, v134
	v_lshlrev_b64 v[134:135], 12, v[134:135]
	v_lshl_add_u64 v[134:135], s[68:69], 0, v[134:135]
	v_lshl_add_u64 v[142:143], v[134:135], 0, v[188:189]
	global_load_dwordx4 v[134:137], v[142:143], off
	global_load_dwordx4 v[138:141], v[142:143], off offset:16
	v_lshlrev_b64 v[144:145], 11, v[130:131]
	v_lshl_add_u64 v[146:147], v[132:133], 0, v[188:189]
	v_lshl_add_u64 v[132:133], s[60:61], 0, v[144:145]
	v_lshl_add_u64 v[144:145], v[186:187], 1, v[132:133]
	s_waitcnt vmcnt(1)
	v_pk_fma_f32 v[128:129], v[128:129], v[96:97], v[136:137]
	v_pk_fma_f32 v[126:127], v[126:127], v[94:95], v[134:135]
	s_waitcnt vmcnt(0)
	v_pk_fma_f32 v[124:125], v[124:125], v[88:89], v[140:141]
	v_pk_fma_f32 v[122:123], v[122:123], v[86:87], v[138:139]
	v_pk_mul_f32 v[134:135], v[92:93], v[128:129]
	v_pk_mul_f32 v[132:133], v[90:91], v[126:127]
	v_pk_mul_f32 v[136:137], v[84:85], v[124:125]
	v_pk_mul_f32 v[138:139], v[82:83], v[122:123]
	v_cvt_pk_bf16_f32 v132, v132, v133
	v_cvt_pk_bf16_f32 v133, v134, v135
	v_cvt_pk_bf16_f32 v134, v138, v139
	v_cvt_pk_bf16_f32 v135, v136, v137
	v_cndmask_b32_e64 v222, v122, v126, s[100:101]
	v_cndmask_b32_e64 v223, v123, v127, s[100:101]
	v_cndmask_b32_e64 v224, v124, v128, s[100:101]
	v_cndmask_b32_e64 v225, v125, v129, s[100:101]
	v_mov_b32_dpp v238, v222 quad_perm:[1,0,3,2] row_mask:0xf bank_mask:0xf
	v_mov_b32_dpp v239, v223 quad_perm:[1,0,3,2] row_mask:0xf bank_mask:0xf
	v_mov_b32_dpp v240, v224 quad_perm:[1,0,3,2] row_mask:0xf bank_mask:0xf
	v_mov_b32_dpp v241, v225 quad_perm:[1,0,3,2] row_mask:0xf bank_mask:0xf
	v_cndmask_b32_e64 v214, v126, v238, s[100:101]
	v_cndmask_b32_e64 v218, v238, v122, s[100:101]
	v_cndmask_b32_e64 v215, v127, v239, s[100:101]
	v_cndmask_b32_e64 v219, v239, v123, s[100:101]
	v_cndmask_b32_e64 v216, v128, v240, s[100:101]
	v_cndmask_b32_e64 v220, v240, v124, s[100:101]
	v_cndmask_b32_e64 v217, v129, v241, s[100:101]
	v_cndmask_b32_e64 v221, v241, v125, s[100:101]
	v_lshl_add_u64 v[226:227], v[146:147], 0, v[242:243]
	global_store_dwordx4 v[226:227], v[214:217], off offset:-4096
	global_store_dwordx4 v[226:227], v[218:221], off
	global_store_dwordx4 v[144:145], v[132:135], off
	global_load_dwordx4 v[132:135], v[142:143], off offset:512
	s_nop 0
	global_load_dwordx4 v[136:139], v[142:143], off offset:528
	v_mul_f32_e32 v127, v127, v127
	v_mul_f32_e32 v129, v129, v129
	v_mul_f32_e32 v123, v123, v123
	v_fmac_f32_e32 v127, v126, v126
	v_fmac_f32_e32 v129, v128, v128
	v_mul_f32_e32 v125, v125, v125
	v_fmac_f32_e32 v123, v122, v122
	v_add_f32_e32 v122, v127, v129
	v_fmac_f32_e32 v125, v124, v124
	v_add_f32_e32 v122, v122, v123
	v_add_f32_e32 v122, v125, v122
	s_waitcnt vmcnt(1)
	v_pk_fma_f32 v[120:121], v[120:121], v[80:81], v[134:135]
	v_pk_fma_f32 v[118:119], v[118:119], v[78:79], v[132:133]
	s_waitcnt vmcnt(0)
	v_pk_fma_f32 v[114:115], v[114:115], v[74:75], v[136:137]
	v_mul_f32_e32 v123, v119, v119
	v_mul_f32_e32 v124, v121, v121
	v_pk_fma_f32 v[116:117], v[116:117], v[76:77], v[138:139]
	v_mul_f32_e32 v125, v115, v115
	v_fmac_f32_e32 v123, v118, v118
	v_fmac_f32_e32 v124, v120, v120
	v_mul_f32_e32 v126, v117, v117
	v_fmac_f32_e32 v125, v114, v114
	v_add_f32_e32 v123, v123, v124
	v_fmac_f32_e32 v126, v116, v116
	v_add_f32_e32 v123, v123, v125
	v_add_f32_e32 v123, v126, v123
	v_add_f32_e32 v126, v122, v123
	ds_bpermute_b32 v127, v200, v126
	v_cndmask_b32_e64 v222, v114, v118, s[100:101]
	v_cndmask_b32_e64 v223, v115, v119, s[100:101]
	v_cndmask_b32_e64 v224, v116, v120, s[100:101]
	v_cndmask_b32_e64 v225, v117, v121, s[100:101]
	v_mov_b32_dpp v238, v222 quad_perm:[1,0,3,2] row_mask:0xf bank_mask:0xf
	v_mov_b32_dpp v239, v223 quad_perm:[1,0,3,2] row_mask:0xf bank_mask:0xf
	v_mov_b32_dpp v240, v224 quad_perm:[1,0,3,2] row_mask:0xf bank_mask:0xf
	v_mov_b32_dpp v241, v225 quad_perm:[1,0,3,2] row_mask:0xf bank_mask:0xf
	v_cndmask_b32_e64 v214, v118, v238, s[100:101]
	v_cndmask_b32_e64 v218, v238, v114, s[100:101]
	v_cndmask_b32_e64 v215, v119, v239, s[100:101]
	v_cndmask_b32_e64 v219, v239, v115, s[100:101]
	v_cndmask_b32_e64 v216, v120, v240, s[100:101]
	v_cndmask_b32_e64 v220, v240, v116, s[100:101]
	v_cndmask_b32_e64 v217, v121, v241, s[100:101]
	v_cndmask_b32_e64 v221, v241, v117, s[100:101]
	v_lshl_add_u64 v[226:227], v[146:147], 0, v[242:243]
	global_store_dwordx4 v[226:227], v[214:217], off offset:-3584
	global_store_dwordx4 v[226:227], v[218:221], off offset:512
	v_pk_mul_f32 v[124:125], v[58:59], v[114:115]
	v_pk_mul_f32 v[120:121], v[64:65], v[120:121]
	v_pk_mul_f32 v[118:119], v[62:63], v[118:119]
	s_waitcnt lgkmcnt(0)
	v_add_f32_e32 v114, v126, v127
	ds_bpermute_b32 v115, v195, v114
	v_pk_mul_f32 v[122:123], v[60:61], v[116:117]
	v_cvt_pk_bf16_f32 v116, v118, v119
	v_cvt_pk_bf16_f32 v117, v120, v121
	v_cvt_pk_bf16_f32 v118, v124, v125
	v_cvt_pk_bf16_f32 v119, v122, v123
	global_store_dwordx4 v[144:145], v[116:119], off offset:256
	s_and_saveexec_b64 s[34:35], s[38:39]
	s_cbranch_execz .LBB0_1229
	v_lshlrev_b64 v[116:117], 6, v[130:131]
	v_lshl_add_u64 v[116:117], s[62:63], 0, v[116:117]
	v_lshl_add_u64 v[116:117], s[24:25], 2, v[116:117]
	s_lshl_b32 s0, s56, 2
	v_lshl_add_u64 v[116:117], v[116:117], 0, s[0:1]
	s_waitcnt lgkmcnt(0)
	v_add_f32_e32 v114, v114, v115
	global_store_dword v[116:117], v114, off

; __device__ __forceinline__ unsigned pk2(float lo, float hi) { return pg8::cvt_pk_bf16(lo, hi); }
;     __device__ __forceinline__ void operator()(const f32x4 (&acc)[2][2][4][2], const pg8::Unit& u, int wr, int wc, int fr, int fq) const {
;     ...
;                 const int R = rowbase + u.pm * 256 + ai * 128 + wr * 64 + m * 16 + fr;
;                 const float* src = islat ? rin_l + (size_t)R * DM : rin_c + (size_t)(R - TL) * DM;
;                 float* dst = islat ? rout_l + (size_t)R * DM : rout_c + (size_t)(R - TL) * DM;
;                 float ss = 0.f;
; #pragma unroll
;                 for (int bj = 0; bj < 2; ++bj) { const int c = u.pn * 256 + bj * 128 + wc * 32 + 8 * fq;
;                     const f32x4 xa = *(const f32x4*)(src + c) + gv[bj][0] * acc[ai][bj][m][0];
;                     const f32x4 xb = *(const f32x4*)(src + c + 4) + gv[bj][1] * acc[ai][bj][m][1];
;                     *(f32x4*)(dst + c) = xa; *(f32x4*)(dst + c + 4) = xb;
;                     ss += (xa[0] * xa[0] + xa[1] * xa[1]) + (xa[2] * xa[2] + xa[3] * xa[3]) + (xb[0] * xb[0] + xb[1] * xb[1]) + (xb[2] * xb[2] + xb[3] * xb[3]);
;                     const f32x4 ya = xa * sv[bj][0], yb = xb * sv[bj][1];
;                     u32x4 w; w.x = pk2(ya[0], ya[1]); w.y = pk2(ya[2], ya[3]); w.z = pk2(yb[0], yb[1]); w.w = pk2(yb[2], yb[3]);
;                     *(u32x4*)(Hn + (size_t)R * DM + c) = w; }
;                 ss += __shfl_xor(ss, 16); ss += __shfl_xor(ss, 32);
;                 if (fq == 0) stat[(size_t)R * 16 + u.pn * 4 + wc] = ss;
.LBB0_1233:
	v_cndmask_b32_e64 v118, v118, v114, s[42:43]
	v_ashrrev_i32_e32 v119, 31, v118
	v_lshlrev_b64 v[118:119], 12, v[118:119]
	v_lshl_add_u64 v[118:119], s[68:69], 0, v[118:119]
	v_lshl_add_u64 v[126:127], v[118:119], 0, v[188:189]
	global_load_dwordx4 v[118:121], v[126:127], off
	global_load_dwordx4 v[122:125], v[126:127], off offset:16
	v_lshlrev_b64 v[128:129], 11, v[114:115]
	v_lshl_add_u64 v[130:131], v[116:117], 0, v[188:189]
	v_lshl_add_u64 v[116:117], s[60:61], 0, v[128:129]
	v_lshl_add_u64 v[128:129], v[186:187], 1, v[116:117]
	s_waitcnt vmcnt(1)
	v_pk_fma_f32 v[112:113], v[112:113], v[96:97], v[120:121]
	v_pk_fma_f32 v[110:111], v[110:111], v[94:95], v[118:119]
	s_waitcnt vmcnt(0)
	v_pk_fma_f32 v[108:109], v[108:109], v[88:89], v[124:125]
	v_pk_fma_f32 v[106:107], v[106:107], v[86:87], v[122:123]
	v_pk_mul_f32 v[118:119], v[92:93], v[112:113]
	v_pk_mul_f32 v[116:117], v[90:91], v[110:111]
	v_pk_mul_f32 v[120:121], v[84:85], v[108:109]
	v_pk_mul_f32 v[122:123], v[82:83], v[106:107]
	v_cvt_pk_bf16_f32 v116, v116, v117
	v_cvt_pk_bf16_f32 v117, v118, v119
	v_cvt_pk_bf16_f32 v118, v122, v123
	v_cvt_pk_bf16_f32 v119, v120, v121
	v_cndmask_b32_e64 v222, v106, v110, s[100:101]
	v_cndmask_b32_e64 v223, v107, v111, s[100:101]
	v_cndmask_b32_e64 v224, v108, v112, s[100:101]
	v_cndmask_b32_e64 v225, v109, v113, s[100:101]
	v_mov_b32_dpp v238, v222 quad_perm:[1,0,3,2] row_mask:0xf bank_mask:0xf
	v_mov_b32_dpp v239, v223 quad_perm:[1,0,3,2] row_mask:0xf bank_mask:0xf
	v_mov_b32_dpp v240, v224 quad_perm:[1,0,3,2] row_mask:0xf bank_mask:0xf
	v_mov_b32_dpp v241, v225 quad_perm:[1,0,3,2] row_mask:0xf bank_mask:0xf
	v_cndmask_b32_e64 v214, v110, v238, s[100:101]
	v_cndmask_b32_e64 v218, v238, v106, s[100:101]
	v_cndmask_b32_e64 v215, v111, v239, s[100:101]
	v_cndmask_b32_e64 v219, v239, v107, s[100:101]
	v_cndmask_b32_e64 v216, v112, v240, s[100:101]
	v_cndmask_b32_e64 v220, v240, v108, s[100:101]
	v_cndmask_b32_e64 v217, v113, v241, s[100:101]
	v_cndmask_b32_e64 v221, v241, v109, s[100:101]
	v_lshl_add_u64 v[226:227], v[130:131], 0, v[242:243]
	global_store_dwordx4 v[226:227], v[214:217], off offset:-4096
	global_store_dwordx4 v[226:227], v[218:221], off
	global_store_dwordx4 v[128:129], v[116:119], off
	global_load_dwordx4 v[116:119], v[126:127], off offset:512
	s_nop 0
	global_load_dwordx4 v[120:123], v[126:127], off offset:528
	v_mul_f32_e32 v111, v111, v111
	v_mul_f32_e32 v113, v113, v113
	v_mul_f32_e32 v107, v107, v107
	v_fmac_f32_e32 v111, v110, v110
	v_fmac_f32_e32 v113, v112, v112
	v_mul_f32_e32 v109, v109, v109
	v_fmac_f32_e32 v107, v106, v106
	v_add_f32_e32 v106, v111, v113
	v_fmac_f32_e32 v109, v108, v108
	v_add_f32_e32 v106, v106, v107
	v_add_f32_e32 v106, v109, v106
	s_waitcnt vmcnt(1)
	v_pk_fma_f32 v[104:105], v[104:105], v[80:81], v[118:119]
	v_pk_fma_f32 v[102:103], v[102:103], v[78:79], v[116:117]
	s_waitcnt vmcnt(0)
	v_pk_fma_f32 v[98:99], v[98:99], v[74:75], v[120:121]
	v_mul_f32_e32 v107, v103, v103
	v_mul_f32_e32 v108, v105, v105
	v_pk_fma_f32 v[100:101], v[100:101], v[76:77], v[122:123]
	v_mul_f32_e32 v109, v99, v99
	v_fmac_f32_e32 v107, v102, v102
	v_fmac_f32_e32 v108, v104, v104
	v_mul_f32_e32 v110, v101, v101
	v_fmac_f32_e32 v109, v98, v98
	v_add_f32_e32 v107, v107, v108
	v_fmac_f32_e32 v110, v100, v100
	v_add_f32_e32 v107, v107, v109
	v_add_f32_e32 v107, v110, v107
	v_add_f32_e32 v110, v106, v107
	ds_bpermute_b32 v111, v200, v110
	v_cndmask_b32_e64 v222, v98, v102, s[100:101]
	v_cndmask_b32_e64 v223, v99, v103, s[100:101]
	v_cndmask_b32_e64 v224, v100, v104, s[100:101]
	v_cndmask_b32_e64 v225, v101, v105, s[100:101]
	v_mov_b32_dpp v238, v222 quad_perm:[1,0,3,2] row_mask:0xf bank_mask:0xf
	v_mov_b32_dpp v239, v223 quad_perm:[1,0,3,2] row_mask:0xf bank_mask:0xf
	v_mov_b32_dpp v240, v224 quad_perm:[1,0,3,2] row_mask:0xf bank_mask:0xf
	v_mov_b32_dpp v241, v225 quad_perm:[1,0,3,2] row_mask:0xf bank_mask:0xf
	v_cndmask_b32_e64 v214, v102, v238, s[100:101]
	v_cndmask_b32_e64 v218, v238, v98, s[100:101]
	v_cndmask_b32_e64 v215, v103, v239, s[100:101]
	v_cndmask_b32_e64 v219, v239, v99, s[100:101]
	v_cndmask_b32_e64 v216, v104, v240, s[100:101]
	v_cndmask_b32_e64 v220, v240, v100, s[100:101]
	v_cndmask_b32_e64 v217, v105, v241, s[100:101]
	v_cndmask_b32_e64 v221, v241, v101, s[100:101]
	v_lshl_add_u64 v[226:227], v[130:131], 0, v[242:243]
	global_store_dwordx4 v[226:227], v[214:217], off offset:-3584
	global_store_dwordx4 v[226:227], v[218:221], off offset:512
	v_pk_mul_f32 v[108:109], v[58:59], v[98:99]
	v_pk_mul_f32 v[104:105], v[64:65], v[104:105]
	v_pk_mul_f32 v[102:103], v[62:63], v[102:103]
	s_waitcnt lgkmcnt(0)
	v_add_f32_e32 v98, v110, v111
	ds_bpermute_b32 v99, v195, v98
	v_pk_mul_f32 v[106:107], v[60:61], v[100:101]
	v_cvt_pk_bf16_f32 v100, v102, v103
	v_cvt_pk_bf16_f32 v101, v104, v105
	v_cvt_pk_bf16_f32 v102, v108, v109
	v_cvt_pk_bf16_f32 v103, v106, v107
	global_store_dwordx4 v[128:129], v[100:103], off offset:256
	s_and_saveexec_b64 s[34:35], s[38:39]
	s_cbranch_execz .LBB0_1235
	v_lshlrev_b64 v[100:101], 6, v[114:115]
	v_lshl_add_u64 v[100:101], s[62:63], 0, v[100:101]
	v_lshl_add_u64 v[100:101], s[24:25], 2, v[100:101]
	s_lshl_b32 s0, s56, 2
	v_lshl_add_u64 v[100:101], v[100:101], 0, s[0:1]
	s_waitcnt lgkmcnt(0)
	v_add_f32_e32 v98, v98, v99
	global_store_dword v[100:101], v98, off

; __device__ __forceinline__ unsigned pk2(float lo, float hi) { return pg8::cvt_pk_bf16(lo, hi); }
;     __device__ __forceinline__ void operator()(const f32x4 (&acc)[2][2][4][2], const pg8::Unit& u, int wr, int wc, int fr, int fq) const {
;     ...
;                 const int R = rowbase + u.pm * 256 + ai * 128 + wr * 64 + m * 16 + fr;
;                 const float* src = islat ? rin_l + (size_t)R * DM : rin_c + (size_t)(R - TL) * DM;
;                 float* dst = islat ? rout_l + (size_t)R * DM : rout_c + (size_t)(R - TL) * DM;
;                 float ss = 0.f;
; #pragma unroll
;                 for (int bj = 0; bj < 2; ++bj) { const int c = u.pn * 256 + bj * 128 + wc * 32 + 8 * fq;
;                     const f32x4 xa = *(const f32x4*)(src + c) + gv[bj][0] * acc[ai][bj][m][0];
;                     const f32x4 xb = *(const f32x4*)(src + c + 4) + gv[bj][1] * acc[ai][bj][m][1];
;                     *(f32x4*)(dst + c) = xa; *(f32x4*)(dst + c + 4) = xb;
;                     ss += (xa[0] * xa[0] + xa[1] * xa[1]) + (xa[2] * xa[2] + xa[3] * xa[3]) + (xb[0] * xb[0] + xb[1] * xb[1]) + (xb[2] * xb[2] + xb[3] * xb[3]);
;                     const f32x4 ya = xa * sv[bj][0], yb = xb * sv[bj][1];
;                     u32x4 w; w.x = pk2(ya[0], ya[1]); w.y = pk2(ya[2], ya[3]); w.z = pk2(yb[0], yb[1]); w.w = pk2(yb[2], yb[3]);
;                     *(u32x4*)(Hn + (size_t)R * DM + c) = w; }
;                 ss += __shfl_xor(ss, 16); ss += __shfl_xor(ss, 32);
;                 if (fq == 0) stat[(size_t)R * 16 + u.pn * 4 + wc] = ss;
.LBB0_1239:
	v_cndmask_b32_e64 v102, v102, v98, s[42:43]
	v_ashrrev_i32_e32 v103, 31, v102
	v_lshlrev_b64 v[102:103], 12, v[102:103]
	v_lshl_add_u64 v[102:103], s[68:69], 0, v[102:103]
	v_lshl_add_u64 v[110:111], v[102:103], 0, v[188:189]
	global_load_dwordx4 v[102:105], v[110:111], off
	global_load_dwordx4 v[106:109], v[110:111], off offset:16
	v_lshlrev_b64 v[112:113], 11, v[98:99]
	v_lshl_add_u64 v[114:115], v[100:101], 0, v[188:189]
	v_lshl_add_u64 v[100:101], s[60:61], 0, v[112:113]
	v_lshl_add_u64 v[112:113], v[186:187], 1, v[100:101]
	s_waitcnt vmcnt(1)
	v_pk_fma_f32 v[72:73], v[72:73], v[96:97], v[104:105]
	v_pk_fma_f32 v[70:71], v[70:71], v[94:95], v[102:103]
	s_waitcnt vmcnt(0)
	v_pk_fma_f32 v[68:69], v[68:69], v[88:89], v[108:109]
	v_pk_fma_f32 v[66:67], v[66:67], v[86:87], v[106:107]
	v_pk_mul_f32 v[102:103], v[92:93], v[72:73]
	v_pk_mul_f32 v[100:101], v[90:91], v[70:71]
	v_pk_mul_f32 v[104:105], v[84:85], v[68:69]
	v_pk_mul_f32 v[106:107], v[82:83], v[66:67]
	v_cvt_pk_bf16_f32 v100, v100, v101
	v_cvt_pk_bf16_f32 v101, v102, v103
	v_cvt_pk_bf16_f32 v102, v106, v107
	v_cvt_pk_bf16_f32 v103, v104, v105
	v_cndmask_b32_e64 v222, v66, v70, s[100:101]
	v_cndmask_b32_e64 v223, v67, v71, s[100:101]
	v_cndmask_b32_e64 v224, v68, v72, s[100:101]
	v_cndmask_b32_e64 v225, v69, v73, s[100:101]
	v_mov_b32_dpp v238, v222 quad_perm:[1,0,3,2] row_mask:0xf bank_mask:0xf
	v_mov_b32_dpp v239, v223 quad_perm:[1,0,3,2] row_mask:0xf bank_mask:0xf
	v_mov_b32_dpp v240, v224 quad_perm:[1,0,3,2] row_mask:0xf bank_mask:0xf
	v_mov_b32_dpp v241, v225 quad_perm:[1,0,3,2] row_mask:0xf bank_mask:0xf
	v_cndmask_b32_e64 v214, v70, v238, s[100:101]
	v_cndmask_b32_e64 v218, v238, v66, s[100:101]
	v_cndmask_b32_e64 v215, v71, v239, s[100:101]
	v_cndmask_b32_e64 v219, v239, v67, s[100:101]
	v_cndmask_b32_e64 v216, v72, v240, s[100:101]
	v_cndmask_b32_e64 v220, v240, v68, s[100:101]
	v_cndmask_b32_e64 v217, v73, v241, s[100:101]
	v_cndmask_b32_e64 v221, v241, v69, s[100:101]
	v_lshl_add_u64 v[226:227], v[114:115], 0, v[242:243]
	global_store_dwordx4 v[226:227], v[214:217], off offset:-4096
	global_store_dwordx4 v[226:227], v[218:221], off
	global_store_dwordx4 v[112:113], v[100:103], off
	global_load_dwordx4 v[100:103], v[110:111], off offset:512
	s_nop 0
	global_load_dwordx4 v[104:107], v[110:111], off offset:528
	v_mul_f32_e32 v71, v71, v71
	v_mul_f32_e32 v73, v73, v73
	v_mul_f32_e32 v67, v67, v67
	v_fmac_f32_e32 v71, v70, v70
	v_fmac_f32_e32 v73, v72, v72
	v_mul_f32_e32 v69, v69, v69
	v_fmac_f32_e32 v67, v66, v66
	v_add_f32_e32 v66, v71, v73
	v_fmac_f32_e32 v69, v68, v68
	v_add_f32_e32 v66, v66, v67
	v_add_f32_e32 v66, v69, v66
	s_waitcnt vmcnt(1)
	v_pk_fma_f32 v[56:57], v[56:57], v[80:81], v[102:103]
	v_pk_fma_f32 v[54:55], v[54:55], v[78:79], v[100:101]
	s_waitcnt vmcnt(0)
	v_pk_fma_f32 v[50:51], v[50:51], v[74:75], v[104:105]
	v_mul_f32_e32 v67, v55, v55
	v_mul_f32_e32 v68, v57, v57
	v_pk_fma_f32 v[52:53], v[52:53], v[76:77], v[106:107]
	v_mul_f32_e32 v69, v51, v51
	v_fmac_f32_e32 v67, v54, v54
	v_fmac_f32_e32 v68, v56, v56
	v_mul_f32_e32 v70, v53, v53
	v_fmac_f32_e32 v69, v50, v50
	v_add_f32_e32 v67, v67, v68
	v_fmac_f32_e32 v70, v52, v52
	v_add_f32_e32 v67, v67, v69
	v_add_f32_e32 v67, v70, v67
	v_add_f32_e32 v70, v66, v67
	ds_bpermute_b32 v71, v200, v70
	v_cndmask_b32_e64 v222, v50, v54, s[100:101]
	v_cndmask_b32_e64 v223, v51, v55, s[100:101]
	v_cndmask_b32_e64 v224, v52, v56, s[100:101]
	v_cndmask_b32_e64 v225, v53, v57, s[100:101]
	v_mov_b32_dpp v238, v222 quad_perm:[1,0,3,2] row_mask:0xf bank_mask:0xf
	v_mov_b32_dpp v239, v223 quad_perm:[1,0,3,2] row_mask:0xf bank_mask:0xf
	v_mov_b32_dpp v240, v224 quad_perm:[1,0,3,2] row_mask:0xf bank_mask:0xf
	v_mov_b32_dpp v241, v225 quad_perm:[1,0,3,2] row_mask:0xf bank_mask:0xf
	v_cndmask_b32_e64 v214, v54, v238, s[100:101]
	v_cndmask_b32_e64 v218, v238, v50, s[100:101]
	v_cndmask_b32_e64 v215, v55, v239, s[100:101]
	v_cndmask_b32_e64 v219, v239, v51, s[100:101]
	v_cndmask_b32_e64 v216, v56, v240, s[100:101]
	v_cndmask_b32_e64 v220, v240, v52, s[100:101]
	v_cndmask_b32_e64 v217, v57, v241, s[100:101]
	v_cndmask_b32_e64 v221, v241, v53, s[100:101]
	v_lshl_add_u64 v[226:227], v[114:115], 0, v[242:243]
	global_store_dwordx4 v[226:227], v[214:217], off offset:-3584
	global_store_dwordx4 v[226:227], v[218:221], off offset:512
	v_pk_mul_f32 v[68:69], v[58:59], v[50:51]
	v_pk_mul_f32 v[56:57], v[64:65], v[56:57]
	v_pk_mul_f32 v[54:55], v[62:63], v[54:55]
	s_waitcnt lgkmcnt(0)
	v_add_f32_e32 v50, v70, v71
	ds_bpermute_b32 v51, v195, v50
	v_pk_mul_f32 v[66:67], v[60:61], v[52:53]
	v_cvt_pk_bf16_f32 v52, v54, v55
	v_cvt_pk_bf16_f32 v53, v56, v57
	v_cvt_pk_bf16_f32 v54, v68, v69
	v_cvt_pk_bf16_f32 v55, v66, v67
	global_store_dwordx4 v[112:113], v[52:55], off offset:256
	s_and_saveexec_b64 s[34:35], s[38:39]
	s_cbranch_execz .LBB0_1241
	v_lshlrev_b64 v[52:53], 6, v[98:99]
	v_lshl_add_u64 v[52:53], s[62:63], 0, v[52:53]
	v_lshl_add_u64 v[52:53], s[24:25], 2, v[52:53]
	s_lshl_b32 s0, s56, 2
	v_lshl_add_u64 v[52:53], v[52:53], 0, s[0:1]
	s_waitcnt lgkmcnt(0)
	v_add_f32_e32 v50, v50, v51
	global_store_dword v[52:53], v50, off

; __device__ __forceinline__ unsigned pk2(float lo, float hi) { return pg8::cvt_pk_bf16(lo, hi); }
;     __device__ __forceinline__ void operator()(const f32x4 (&acc)[2][2][4][2], const pg8::Unit& u, int wr, int wc, int fr, int fq) const {
;     ...
;                 const int R = rowbase + u.pm * 256 + ai * 128 + wr * 64 + m * 16 + fr;
;                 const float* src = islat ? rin_l + (size_t)R * DM : rin_c + (size_t)(R - TL) * DM;
;                 float* dst = islat ? rout_l + (size_t)R * DM : rout_c + (size_t)(R - TL) * DM;
;                 float ss = 0.f;
; #pragma unroll
;                 for (int bj = 0; bj < 2; ++bj) { const int c = u.pn * 256 + bj * 128 + wc * 32 + 8 * fq;
;                     const f32x4 xa = *(const f32x4*)(src + c) + gv[bj][0] * acc[ai][bj][m][0];
;                     const f32x4 xb = *(const f32x4*)(src + c + 4) + gv[bj][1] * acc[ai][bj][m][1];
;                     *(f32x4*)(dst + c) = xa; *(f32x4*)(dst + c + 4) = xb;
;                     ss += (xa[0] * xa[0] + xa[1] * xa[1]) + (xa[2] * xa[2] + xa[3] * xa[3]) + (xb[0] * xb[0] + xb[1] * xb[1]) + (xb[2] * xb[2] + xb[3] * xb[3]);
;                     const f32x4 ya = xa * sv[bj][0], yb = xb * sv[bj][1];
;                     u32x4 w; w.x = pk2(ya[0], ya[1]); w.y = pk2(ya[2], ya[3]); w.z = pk2(yb[0], yb[1]); w.w = pk2(yb[2], yb[3]);
;                     *(u32x4*)(Hn + (size_t)R * DM + c) = w; }
;                 ss += __shfl_xor(ss, 16); ss += __shfl_xor(ss, 32);
;                 if (fq == 0) stat[(size_t)R * 16 + u.pn * 4 + wc] = ss;
.LBB0_1245:
	v_cndmask_b32_e64 v54, v54, v50, s[42:43]
	v_ashrrev_i32_e32 v55, 31, v54
	v_lshlrev_b64 v[54:55], 12, v[54:55]
	v_lshl_add_u64 v[54:55], s[68:69], 0, v[54:55]
	v_lshl_add_u64 v[70:71], v[54:55], 0, v[188:189]
	global_load_dwordx4 v[54:57], v[70:71], off
	global_load_dwordx4 v[66:69], v[70:71], off offset:16
	v_lshlrev_b64 v[72:73], 11, v[50:51]
	v_lshl_add_u64 v[98:99], v[52:53], 0, v[188:189]
	v_lshl_add_u64 v[52:53], s[60:61], 0, v[72:73]
	v_lshl_add_u64 v[72:73], v[186:187], 1, v[52:53]
	s_waitcnt vmcnt(1)
	v_pk_fma_f32 v[48:49], v[48:49], v[96:97], v[56:57]
	v_pk_fma_f32 v[46:47], v[46:47], v[94:95], v[54:55]
	s_waitcnt vmcnt(0)
	v_pk_fma_f32 v[44:45], v[44:45], v[88:89], v[68:69]
	v_pk_fma_f32 v[42:43], v[42:43], v[86:87], v[66:67]
	v_pk_mul_f32 v[54:55], v[92:93], v[48:49]
	v_pk_mul_f32 v[52:53], v[90:91], v[46:47]
	v_pk_mul_f32 v[56:57], v[84:85], v[44:45]
	v_pk_mul_f32 v[66:67], v[82:83], v[42:43]
	v_cvt_pk_bf16_f32 v52, v52, v53
	v_cvt_pk_bf16_f32 v53, v54, v55
	v_cvt_pk_bf16_f32 v54, v66, v67
	v_cvt_pk_bf16_f32 v55, v56, v57
	v_cndmask_b32_e64 v222, v42, v46, s[100:101]
	v_cndmask_b32_e64 v223, v43, v47, s[100:101]
	v_cndmask_b32_e64 v224, v44, v48, s[100:101]
	v_cndmask_b32_e64 v225, v45, v49, s[100:101]
	v_mov_b32_dpp v238, v222 quad_perm:[1,0,3,2] row_mask:0xf bank_mask:0xf
	v_mov_b32_dpp v239, v223 quad_perm:[1,0,3,2] row_mask:0xf bank_mask:0xf
	v_mov_b32_dpp v240, v224 quad_perm:[1,0,3,2] row_mask:0xf bank_mask:0xf
	v_mov_b32_dpp v241, v225 quad_perm:[1,0,3,2] row_mask:0xf bank_mask:0xf
	v_cndmask_b32_e64 v214, v46, v238, s[100:101]
	v_cndmask_b32_e64 v218, v238, v42, s[100:101]
	v_cndmask_b32_e64 v215, v47, v239, s[100:101]
	v_cndmask_b32_e64 v219, v239, v43, s[100:101]
	v_cndmask_b32_e64 v216, v48, v240, s[100:101]
	v_cndmask_b32_e64 v220, v240, v44, s[100:101]
	v_cndmask_b32_e64 v217, v49, v241, s[100:101]
	v_cndmask_b32_e64 v221, v241, v45, s[100:101]
	v_lshl_add_u64 v[226:227], v[98:99], 0, v[242:243]
	global_store_dwordx4 v[226:227], v[214:217], off offset:-4096
	global_store_dwordx4 v[226:227], v[218:221], off
	global_store_dwordx4 v[72:73], v[52:55], off
	global_load_dwordx4 v[52:55], v[70:71], off offset:512
	s_nop 0
	global_load_dwordx4 v[66:69], v[70:71], off offset:528
	v_mul_f32_e32 v47, v47, v47
	v_mul_f32_e32 v49, v49, v49
	v_mul_f32_e32 v43, v43, v43
	v_fmac_f32_e32 v47, v46, v46
	v_fmac_f32_e32 v49, v48, v48
	v_mul_f32_e32 v45, v45, v45
	v_fmac_f32_e32 v43, v42, v42
	v_add_f32_e32 v42, v47, v49
	v_fmac_f32_e32 v45, v44, v44
	v_add_f32_e32 v42, v42, v43
	v_add_f32_e32 v42, v45, v42
	s_waitcnt vmcnt(1)
	v_pk_fma_f32 v[40:41], v[40:41], v[80:81], v[54:55]
	v_pk_fma_f32 v[38:39], v[38:39], v[78:79], v[52:53]
	s_waitcnt vmcnt(0)
	v_pk_fma_f32 v[34:35], v[34:35], v[74:75], v[66:67]
	v_mul_f32_e32 v43, v39, v39
	v_mul_f32_e32 v44, v41, v41
	v_pk_fma_f32 v[36:37], v[36:37], v[76:77], v[68:69]
	v_mul_f32_e32 v45, v35, v35
	v_fmac_f32_e32 v43, v38, v38
	v_fmac_f32_e32 v44, v40, v40
	v_mul_f32_e32 v46, v37, v37
	v_fmac_f32_e32 v45, v34, v34
	v_add_f32_e32 v43, v43, v44
	v_fmac_f32_e32 v46, v36, v36
	v_add_f32_e32 v43, v43, v45
	v_add_f32_e32 v43, v46, v43
	v_add_f32_e32 v46, v42, v43
	ds_bpermute_b32 v47, v200, v46
	v_cndmask_b32_e64 v222, v34, v38, s[100:101]
	v_cndmask_b32_e64 v223, v35, v39, s[100:101]
	v_cndmask_b32_e64 v224, v36, v40, s[100:101]
	v_cndmask_b32_e64 v225, v37, v41, s[100:101]
	v_mov_b32_dpp v238, v222 quad_perm:[1,0,3,2] row_mask:0xf bank_mask:0xf
	v_mov_b32_dpp v239, v223 quad_perm:[1,0,3,2] row_mask:0xf bank_mask:0xf
	v_mov_b32_dpp v240, v224 quad_perm:[1,0,3,2] row_mask:0xf bank_mask:0xf
	v_mov_b32_dpp v241, v225 quad_perm:[1,0,3,2] row_mask:0xf bank_mask:0xf
	v_cndmask_b32_e64 v214, v38, v238, s[100:101]
	v_cndmask_b32_e64 v218, v238, v34, s[100:101]
	v_cndmask_b32_e64 v215, v39, v239, s[100:101]
	v_cndmask_b32_e64 v219, v239, v35, s[100:101]
	v_cndmask_b32_e64 v216, v40, v240, s[100:101]
	v_cndmask_b32_e64 v220, v240, v36, s[100:101]
	v_cndmask_b32_e64 v217, v41, v241, s[100:101]
	v_cndmask_b32_e64 v221, v241, v37, s[100:101]
	v_lshl_add_u64 v[226:227], v[98:99], 0, v[242:243]
	global_store_dwordx4 v[226:227], v[214:217], off offset:-3584
	global_store_dwordx4 v[226:227], v[218:221], off offset:512
	v_pk_mul_f32 v[44:45], v[58:59], v[34:35]
	v_pk_mul_f32 v[40:41], v[64:65], v[40:41]
	v_pk_mul_f32 v[38:39], v[62:63], v[38:39]
	s_waitcnt lgkmcnt(0)
	v_add_f32_e32 v34, v46, v47
	ds_bpermute_b32 v35, v195, v34
	v_pk_mul_f32 v[42:43], v[60:61], v[36:37]
	v_cvt_pk_bf16_f32 v36, v38, v39
	v_cvt_pk_bf16_f32 v37, v40, v41
	v_cvt_pk_bf16_f32 v38, v44, v45
	v_cvt_pk_bf16_f32 v39, v42, v43
	global_store_dwordx4 v[72:73], v[36:39], off offset:256
	s_and_saveexec_b64 s[34:35], s[38:39]
	s_cbranch_execz .LBB0_1247
	v_lshlrev_b64 v[36:37], 6, v[50:51]
	v_lshl_add_u64 v[36:37], s[62:63], 0, v[36:37]
	v_lshl_add_u64 v[36:37], s[24:25], 2, v[36:37]
	s_lshl_b32 s0, s56, 2
	v_lshl_add_u64 v[36:37], v[36:37], 0, s[0:1]
	s_waitcnt lgkmcnt(0)
	v_add_f32_e32 v34, v34, v35
	global_store_dword v[36:37], v34, off

; __device__ __forceinline__ unsigned pk2(float lo, float hi) { return pg8::cvt_pk_bf16(lo, hi); }
;     __device__ __forceinline__ void operator()(const f32x4 (&acc)[2][2][4][2], const pg8::Unit& u, int wr, int wc, int fr, int fq) const {
;     ...
;                 const int R = rowbase + u.pm * 256 + ai * 128 + wr * 64 + m * 16 + fr;
;                 const float* src = islat ? rin_l + (size_t)R * DM : rin_c + (size_t)(R - TL) * DM;
;                 float* dst = islat ? rout_l + (size_t)R * DM : rout_c + (size_t)(R - TL) * DM;
;                 float ss = 0.f;
; #pragma unroll
;                 for (int bj = 0; bj < 2; ++bj) { const int c = u.pn * 256 + bj * 128 + wc * 32 + 8 * fq;
;                     const f32x4 xa = *(const f32x4*)(src + c) + gv[bj][0] * acc[ai][bj][m][0];
;                     const f32x4 xb = *(const f32x4*)(src + c + 4) + gv[bj][1] * acc[ai][bj][m][1];
;                     *(f32x4*)(dst + c) = xa; *(f32x4*)(dst + c + 4) = xb;
;                     ss += (xa[0] * xa[0] + xa[1] * xa[1]) + (xa[2] * xa[2] + xa[3] * xa[3]) + (xb[0] * xb[0] + xb[1] * xb[1]) + (xb[2] * xb[2] + xb[3] * xb[3]);
;                     const f32x4 ya = xa * sv[bj][0], yb = xb * sv[bj][1];
;                     u32x4 w; w.x = pk2(ya[0], ya[1]); w.y = pk2(ya[2], ya[3]); w.z = pk2(yb[0], yb[1]); w.w = pk2(yb[2], yb[3]);
;                     *(u32x4*)(Hn + (size_t)R * DM + c) = w; }
;                 ss += __shfl_xor(ss, 16); ss += __shfl_xor(ss, 32);
;                 if (fq == 0) stat[(size_t)R * 16 + u.pn * 4 + wc] = ss;
.LBB0_1251:
	v_cndmask_b32_e64 v38, v38, v34, s[42:43]
	v_ashrrev_i32_e32 v39, 31, v38
	v_lshlrev_b64 v[38:39], 12, v[38:39]
	v_lshl_add_u64 v[38:39], s[68:69], 0, v[38:39]
	v_lshl_add_u64 v[46:47], v[38:39], 0, v[188:189]
	global_load_dwordx4 v[38:41], v[46:47], off
	global_load_dwordx4 v[42:45], v[46:47], off offset:16
	v_lshlrev_b64 v[48:49], 11, v[34:35]
	v_lshl_add_u64 v[50:51], v[36:37], 0, v[188:189]
	v_lshl_add_u64 v[36:37], s[60:61], 0, v[48:49]
	v_lshl_add_u64 v[48:49], v[186:187], 1, v[36:37]
	s_waitcnt vmcnt(1)
	v_pk_fma_f32 v[32:33], v[32:33], v[96:97], v[40:41]
	v_pk_fma_f32 v[30:31], v[30:31], v[94:95], v[38:39]
	s_waitcnt vmcnt(0)
	v_pk_fma_f32 v[28:29], v[28:29], v[88:89], v[44:45]
	v_pk_fma_f32 v[26:27], v[26:27], v[86:87], v[42:43]
	v_pk_mul_f32 v[38:39], v[92:93], v[32:33]
	v_pk_mul_f32 v[36:37], v[90:91], v[30:31]
	v_pk_mul_f32 v[40:41], v[84:85], v[28:29]
	v_pk_mul_f32 v[42:43], v[82:83], v[26:27]
	v_cvt_pk_bf16_f32 v36, v36, v37
	v_cvt_pk_bf16_f32 v37, v38, v39
	v_cvt_pk_bf16_f32 v38, v42, v43
	v_cvt_pk_bf16_f32 v39, v40, v41
	v_cndmask_b32_e64 v222, v26, v30, s[100:101]
	v_cndmask_b32_e64 v223, v27, v31, s[100:101]
	v_cndmask_b32_e64 v224, v28, v32, s[100:101]
	v_cndmask_b32_e64 v225, v29, v33, s[100:101]
	v_mov_b32_dpp v238, v222 quad_perm:[1,0,3,2] row_mask:0xf bank_mask:0xf
	v_mov_b32_dpp v239, v223 quad_perm:[1,0,3,2] row_mask:0xf bank_mask:0xf
	v_mov_b32_dpp v240, v224 quad_perm:[1,0,3,2] row_mask:0xf bank_mask:0xf
	v_mov_b32_dpp v241, v225 quad_perm:[1,0,3,2] row_mask:0xf bank_mask:0xf
	v_cndmask_b32_e64 v214, v30, v238, s[100:101]
	v_cndmask_b32_e64 v218, v238, v26, s[100:101]
	v_cndmask_b32_e64 v215, v31, v239, s[100:101]
	v_cndmask_b32_e64 v219, v239, v27, s[100:101]
	v_cndmask_b32_e64 v216, v32, v240, s[100:101]
	v_cndmask_b32_e64 v220, v240, v28, s[100:101]
	v_cndmask_b32_e64 v217, v33, v241, s[100:101]
	v_cndmask_b32_e64 v221, v241, v29, s[100:101]
	v_lshl_add_u64 v[226:227], v[50:51], 0, v[242:243]
	global_store_dwordx4 v[226:227], v[214:217], off offset:-4096
	global_store_dwordx4 v[226:227], v[218:221], off
	global_store_dwordx4 v[48:49], v[36:39], off
	global_load_dwordx4 v[36:39], v[46:47], off offset:512
	s_nop 0
	global_load_dwordx4 v[40:43], v[46:47], off offset:528
	v_mul_f32_e32 v31, v31, v31
	v_mul_f32_e32 v33, v33, v33
	v_mul_f32_e32 v27, v27, v27
	v_fmac_f32_e32 v31, v30, v30
	v_fmac_f32_e32 v33, v32, v32
	v_mul_f32_e32 v29, v29, v29
	v_fmac_f32_e32 v27, v26, v26
	v_add_f32_e32 v26, v31, v33
	v_fmac_f32_e32 v29, v28, v28
	v_add_f32_e32 v26, v26, v27
	v_add_f32_e32 v26, v29, v26
	s_waitcnt vmcnt(1)
	v_pk_fma_f32 v[24:25], v[24:25], v[80:81], v[38:39]
	v_pk_fma_f32 v[22:23], v[22:23], v[78:79], v[36:37]
	s_waitcnt vmcnt(0)
	v_pk_fma_f32 v[18:19], v[18:19], v[74:75], v[40:41]
	v_mul_f32_e32 v27, v23, v23
	v_mul_f32_e32 v28, v25, v25
	v_pk_fma_f32 v[20:21], v[20:21], v[76:77], v[42:43]
	v_mul_f32_e32 v29, v19, v19
	v_fmac_f32_e32 v27, v22, v22
	v_fmac_f32_e32 v28, v24, v24
	v_mul_f32_e32 v30, v21, v21
	v_fmac_f32_e32 v29, v18, v18
	v_add_f32_e32 v27, v27, v28
	v_fmac_f32_e32 v30, v20, v20
	v_add_f32_e32 v27, v27, v29
	v_add_f32_e32 v27, v30, v27
	v_add_f32_e32 v30, v26, v27
	ds_bpermute_b32 v31, v200, v30
	v_cndmask_b32_e64 v222, v18, v22, s[100:101]
	v_cndmask_b32_e64 v223, v19, v23, s[100:101]
	v_cndmask_b32_e64 v224, v20, v24, s[100:101]
	v_cndmask_b32_e64 v225, v21, v25, s[100:101]
	v_mov_b32_dpp v238, v222 quad_perm:[1,0,3,2] row_mask:0xf bank_mask:0xf
	v_mov_b32_dpp v239, v223 quad_perm:[1,0,3,2] row_mask:0xf bank_mask:0xf
	v_mov_b32_dpp v240, v224 quad_perm:[1,0,3,2] row_mask:0xf bank_mask:0xf
	v_mov_b32_dpp v241, v225 quad_perm:[1,0,3,2] row_mask:0xf bank_mask:0xf
	v_cndmask_b32_e64 v214, v22, v238, s[100:101]
	v_cndmask_b32_e64 v218, v238, v18, s[100:101]
	v_cndmask_b32_e64 v215, v23, v239, s[100:101]
	v_cndmask_b32_e64 v219, v239, v19, s[100:101]
	v_cndmask_b32_e64 v216, v24, v240, s[100:101]
	v_cndmask_b32_e64 v220, v240, v20, s[100:101]
	v_cndmask_b32_e64 v217, v25, v241, s[100:101]
	v_cndmask_b32_e64 v221, v241, v21, s[100:101]
	v_lshl_add_u64 v[226:227], v[50:51], 0, v[242:243]
	global_store_dwordx4 v[226:227], v[214:217], off offset:-3584
	global_store_dwordx4 v[226:227], v[218:221], off offset:512
	v_pk_mul_f32 v[28:29], v[58:59], v[18:19]
	v_pk_mul_f32 v[24:25], v[64:65], v[24:25]
	v_pk_mul_f32 v[22:23], v[62:63], v[22:23]
	s_waitcnt lgkmcnt(0)
	v_add_f32_e32 v18, v30, v31
	ds_bpermute_b32 v19, v195, v18
	v_pk_mul_f32 v[26:27], v[60:61], v[20:21]
	v_cvt_pk_bf16_f32 v20, v22, v23
	v_cvt_pk_bf16_f32 v21, v24, v25
	v_cvt_pk_bf16_f32 v22, v28, v29
	v_cvt_pk_bf16_f32 v23, v26, v27
	global_store_dwordx4 v[48:49], v[20:23], off offset:256
	s_and_saveexec_b64 s[34:35], s[38:39]
	s_cbranch_execz .LBB0_1253
	v_lshlrev_b64 v[20:21], 6, v[34:35]
	v_lshl_add_u64 v[20:21], s[62:63], 0, v[20:21]
	v_lshl_add_u64 v[20:21], s[24:25], 2, v[20:21]
	s_lshl_b32 s0, s56, 2
	v_lshl_add_u64 v[20:21], v[20:21], 0, s[0:1]
	s_waitcnt lgkmcnt(0)
	v_add_f32_e32 v18, v18, v19
	global_store_dword v[20:21], v18, off

; __device__ __forceinline__ unsigned pk2(float lo, float hi) { return pg8::cvt_pk_bf16(lo, hi); }
;     __device__ __forceinline__ void operator()(const f32x4 (&acc)[2][2][4][2], const pg8::Unit& u, int wr, int wc, int fr, int fq) const {
;     ...
;                 const int R = rowbase + u.pm * 256 + ai * 128 + wr * 64 + m * 16 + fr;
;                 const float* src = islat ? rin_l + (size_t)R * DM : rin_c + (size_t)(R - TL) * DM;
;                 float* dst = islat ? rout_l + (size_t)R * DM : rout_c + (size_t)(R - TL) * DM;
;                 float ss = 0.f;
; #pragma unroll
;                 for (int bj = 0; bj < 2; ++bj) { const int c = u.pn * 256 + bj * 128 + wc * 32 + 8 * fq;
;                     const f32x4 xa = *(const f32x4*)(src + c) + gv[bj][0] * acc[ai][bj][m][0];
;                     const f32x4 xb = *(const f32x4*)(src + c + 4) + gv[bj][1] * acc[ai][bj][m][1];
;                     *(f32x4*)(dst + c) = xa; *(f32x4*)(dst + c + 4) = xb;
;                     ss += (xa[0] * xa[0] + xa[1] * xa[1]) + (xa[2] * xa[2] + xa[3] * xa[3]) + (xb[0] * xb[0] + xb[1] * xb[1]) + (xb[2] * xb[2] + xb[3] * xb[3]);
;                     const f32x4 ya = xa * sv[bj][0], yb = xb * sv[bj][1];
;                     u32x4 w; w.x = pk2(ya[0], ya[1]); w.y = pk2(ya[2], ya[3]); w.z = pk2(yb[0], yb[1]); w.w = pk2(yb[2], yb[3]);
;                     *(u32x4*)(Hn + (size_t)R * DM + c) = w; }
;                 ss += __shfl_xor(ss, 16); ss += __shfl_xor(ss, 32);
;                 if (fq == 0) stat[(size_t)R * 16 + u.pn * 4 + wc] = ss;
.LBB0_1257:
	v_cndmask_b32_e64 v22, v22, v18, s[42:43]
	v_ashrrev_i32_e32 v23, 31, v22
	v_lshlrev_b64 v[22:23], 12, v[22:23]
	v_lshl_add_u64 v[22:23], s[68:69], 0, v[22:23]
	v_lshl_add_u64 v[30:31], v[22:23], 0, v[188:189]
	global_load_dwordx4 v[22:25], v[30:31], off
	global_load_dwordx4 v[26:29], v[30:31], off offset:16
	v_lshlrev_b64 v[32:33], 11, v[18:19]
	v_lshl_add_u64 v[34:35], v[20:21], 0, v[188:189]
	v_lshl_add_u64 v[20:21], s[60:61], 0, v[32:33]
	v_lshl_add_u64 v[32:33], v[186:187], 1, v[20:21]
	s_waitcnt vmcnt(1)
	v_pk_fma_f32 v[16:17], v[16:17], v[96:97], v[24:25]
	v_pk_fma_f32 v[14:15], v[14:15], v[94:95], v[22:23]
	s_waitcnt vmcnt(0)
	v_pk_fma_f32 v[12:13], v[12:13], v[88:89], v[28:29]
	v_pk_fma_f32 v[10:11], v[10:11], v[86:87], v[26:27]
	v_pk_mul_f32 v[22:23], v[92:93], v[16:17]
	v_pk_mul_f32 v[20:21], v[90:91], v[14:15]
	v_pk_mul_f32 v[24:25], v[84:85], v[12:13]
	v_pk_mul_f32 v[26:27], v[82:83], v[10:11]
	v_cvt_pk_bf16_f32 v20, v20, v21
	v_cvt_pk_bf16_f32 v21, v22, v23
	v_cvt_pk_bf16_f32 v22, v26, v27
	v_cvt_pk_bf16_f32 v23, v24, v25
	v_cndmask_b32_e64 v222, v10, v14, s[100:101]
	v_cndmask_b32_e64 v223, v11, v15, s[100:101]
	v_cndmask_b32_e64 v224, v12, v16, s[100:101]
	v_cndmask_b32_e64 v225, v13, v17, s[100:101]
	v_mov_b32_dpp v238, v222 quad_perm:[1,0,3,2] row_mask:0xf bank_mask:0xf
	v_mov_b32_dpp v239, v223 quad_perm:[1,0,3,2] row_mask:0xf bank_mask:0xf
	v_mov_b32_dpp v240, v224 quad_perm:[1,0,3,2] row_mask:0xf bank_mask:0xf
	v_mov_b32_dpp v241, v225 quad_perm:[1,0,3,2] row_mask:0xf bank_mask:0xf
	v_cndmask_b32_e64 v214, v14, v238, s[100:101]
	v_cndmask_b32_e64 v218, v238, v10, s[100:101]
	v_cndmask_b32_e64 v215, v15, v239, s[100:101]
	v_cndmask_b32_e64 v219, v239, v11, s[100:101]
	v_cndmask_b32_e64 v216, v16, v240, s[100:101]
	v_cndmask_b32_e64 v220, v240, v12, s[100:101]
	v_cndmask_b32_e64 v217, v17, v241, s[100:101]
	v_cndmask_b32_e64 v221, v241, v13, s[100:101]
	v_lshl_add_u64 v[226:227], v[34:35], 0, v[242:243]
	global_store_dwordx4 v[226:227], v[214:217], off offset:-4096
	global_store_dwordx4 v[226:227], v[218:221], off
	global_store_dwordx4 v[32:33], v[20:23], off
	global_load_dwordx4 v[20:23], v[30:31], off offset:512
	s_nop 0
	global_load_dwordx4 v[24:27], v[30:31], off offset:528
	v_mul_f32_e32 v15, v15, v15
	v_mul_f32_e32 v17, v17, v17
	v_mul_f32_e32 v11, v11, v11
	v_fmac_f32_e32 v15, v14, v14
	v_fmac_f32_e32 v17, v16, v16
	v_mul_f32_e32 v13, v13, v13
	v_fmac_f32_e32 v11, v10, v10
	v_add_f32_e32 v10, v15, v17
	v_fmac_f32_e32 v13, v12, v12
	v_add_f32_e32 v10, v10, v11
	v_add_f32_e32 v10, v13, v10
	s_waitcnt vmcnt(1)
	v_pk_fma_f32 v[8:9], v[8:9], v[80:81], v[22:23]
	v_pk_fma_f32 v[6:7], v[6:7], v[78:79], v[20:21]
	s_waitcnt vmcnt(0)
	v_pk_fma_f32 v[2:3], v[2:3], v[74:75], v[24:25]
	v_mul_f32_e32 v11, v7, v7
	v_mul_f32_e32 v12, v9, v9
	v_pk_fma_f32 v[4:5], v[4:5], v[76:77], v[26:27]
	v_mul_f32_e32 v13, v3, v3
	v_fmac_f32_e32 v11, v6, v6
	v_fmac_f32_e32 v12, v8, v8
	v_mul_f32_e32 v14, v5, v5
	v_fmac_f32_e32 v13, v2, v2
	v_add_f32_e32 v11, v11, v12
	v_fmac_f32_e32 v14, v4, v4
	v_add_f32_e32 v11, v11, v13
	v_add_f32_e32 v11, v14, v11
	v_add_f32_e32 v14, v10, v11
	ds_bpermute_b32 v15, v200, v14
	v_cndmask_b32_e64 v222, v2, v6, s[100:101]
	v_cndmask_b32_e64 v223, v3, v7, s[100:101]
	v_cndmask_b32_e64 v224, v4, v8, s[100:101]
	v_cndmask_b32_e64 v225, v5, v9, s[100:101]
	v_mov_b32_dpp v238, v222 quad_perm:[1,0,3,2] row_mask:0xf bank_mask:0xf
	v_mov_b32_dpp v239, v223 quad_perm:[1,0,3,2] row_mask:0xf bank_mask:0xf
	v_mov_b32_dpp v240, v224 quad_perm:[1,0,3,2] row_mask:0xf bank_mask:0xf
	v_mov_b32_dpp v241, v225 quad_perm:[1,0,3,2] row_mask:0xf bank_mask:0xf
	v_cndmask_b32_e64 v214, v6, v238, s[100:101]
	v_cndmask_b32_e64 v218, v238, v2, s[100:101]
	v_cndmask_b32_e64 v215, v7, v239, s[100:101]
	v_cndmask_b32_e64 v219, v239, v3, s[100:101]
	v_cndmask_b32_e64 v216, v8, v240, s[100:101]
	v_cndmask_b32_e64 v220, v240, v4, s[100:101]
	v_cndmask_b32_e64 v217, v9, v241, s[100:101]
	v_cndmask_b32_e64 v221, v241, v5, s[100:101]
	v_lshl_add_u64 v[226:227], v[34:35], 0, v[242:243]
	global_store_dwordx4 v[226:227], v[214:217], off offset:-3584
	global_store_dwordx4 v[226:227], v[218:221], off offset:512
	v_pk_mul_f32 v[12:13], v[58:59], v[2:3]
	v_pk_mul_f32 v[8:9], v[64:65], v[8:9]
	v_pk_mul_f32 v[6:7], v[62:63], v[6:7]
	s_waitcnt lgkmcnt(0)
	v_add_f32_e32 v2, v14, v15
	ds_bpermute_b32 v3, v195, v2
	v_pk_mul_f32 v[10:11], v[60:61], v[4:5]
	v_cvt_pk_bf16_f32 v4, v6, v7
	v_cvt_pk_bf16_f32 v5, v8, v9
	v_cvt_pk_bf16_f32 v6, v12, v13
	v_cvt_pk_bf16_f32 v7, v10, v11
	global_store_dwordx4 v[32:33], v[4:7], off offset:256
	s_and_saveexec_b64 s[34:35], s[38:39]
	s_cbranch_execz .LBB0_1259
	v_lshlrev_b64 v[4:5], 6, v[18:19]
	v_lshl_add_u64 v[4:5], s[62:63], 0, v[4:5]
	v_lshl_add_u64 v[4:5], s[24:25], 2, v[4:5]
	s_lshl_b32 s0, s56, 2
	v_lshl_add_u64 v[4:5], v[4:5], 0, s[0:1]
	s_waitcnt lgkmcnt(0)
	v_add_f32_e32 v2, v2, v3
	global_store_dword v[4:5], v2, off

; __device__ __forceinline__ unsigned pk2(float lo, float hi) { return pg8::cvt_pk_bf16(lo, hi); }
;     __device__ __forceinline__ void operator()(const f32x4 (&acc)[2][2][4][2], const pg8::Unit& u, int wr, int wc, int fr, int fq) const {
;         const int row0 = u.pm * 256 + wr * 64 + fr, col0 = u.pn * 256 + wc * 32 + 8 * fq;
;         const int Rt = rowbase + u.pm * 256;
;         const float* bp = bias + (size_t)(Rt < TL ? (Rt >> 13) : 8) * FF2 + col0;
;         f32x4 bv[2][2];
; #pragma unroll
;         for (int bj = 0; bj < 2; ++bj) { bv[bj][0] = *(const f32x4*)(bp + bj * 128); bv[bj][1] = *(const f32x4*)(bp + bj * 128 + 4); }
; #pragma unroll
;         for (int ai = 0; ai < 2; ++ai)
; #pragma unroll
;             for (int m = 0; m < 4; ++m) { const int r = row0 + ai * 128 + m * 16, Rg = rowbase + r;
;                 const f32x4 q = *(const f32x4*)(stat + (size_t)Rg * 16 + fq * 4);
;                 float ssq = (q[0] + q[1]) + (q[2] + q[3]); ssq += __shfl_xor(ssq, 16); ssq += __shfl_xor(ssq, 32);
;                 const float rstd = rsqrtf(ssq * (1.f / DM) + 1e-6f);
;                 bf16_t* rowp = O + (size_t)r * ldc + col0;
; #pragma unroll
;                 for (int bj = 0; bj < 2; ++bj) { const f32x4 v0 = acc[ai][bj][m][0] * rstd + bv[bj][0], v1 = acc[ai][bj][m][1] * rstd + bv[bj][1];
;                     u32x4 w; w.x = pk2(v0[0], v0[1]); w.y = pk2(v0[2], v0[3]); w.z = pk2(v1[0], v1[1]); w.w = pk2(v1[2], v1[3]);
;                     *(u32x4*)(rowp + bj * 128) = w; } }
;     }
.LBB0_1278:
	s_lshl_b32 s10, s58, 8
	v_add_u32_e32 v176, s10, v178
	v_ashrrev_i32_e32 v177, 31, v176
	v_lshlrev_b64 v[130:131], 6, v[176:177]
	v_lshl_add_u64 v[130:131], v[152:153], 0, v[130:131]
	global_load_dwordx4 v[158:161], v[130:131], off
	global_load_dwordx4 v[196:199], v[130:131], off offset:1024
	global_load_dwordx4 v[200:203], v[130:131], off offset:2048
	global_load_dwordx4 v[204:207], v[130:131], off offset:3072
	v_add_co_u32_e32 v194, vcc, 0x2000, v130
	s_nop 1
	v_addc_co_u32_e32 v195, vcc, 0, v131, vcc
	global_load_dwordx4 v[208:211], v[194:195], off
	global_load_dwordx4 v[212:215], v[194:195], off offset:1024
	global_load_dwordx4 v[216:219], v[194:195], off offset:2048
	global_load_dwordx4 v[220:223], v[194:195], off offset:3072
	s_min_i32 s10, s10, 0x10000
	s_ashr_i32 s10, s10, 13
	s_mulk_i32 s10, 0x1600
	s_ashr_i32 s11, s10, 31
	s_lshl_b64 s[10:11], s[10:11], 2
	v_lshl_or_b32 v184, s57, 8, v180
	s_add_u32 s10, s8, s10
	v_ashrrev_i32_e32 v185, 31, v184
	s_addc_u32 s11, s9, s11
	v_lshl_add_u64 v[130:131], v[184:185], 2, s[10:11]
	global_load_dwordx4 v[142:145], v[130:131], off
	global_load_dwordx4 v[138:141], v[130:131], off offset:16
	global_load_dwordx4 v[134:137], v[130:131], off offset:512
	s_nop 0
	global_load_dwordx4 v[130:133], v[130:131], off offset:528
	v_and_b32_e32 v182, 64, v228
	v_xor_b32_e32 v177, 16, v228
	v_add_u32_e32 v187, 64, v182
	v_cmp_lt_i32_e32 vcc, v177, v187
	v_xor_b32_e32 v186, 32, v228
	s_mov_b64 s[34:35], -1
	v_cndmask_b32_e32 v177, v228, v177, vcc
	v_lshlrev_b32_e32 v177, 2, v177
	v_cmp_lt_i32_e32 vcc, v186, v187
	s_waitcnt vmcnt(0)
	v_mov_b32_e32 v182, v159
	v_mov_b32_e32 v183, v160
	v_mov_b32_e32 v159, v161
	v_pk_add_f32 v[158:159], v[182:183], v[158:159]
	v_cndmask_b32_e32 v182, v228, v186, vcc
	v_add_f32_e32 v160, v158, v159
	ds_bpermute_b32 v161, v177, v160
	v_lshlrev_b32_e32 v182, 2, v182
	v_mov_b64_e32 v[158:159], s[22:23]
	v_mad_i64_i32 v[186:187], s[10:11], v176, s83, v[158:159]
	s_waitcnt lgkmcnt(0)
	v_add_f32_e32 v183, v160, v161
	ds_bpermute_b32 v188, v182, v183
	v_lshlrev_b64 v[160:161], 1, v[184:185]
	v_or_b32_e32 v184, 16, v176
	v_lshl_add_u64 v[186:187], v[186:187], 0, v[160:161]
	s_waitcnt lgkmcnt(0)
	v_add_f32_e32 v183, v183, v188
	v_fmamk_f32 v183, v183, 0x3a800000, v162
	v_mul_f32_e32 v185, 0x4b800000, v183
	v_cmp_gt_f32_e32 vcc, s82, v183
	s_nop 1
	v_cndmask_b32_e32 v183, v183, v185, vcc
	v_rsq_f32_e32 v183, v183
	v_ashrrev_i32_e32 v185, 31, v184
	v_lshlrev_b64 v[188:189], 6, v[184:185]
	v_lshl_add_u64 v[188:189], v[152:153], 0, v[188:189]
	v_mul_f32_e32 v185, 0x45800000, v183
	v_cndmask_b32_e32 v190, v183, v185, vcc
	v_pk_fma_f32 v[128:129], v[128:129], v[190:191], v[144:145] op_sel_hi:[1,0,1]
	v_pk_fma_f32 v[126:127], v[126:127], v[190:191], v[142:143] op_sel_hi:[1,0,1]
	v_pk_fma_f32 v[124:125], v[124:125], v[190:191], v[140:141] op_sel_hi:[1,0,1]
	v_pk_fma_f32 v[122:123], v[122:123], v[190:191], v[138:139] op_sel_hi:[1,0,1]
	v_pk_fma_f32 v[120:121], v[120:121], v[190:191], v[136:137] op_sel_hi:[1,0,1]
	v_pk_fma_f32 v[118:119], v[118:119], v[190:191], v[134:135] op_sel_hi:[1,0,1]
	v_pk_fma_f32 v[192:193], v[116:117], v[190:191], v[132:133] op_sel_hi:[1,0,1]
	v_pk_fma_f32 v[190:191], v[114:115], v[190:191], v[130:131] op_sel_hi:[1,0,1]
	v_cvt_pk_bf16_f32 v114, v126, v127
	v_cvt_pk_bf16_f32 v115, v128, v129
	v_cvt_pk_bf16_f32 v116, v122, v123
	v_cvt_pk_bf16_f32 v117, v124, v125
	v_cvt_pk_bf16_f32 v118, v118, v119
	v_cvt_pk_bf16_f32 v119, v120, v121
	v_cvt_pk_bf16_f32 v120, v190, v191
	v_cvt_pk_bf16_f32 v121, v192, v193
	global_store_dwordx4 v[186:187], v[114:117], off
	global_store_dwordx4 v[186:187], v[118:121], off offset:256
	s_nop 1
	v_add_f32_e32 v114, v196, v197
	v_add_f32_e32 v115, v198, v199
	v_mad_i64_i32 v[116:117], s[10:11], v184, s83, v[158:159]
	v_add_f32_e32 v114, v114, v115
	ds_bpermute_b32 v115, v177, v114
	v_lshl_add_u64 v[116:117], v[116:117], 0, v[160:161]
	s_waitcnt lgkmcnt(0)
	v_add_f32_e32 v118, v114, v115
	ds_bpermute_b32 v119, v182, v118
	v_or_b32_e32 v114, 32, v176
	v_ashrrev_i32_e32 v115, 31, v114
	s_waitcnt lgkmcnt(0)
	v_add_f32_e32 v118, v118, v119
	v_fmamk_f32 v118, v118, 0x3a800000, v162
	v_mul_f32_e32 v119, 0x4b800000, v118
	v_cmp_gt_f32_e32 vcc, s82, v118
	s_nop 1
	v_cndmask_b32_e32 v118, v118, v119, vcc
	v_rsq_f32_e32 v120, v118
	v_lshlrev_b64 v[118:119], 6, v[114:115]
	v_lshl_add_u64 v[118:119], v[152:153], 0, v[118:119]
	v_mul_f32_e32 v115, 0x45800000, v120
	v_cndmask_b32_e32 v120, v120, v115, vcc
	v_pk_fma_f32 v[112:113], v[112:113], v[120:121], v[144:145] op_sel_hi:[1,0,1]
	v_pk_fma_f32 v[110:111], v[110:111], v[120:121], v[142:143] op_sel_hi:[1,0,1]
	v_pk_fma_f32 v[108:109], v[108:109], v[120:121], v[140:141] op_sel_hi:[1,0,1]
	v_pk_fma_f32 v[106:107], v[106:107], v[120:121], v[138:139] op_sel_hi:[1,0,1]
	v_pk_fma_f32 v[104:105], v[104:105], v[120:121], v[136:137] op_sel_hi:[1,0,1]
	v_pk_fma_f32 v[102:103], v[102:103], v[120:121], v[134:135] op_sel_hi:[1,0,1]
	v_pk_fma_f32 v[122:123], v[100:101], v[120:121], v[132:133] op_sel_hi:[1,0,1]
	v_pk_fma_f32 v[120:121], v[98:99], v[120:121], v[130:131] op_sel_hi:[1,0,1]
	v_cvt_pk_bf16_f32 v98, v110, v111
	v_cvt_pk_bf16_f32 v99, v112, v113
	v_cvt_pk_bf16_f32 v100, v106, v107
	v_cvt_pk_bf16_f32 v101, v108, v109
	v_cvt_pk_bf16_f32 v102, v102, v103
	v_cvt_pk_bf16_f32 v103, v104, v105
	v_cvt_pk_bf16_f32 v104, v120, v121
	v_cvt_pk_bf16_f32 v105, v122, v123
	global_store_dwordx4 v[116:117], v[98:101], off
	global_store_dwordx4 v[116:117], v[102:105], off offset:256
	s_nop 1
	v_add_f32_e32 v98, v200, v201
	v_add_f32_e32 v99, v202, v203
	v_mad_i64_i32 v[100:101], s[10:11], v114, s83, v[158:159]
	v_add_f32_e32 v98, v98, v99
	ds_bpermute_b32 v99, v177, v98
	v_lshl_add_u64 v[100:101], v[100:101], 0, v[160:161]
	s_waitcnt lgkmcnt(0)
; __device__ __forceinline__ unsigned pk2(float lo, float hi) { return pg8::cvt_pk_bf16(lo, hi); }
;     __device__ __forceinline__ void operator()(const f32x4 (&acc)[2][2][4][2], const pg8::Unit& u, int wr, int wc, int fr, int fq) const {
;     ...
;         for (int ai = 0; ai < 2; ++ai)
; #pragma unroll
;             for (int m = 0; m < 4; ++m) { const int r = row0 + ai * 128 + m * 16, Rg = rowbase + r;
;                 const f32x4 q = *(const f32x4*)(stat + (size_t)Rg * 16 + fq * 4);
;                 float ssq = (q[0] + q[1]) + (q[2] + q[3]); ssq += __shfl_xor(ssq, 16); ssq += __shfl_xor(ssq, 32);
;                 const float rstd = rsqrtf(ssq * (1.f / DM) + 1e-6f);
;                 bf16_t* rowp = O + (size_t)r * ldc + col0;
; #pragma unroll
;                 for (int bj = 0; bj < 2; ++bj) { const f32x4 v0 = acc[ai][bj][m][0] * rstd + bv[bj][0], v1 = acc[ai][bj][m][1] * rstd + bv[bj][1];
;                     u32x4 w; w.x = pk2(v0[0], v0[1]); w.y = pk2(v0[2], v0[3]); w.z = pk2(v1[0], v1[1]); w.w = pk2(v1[2], v1[3]);
;                     *(u32x4*)(rowp + bj * 128) = w; } }
	v_add_f32_e32 v102, v98, v99
	ds_bpermute_b32 v103, v182, v102
	v_or_b32_e32 v98, 48, v176
	v_ashrrev_i32_e32 v99, 31, v98
	s_waitcnt lgkmcnt(0)
	v_add_f32_e32 v102, v102, v103
	v_fmamk_f32 v102, v102, 0x3a800000, v162
	v_mul_f32_e32 v103, 0x4b800000, v102
	v_cmp_gt_f32_e32 vcc, s82, v102
	s_nop 1
	v_cndmask_b32_e32 v102, v102, v103, vcc
	v_rsq_f32_e32 v104, v102
	v_lshlrev_b64 v[102:103], 6, v[98:99]
	v_lshl_add_u64 v[102:103], v[152:153], 0, v[102:103]
	v_mul_f32_e32 v99, 0x45800000, v104
	v_cndmask_b32_e32 v104, v104, v99, vcc
	v_pk_fma_f32 v[96:97], v[96:97], v[104:105], v[144:145] op_sel_hi:[1,0,1]
	v_pk_fma_f32 v[94:95], v[94:95], v[104:105], v[142:143] op_sel_hi:[1,0,1]
	v_pk_fma_f32 v[92:93], v[92:93], v[104:105], v[140:141] op_sel_hi:[1,0,1]
	v_pk_fma_f32 v[90:91], v[90:91], v[104:105], v[138:139] op_sel_hi:[1,0,1]
	v_pk_fma_f32 v[88:89], v[88:89], v[104:105], v[136:137] op_sel_hi:[1,0,1]
	v_pk_fma_f32 v[86:87], v[86:87], v[104:105], v[134:135] op_sel_hi:[1,0,1]
	v_pk_fma_f32 v[106:107], v[84:85], v[104:105], v[132:133] op_sel_hi:[1,0,1]
	v_pk_fma_f32 v[104:105], v[82:83], v[104:105], v[130:131] op_sel_hi:[1,0,1]
	v_cvt_pk_bf16_f32 v82, v94, v95
	v_cvt_pk_bf16_f32 v83, v96, v97
	v_cvt_pk_bf16_f32 v84, v90, v91
	v_cvt_pk_bf16_f32 v85, v92, v93
	v_cvt_pk_bf16_f32 v86, v86, v87
	v_cvt_pk_bf16_f32 v87, v88, v89
	v_cvt_pk_bf16_f32 v88, v104, v105
	v_cvt_pk_bf16_f32 v89, v106, v107
	global_store_dwordx4 v[100:101], v[82:85], off
	global_store_dwordx4 v[100:101], v[86:89], off offset:256
	s_nop 1
	v_add_f32_e32 v82, v204, v205
	v_add_f32_e32 v83, v206, v207
	v_mad_i64_i32 v[84:85], s[10:11], v98, s83, v[158:159]
	v_add_f32_e32 v82, v82, v83
	ds_bpermute_b32 v83, v177, v82
	v_lshl_add_u64 v[84:85], v[84:85], 0, v[160:161]
	s_waitcnt lgkmcnt(0)
	v_add_f32_e32 v86, v82, v83
	ds_bpermute_b32 v87, v182, v86
	v_add_u32_e32 v82, 0x80, v176
	v_ashrrev_i32_e32 v83, 31, v82
	s_waitcnt lgkmcnt(0)
	v_add_f32_e32 v86, v86, v87
	v_fmamk_f32 v86, v86, 0x3a800000, v162
	v_mul_f32_e32 v87, 0x4b800000, v86
	v_cmp_gt_f32_e32 vcc, s82, v86
	s_nop 1
	v_cndmask_b32_e32 v86, v86, v87, vcc
	v_rsq_f32_e32 v88, v86
	v_lshlrev_b64 v[86:87], 6, v[82:83]
	v_lshl_add_u64 v[86:87], v[152:153], 0, v[86:87]
	v_mul_f32_e32 v83, 0x45800000, v88
	v_cndmask_b32_e32 v88, v88, v83, vcc
	v_pk_fma_f32 v[80:81], v[80:81], v[88:89], v[144:145] op_sel_hi:[1,0,1]
	v_pk_fma_f32 v[78:79], v[78:79], v[88:89], v[142:143] op_sel_hi:[1,0,1]
	v_pk_fma_f32 v[76:77], v[76:77], v[88:89], v[140:141] op_sel_hi:[1,0,1]
	v_pk_fma_f32 v[74:75], v[74:75], v[88:89], v[138:139] op_sel_hi:[1,0,1]
	v_pk_fma_f32 v[72:73], v[72:73], v[88:89], v[136:137] op_sel_hi:[1,0,1]
	v_pk_fma_f32 v[70:71], v[70:71], v[88:89], v[134:135] op_sel_hi:[1,0,1]
	v_pk_fma_f32 v[90:91], v[68:69], v[88:89], v[132:133] op_sel_hi:[1,0,1]
	v_pk_fma_f32 v[88:89], v[66:67], v[88:89], v[130:131] op_sel_hi:[1,0,1]
	v_cvt_pk_bf16_f32 v66, v78, v79
	v_cvt_pk_bf16_f32 v67, v80, v81
	v_cvt_pk_bf16_f32 v68, v74, v75
	v_cvt_pk_bf16_f32 v69, v76, v77
	v_cvt_pk_bf16_f32 v70, v70, v71
	v_cvt_pk_bf16_f32 v71, v72, v73
	v_cvt_pk_bf16_f32 v72, v88, v89
	v_cvt_pk_bf16_f32 v73, v90, v91
	global_store_dwordx4 v[84:85], v[66:69], off
	global_store_dwordx4 v[84:85], v[70:73], off offset:256
	s_nop 1
	v_add_f32_e32 v66, v208, v209
	v_add_f32_e32 v67, v210, v211
	v_mad_i64_i32 v[68:69], s[10:11], v82, s83, v[158:159]
	v_add_f32_e32 v66, v66, v67
	ds_bpermute_b32 v67, v177, v66
	v_lshl_add_u64 v[68:69], v[68:69], 0, v[160:161]
	s_waitcnt lgkmcnt(0)
	v_add_f32_e32 v70, v66, v67
	ds_bpermute_b32 v71, v182, v70
	v_add_u32_e32 v66, 0x90, v176
	v_ashrrev_i32_e32 v67, 31, v66
	s_waitcnt lgkmcnt(0)
	v_add_f32_e32 v70, v70, v71
	v_fmamk_f32 v70, v70, 0x3a800000, v162
	v_mul_f32_e32 v71, 0x4b800000, v70
	v_cmp_gt_f32_e32 vcc, s82, v70
	s_nop 1
	v_cndmask_b32_e32 v70, v70, v71, vcc
	v_rsq_f32_e32 v72, v70
	v_lshlrev_b64 v[70:71], 6, v[66:67]
	v_lshl_add_u64 v[70:71], v[152:153], 0, v[70:71]
	v_mul_f32_e32 v67, 0x45800000, v72
	v_cndmask_b32_e32 v72, v72, v67, vcc
	v_pk_fma_f32 v[64:65], v[64:65], v[72:73], v[144:145] op_sel_hi:[1,0,1]
	v_pk_fma_f32 v[62:63], v[62:63], v[72:73], v[142:143] op_sel_hi:[1,0,1]
	v_pk_fma_f32 v[60:61], v[60:61], v[72:73], v[140:141] op_sel_hi:[1,0,1]
	v_pk_fma_f32 v[58:59], v[58:59], v[72:73], v[138:139] op_sel_hi:[1,0,1]
	v_pk_fma_f32 v[56:57], v[56:57], v[72:73], v[136:137] op_sel_hi:[1,0,1]
	v_pk_fma_f32 v[54:55], v[54:55], v[72:73], v[134:135] op_sel_hi:[1,0,1]
	v_pk_fma_f32 v[74:75], v[52:53], v[72:73], v[132:133] op_sel_hi:[1,0,1]
	v_pk_fma_f32 v[72:73], v[50:51], v[72:73], v[130:131] op_sel_hi:[1,0,1]
	v_cvt_pk_bf16_f32 v50, v62, v63
	v_cvt_pk_bf16_f32 v51, v64, v65
	v_cvt_pk_bf16_f32 v52, v58, v59
	v_cvt_pk_bf16_f32 v53, v60, v61
	v_cvt_pk_bf16_f32 v54, v54, v55
	v_cvt_pk_bf16_f32 v55, v56, v57
	v_cvt_pk_bf16_f32 v56, v72, v73
	v_cvt_pk_bf16_f32 v57, v74, v75
	global_store_dwordx4 v[68:69], v[50:53], off
	global_store_dwordx4 v[68:69], v[54:57], off offset:256
	s_nop 1
	v_add_f32_e32 v50, v212, v213
	v_add_f32_e32 v51, v214, v215
	v_mad_i64_i32 v[52:53], s[10:11], v66, s83, v[158:159]
	v_add_f32_e32 v50, v50, v51
	ds_bpermute_b32 v51, v177, v50
	v_lshl_add_u64 v[52:53], v[52:53], 0, v[160:161]
	s_waitcnt lgkmcnt(0)
; __device__ __forceinline__ unsigned pk2(float lo, float hi) { return pg8::cvt_pk_bf16(lo, hi); }
;     __device__ __forceinline__ void operator()(const f32x4 (&acc)[2][2][4][2], const pg8::Unit& u, int wr, int wc, int fr, int fq) const {
;     ...
;         for (int ai = 0; ai < 2; ++ai)
; #pragma unroll
;             for (int m = 0; m < 4; ++m) { const int r = row0 + ai * 128 + m * 16, Rg = rowbase + r;
;                 const f32x4 q = *(const f32x4*)(stat + (size_t)Rg * 16 + fq * 4);
;                 float ssq = (q[0] + q[1]) + (q[2] + q[3]); ssq += __shfl_xor(ssq, 16); ssq += __shfl_xor(ssq, 32);
;                 const float rstd = rsqrtf(ssq * (1.f / DM) + 1e-6f);
;                 bf16_t* rowp = O + (size_t)r * ldc + col0;
; #pragma unroll
;                 for (int bj = 0; bj < 2; ++bj) { const f32x4 v0 = acc[ai][bj][m][0] * rstd + bv[bj][0], v1 = acc[ai][bj][m][1] * rstd + bv[bj][1];
;                     u32x4 w; w.x = pk2(v0[0], v0[1]); w.y = pk2(v0[2], v0[3]); w.z = pk2(v1[0], v1[1]); w.w = pk2(v1[2], v1[3]);
;                     *(u32x4*)(rowp + bj * 128) = w; } }
;     }
	v_add_f32_e32 v54, v50, v51
	ds_bpermute_b32 v55, v182, v54
	v_add_u32_e32 v50, 0xa0, v176
	v_ashrrev_i32_e32 v51, 31, v50
	s_waitcnt lgkmcnt(0)
	v_add_f32_e32 v54, v54, v55
	v_fmamk_f32 v54, v54, 0x3a800000, v162
	v_mul_f32_e32 v55, 0x4b800000, v54
	v_cmp_gt_f32_e32 vcc, s82, v54
	s_nop 1
	v_cndmask_b32_e32 v54, v54, v55, vcc
	v_rsq_f32_e32 v56, v54
	v_lshlrev_b64 v[54:55], 6, v[50:51]
	v_lshl_add_u64 v[54:55], v[152:153], 0, v[54:55]
	v_mul_f32_e32 v51, 0x45800000, v56
	v_cndmask_b32_e32 v56, v56, v51, vcc
	v_pk_fma_f32 v[48:49], v[48:49], v[56:57], v[144:145] op_sel_hi:[1,0,1]
	v_pk_fma_f32 v[46:47], v[46:47], v[56:57], v[142:143] op_sel_hi:[1,0,1]
	v_pk_fma_f32 v[44:45], v[44:45], v[56:57], v[140:141] op_sel_hi:[1,0,1]
	v_pk_fma_f32 v[42:43], v[42:43], v[56:57], v[138:139] op_sel_hi:[1,0,1]
	v_pk_fma_f32 v[40:41], v[40:41], v[56:57], v[136:137] op_sel_hi:[1,0,1]
	v_pk_fma_f32 v[38:39], v[38:39], v[56:57], v[134:135] op_sel_hi:[1,0,1]
	v_pk_fma_f32 v[58:59], v[36:37], v[56:57], v[132:133] op_sel_hi:[1,0,1]
	v_pk_fma_f32 v[56:57], v[34:35], v[56:57], v[130:131] op_sel_hi:[1,0,1]
	v_cvt_pk_bf16_f32 v34, v46, v47
	v_cvt_pk_bf16_f32 v35, v48, v49
	v_cvt_pk_bf16_f32 v36, v42, v43
	v_cvt_pk_bf16_f32 v37, v44, v45
	v_cvt_pk_bf16_f32 v38, v38, v39
	v_cvt_pk_bf16_f32 v39, v40, v41
	v_cvt_pk_bf16_f32 v40, v56, v57
	v_cvt_pk_bf16_f32 v41, v58, v59
	global_store_dwordx4 v[52:53], v[34:37], off
	global_store_dwordx4 v[52:53], v[38:41], off offset:256
	s_nop 1
	v_add_f32_e32 v34, v216, v217
	v_add_f32_e32 v35, v218, v219
	v_mad_i64_i32 v[36:37], s[10:11], v50, s83, v[158:159]
	v_add_f32_e32 v34, v34, v35
	ds_bpermute_b32 v35, v177, v34
	v_lshl_add_u64 v[36:37], v[36:37], 0, v[160:161]
	s_waitcnt lgkmcnt(0)
	v_add_f32_e32 v38, v34, v35
	ds_bpermute_b32 v39, v182, v38
	v_add_u32_e32 v34, 0xb0, v176
	v_ashrrev_i32_e32 v35, 31, v34
	s_waitcnt lgkmcnt(0)
	v_add_f32_e32 v38, v38, v39
	v_fmamk_f32 v38, v38, 0x3a800000, v162
	v_mul_f32_e32 v39, 0x4b800000, v38
	v_cmp_gt_f32_e32 vcc, s82, v38
	s_nop 1
	v_cndmask_b32_e32 v38, v38, v39, vcc
	v_rsq_f32_e32 v40, v38
	v_lshlrev_b64 v[38:39], 6, v[34:35]
	v_lshl_add_u64 v[38:39], v[152:153], 0, v[38:39]
	v_mul_f32_e32 v35, 0x45800000, v40
	v_cndmask_b32_e32 v40, v40, v35, vcc
	v_pk_fma_f32 v[32:33], v[32:33], v[40:41], v[144:145] op_sel_hi:[1,0,1]
	v_pk_fma_f32 v[30:31], v[30:31], v[40:41], v[142:143] op_sel_hi:[1,0,1]
	v_pk_fma_f32 v[28:29], v[28:29], v[40:41], v[140:141] op_sel_hi:[1,0,1]
	v_pk_fma_f32 v[26:27], v[26:27], v[40:41], v[138:139] op_sel_hi:[1,0,1]
	v_pk_fma_f32 v[24:25], v[24:25], v[40:41], v[136:137] op_sel_hi:[1,0,1]
	v_pk_fma_f32 v[22:23], v[22:23], v[40:41], v[134:135] op_sel_hi:[1,0,1]
	v_pk_fma_f32 v[42:43], v[20:21], v[40:41], v[132:133] op_sel_hi:[1,0,1]
	v_pk_fma_f32 v[40:41], v[18:19], v[40:41], v[130:131] op_sel_hi:[1,0,1]
	v_cvt_pk_bf16_f32 v18, v30, v31
	v_cvt_pk_bf16_f32 v19, v32, v33
	v_cvt_pk_bf16_f32 v20, v26, v27
	v_cvt_pk_bf16_f32 v21, v28, v29
	v_cvt_pk_bf16_f32 v22, v22, v23
	v_cvt_pk_bf16_f32 v23, v24, v25
	v_cvt_pk_bf16_f32 v24, v40, v41
	v_cvt_pk_bf16_f32 v25, v42, v43
	global_store_dwordx4 v[36:37], v[18:21], off
	global_store_dwordx4 v[36:37], v[22:25], off offset:256
	s_andn2_b64 vcc, exec, s[38:39]
	s_nop 1
	v_add_f32_e32 v18, v220, v221
	v_add_f32_e32 v19, v222, v223
	s_nop 0
	v_add_f32_e32 v18, v18, v19
	ds_bpermute_b32 v19, v177, v18
	s_waitcnt lgkmcnt(0)
	v_add_f32_e32 v18, v18, v19
	ds_bpermute_b32 v19, v182, v18
	s_waitcnt lgkmcnt(0)
	v_add_f32_e32 v18, v18, v19
	v_fmamk_f32 v18, v18, 0x3a800000, v162
	v_mul_f32_e32 v19, 0x4b800000, v18
	v_cmp_gt_f32_e64 s[40:41], s82, v18
	s_nop 1
	v_cndmask_b32_e64 v18, v18, v19, s[40:41]
	v_rsq_f32_e32 v20, v18
	v_mad_i64_i32 v[18:19], s[10:11], v34, s83, v[158:159]
	v_lshl_add_u64 v[18:19], v[18:19], 0, v[160:161]
	v_mul_f32_e32 v21, 0x45800000, v20
	v_cndmask_b32_e64 v20, v20, v21, s[40:41]
	v_pk_fma_f32 v[16:17], v[16:17], v[20:21], v[144:145] op_sel_hi:[1,0,1]
	v_pk_fma_f32 v[14:15], v[14:15], v[20:21], v[142:143] op_sel_hi:[1,0,1]
	v_pk_fma_f32 v[12:13], v[12:13], v[20:21], v[140:141] op_sel_hi:[1,0,1]
	v_pk_fma_f32 v[10:11], v[10:11], v[20:21], v[138:139] op_sel_hi:[1,0,1]
	v_pk_fma_f32 v[8:9], v[8:9], v[20:21], v[136:137] op_sel_hi:[1,0,1]
	v_pk_fma_f32 v[6:7], v[6:7], v[20:21], v[134:135] op_sel_hi:[1,0,1]
	v_pk_fma_f32 v[22:23], v[4:5], v[20:21], v[132:133] op_sel_hi:[1,0,1]
	v_pk_fma_f32 v[20:21], v[2:3], v[20:21], v[130:131] op_sel_hi:[1,0,1]
	v_cvt_pk_bf16_f32 v2, v14, v15
	v_cvt_pk_bf16_f32 v3, v16, v17
	v_cvt_pk_bf16_f32 v4, v10, v11
	v_cvt_pk_bf16_f32 v5, v12, v13
	v_cvt_pk_bf16_f32 v6, v6, v7
	v_cvt_pk_bf16_f32 v7, v8, v9
	v_cvt_pk_bf16_f32 v8, v20, v21
	v_cvt_pk_bf16_f32 v9, v22, v23
	global_store_dwordx4 v[18:19], v[2:5], off
	global_store_dwordx4 v[18:19], v[6:9], off offset:256
	s_cbranch_vccnz .LBB0_1271
	s_andn2_b64 vcc, exec, s[20:21]
	s_cbranch_vccnz .LBB0_1270
	s_barrier
	s_branch .LBB0_1270

; __global__ void __launch_bounds__(512, 2) fwd_megakernel(Params p_unused) {
;     extern __shared__ __attribute__((aligned(16))) unsigned char smem[];
;     cg::grid_group grid = cg::this_grid();
	.amdhsa_kernel _Z14fwd_megakernel6Params
		.amdhsa_group_segment_fixed_size 16
		.amdhsa_private_segment_fixed_size 0
		.amdhsa_kernarg_size 456
		.amdhsa_user_sgpr_count 2
		.amdhsa_user_sgpr_dispatch_ptr 0
		.amdhsa_user_sgpr_queue_ptr 0
		.amdhsa_user_sgpr_kernarg_segment_ptr 1
		.amdhsa_user_sgpr_dispatch_id 0
		.amdhsa_user_sgpr_kernarg_preload_length 0
		.amdhsa_user_sgpr_kernarg_preload_offset 0
		.amdhsa_user_sgpr_private_segment_size 0
		.amdhsa_uses_dynamic_stack 0
		.amdhsa_enable_private_segment 0
		.amdhsa_system_sgpr_workgroup_id_x 1
		.amdhsa_system_sgpr_workgroup_id_y 0
		.amdhsa_system_sgpr_workgroup_id_z 0
		.amdhsa_system_sgpr_workgroup_info 0
		.amdhsa_system_vgpr_workitem_id 2
		.amdhsa_next_free_vgpr 253
		.amdhsa_next_free_sgpr 102
		.amdhsa_accum_offset 256
		.amdhsa_reserve_vcc 1
		.amdhsa_float_round_mode_32 0
		.amdhsa_float_round_mode_16_64 0
		.amdhsa_float_denorm_mode_32 3
		.amdhsa_float_denorm_mode_16_64 3
		.amdhsa_dx10_clamp 1
		.amdhsa_ieee_mode 1
		.amdhsa_fp16_overflow 0
		.amdhsa_tg_split 0
		.amdhsa_exception_fp_ieee_invalid_op 0
		.amdhsa_exception_fp_denorm_src 0
		.amdhsa_exception_fp_ieee_div_zero 0
		.amdhsa_exception_fp_ieee_overflow 0
		.amdhsa_exception_fp_ieee_underflow 0
		.amdhsa_exception_fp_ieee_inexact 0
		.amdhsa_exception_int_div_zero 0
	.end_amdhsa_kernel

; __global__ void __launch_bounds__(512, 2) fwd_megakernel(Params p_unused) {
;     extern __shared__ __attribute__((aligned(16))) unsigned char smem[];
;     cg::grid_group grid = cg::this_grid();
amdhsa.kernels:
  - .agpr_count:     0
    .args:
      - .offset:         0
        .size:           200
        .value_kind:     by_value
      - .offset:         200
        .size:           4
        .value_kind:     hidden_block_count_x
      - .offset:         204
        .size:           4
        .value_kind:     hidden_block_count_y
      - .offset:         208
        .size:           4
        .value_kind:     hidden_block_count_z
      - .offset:         212
        .size:           2
        .value_kind:     hidden_group_size_x
      - .offset:         214
        .size:           2
        .value_kind:     hidden_group_size_y
      - .offset:         216
        .size:           2
        .value_kind:     hidden_group_size_z
      - .offset:         218
        .size:           2
        .value_kind:     hidden_remainder_x
      - .offset:         220
        .size:           2
        .value_kind:     hidden_remainder_y
      - .offset:         222
        .size:           2
        .value_kind:     hidden_remainder_z
      - .offset:         240
        .size:           8
        .value_kind:     hidden_global_offset_x
      - .offset:         248
        .size:           8
        .value_kind:     hidden_global_offset_y
      - .offset:         256
        .size:           8
        .value_kind:     hidden_global_offset_z
      - .offset:         264
        .size:           2
        .value_kind:     hidden_grid_dims
      - .offset:         288
        .size:           8
        .value_kind:     hidden_multigrid_sync_arg
      - .offset:         320
        .size:           4
        .value_kind:     hidden_dynamic_lds_size
    .group_segment_fixed_size: 16
    .kernarg_segment_align: 8
    .kernarg_segment_size: 456
    .language:       OpenCL C
    .language_version:
      - 2
      - 0
    .max_flat_workgroup_size: 512
    .name:           _Z14fwd_megakernel6Params
    .private_segment_fixed_size: 0
    .sgpr_count:     108
    .sgpr_spill_count: 178
    .symbol:         _Z14fwd_megakernel6Params.kd
    .uniform_work_group_size: 1
    .uses_dynamic_stack: false
    .vgpr_count:     253
    .vgpr_spill_count: 0
    .wavefront_size: 64
